# trailing-half stagger barrier deferred past the next-tile header in all 9 GEMM loops (on top of flag-based group-local seams)
# baseline (speedup 1.0000x reference)
_Z14fwd_megakernel4Args:
	s_mov_b32 s99, 0
	s_mov_b32 s98, 0
	s_load_dwordx8 s[36:43], s[0:1], 0x80
	s_load_dword s3, s[0:1], 0xa8
	s_load_dwordx2 s[14:15], s[0:1], 0xa0
	s_add_u32 s6, s0, 0xa0
	v_and_b32_e32 v241, 0x3ff, v0
	s_addc_u32 s7, s1, 0
	v_cmp_gt_u32_e32 vcc, 64, v241
	s_and_saveexec_b64 s[4:5], vcc
	v_lshl_add_u32 v1, v241, 2, 0
	v_add_u32_e32 v1, 0x20000, v1
	v_mov_b32_e32 v2, 0
	ds_write_b32 v1, v2
	s_or_b64 exec, exec, s[4:5]
	s_waitcnt lgkmcnt(0)
	s_barrier
	s_add_u32 s34, s42, 0xe0000
	s_getreg_b32 s4, hwreg(HW_REG_XCC_ID, 0, 4)
	s_addc_u32 s35, s43, 0
	s_and_b32 s52, s4, 15
	v_cmp_eq_u32_e64 s[62:63], 0, v241
	s_and_saveexec_b64 s[4:5], s[62:63]
	s_cbranch_execz .LBB0_5
	s_mov_b64 s[8:9], exec
	v_mbcnt_lo_u32_b32 v1, s8, 0
	v_mbcnt_hi_u32_b32 v1, s9, v1
	v_cmp_eq_u32_e32 vcc, 0, v1
	s_and_b64 s[10:11], exec, vcc
	s_mov_b64 exec, s[10:11]
	s_cbranch_execz .LBB0_5
	s_lshl_b32 s10, s52, 8
	s_bcnt1_i32_b64 s8, s[8:9]
	v_mov_b32_e32 v1, s10
	v_mov_b32_e32 v2, s8
	global_atomic_add v1, v2, s[34:35] offset:1024
	s_and_b32 s12, s2, 7
	s_lshl_b32 s12, s12, 3
	s_add_u32 s12, s12, 0x3800
	s_add_i32 s13, s52, 1
	v_mov_b32_e32 v3, s12
	v_mov_b32_e32 v4, s13
	s_sub_i32 s13, 16, s52
	v_mov_b32_e32 v5, s13
	global_atomic_umax v3, v4, s[34:35]
	global_atomic_umax v3, v5, s[34:35] offset:4

.LBB0_191:
	s_ashr_i32 s39, s38, 31
	s_lshl_b64 s[40:41], s[38:39], 19
	s_add_u32 s40, s65, s40
	s_addc_u32 s41, s64, s41
	s_and_b64 s[42:43], s[4:5], exec
	s_cselect_b32 s39, s41, s47
	s_cselect_b32 s78, s40, s46
	s_ashr_i32 s37, s36, 31
	s_lshl_b64 s[42:43], s[36:37], 19
	s_add_u32 s42, s67, s42
	s_addc_u32 s43, s66, s43
	s_and_b64 s[80:81], s[4:5], exec
	s_cselect_b32 s37, s43, s49
	s_cselect_b32 s79, s42, s48
	s_add_u32 s46, s46, 0x40080
	s_addc_u32 s47, s47, 0
	s_add_u32 s80, s48, 0x100
	s_addc_u32 s81, s49, 0
	s_mov_b32 s82, -2
	s_cmp_eq_u32 s98, 1
	s_cbranch_scc0 .Lnostb0
	s_mov_b32 s98, 0
	s_barrier
.Lnostb0:
	s_add_u32 s48, s46, 0xfffc0080
	s_addc_u32 s49, s47, -1
	s_add_i32 s83, 0, 0x10000
	s_cmp_eq_u32 s82, 12
	s_cselect_b32 s49, s39, s49
	s_cselect_b32 s48, s78, s48
	v_add_u32_e32 v140, s83, v146
	s_cselect_b32 s85, s37, s81
	s_cselect_b32 s84, s79, s80
	s_add_i32 s86, 0, 0x14000
	ds_read_b128 v[136:139], v140
	ds_read_b128 v[152:155], v140 offset:1024
	ds_read_b128 v[156:159], v140 offset:2048
	ds_read_b128 v[160:163], v140 offset:3072
	v_add_u32_e32 v140, s86, v146
	ds_read_b128 v[164:167], v140
	ds_read_b128 v[168:171], v140 offset:1024
	ds_read_b128 v[172:175], v140 offset:2048
	ds_read_b128 v[176:179], v140 offset:3072
	v_lshl_add_u64 v[140:141], s[46:47], 0, v[132:133]
	s_add_i32 m0, s45, 0xc000
	ds_read_b128 v[180:183], v150
	ds_read_b128 v[184:187], v150 offset:1024
	ds_read_b128 v[188:191], v150 offset:2048
	ds_read_b128 v[192:195], v150 offset:3072
	ds_read_b128 v[196:199], v150 offset:4096
	ds_read_b128 v[200:203], v150 offset:5120
	ds_read_b128 v[204:207], v150 offset:6144
	ds_read_b128 v[208:211], v150 offset:7168
	global_load_lds_dwordx4 v[140:141], off
	v_lshl_add_u64 v[140:141], v[140:141], 0, s[12:13]
	s_add_i32 m0, s45, 0xe000
	s_nop 0
	global_load_lds_dwordx4 v[140:141], off
	s_waitcnt vmcnt(8)
	s_waitcnt lgkmcnt(0)
	s_barrier
	s_setprio 1
	s_waitcnt lgkmcnt(0)
	v_mfma_f32_16x16x32_bf16 v[124:127], v[136:139], v[180:183], 0
	v_mfma_f32_16x16x32_bf16 v[120:123], v[156:159], v[180:183], 0
	v_mfma_f32_16x16x32_bf16 v[112:115], v[136:139], v[188:191], 0
	v_mfma_f32_16x16x32_bf16 v[104:107], v[156:159], v[188:191], 0
	v_mfma_f32_16x16x32_bf16 v[96:99], v[136:139], v[196:199], 0
	v_mfma_f32_16x16x32_bf16 v[88:91], v[156:159], v[196:199], 0
	v_mfma_f32_16x16x32_bf16 v[80:83], v[136:139], v[204:207], 0
	v_mfma_f32_16x16x32_bf16 v[72:75], v[156:159], v[204:207], 0
	v_mfma_f32_16x16x32_bf16 v[124:127], v[152:155], v[184:187], v[124:127]
	v_mfma_f32_16x16x32_bf16 v[120:123], v[160:163], v[184:187], v[120:123]
	v_mfma_f32_16x16x32_bf16 v[112:115], v[152:155], v[192:195], v[112:115]
	v_mfma_f32_16x16x32_bf16 v[104:107], v[160:163], v[192:195], v[104:107]
	v_mfma_f32_16x16x32_bf16 v[96:99], v[152:155], v[200:203], v[96:99]
	v_mfma_f32_16x16x32_bf16 v[88:91], v[160:163], v[200:203], v[88:91]
	v_mfma_f32_16x16x32_bf16 v[80:83], v[152:155], v[208:211], v[80:83]
	v_mfma_f32_16x16x32_bf16 v[72:75], v[160:163], v[208:211], v[72:75]
	s_setprio 0
	s_setprio 1
	v_mfma_f32_16x16x32_bf16 v[116:119], v[164:167], v[180:183], 0
	v_mfma_f32_16x16x32_bf16 v[108:111], v[172:175], v[180:183], 0
	v_mfma_f32_16x16x32_bf16 v[100:103], v[164:167], v[188:191], 0
	v_mfma_f32_16x16x32_bf16 v[92:95], v[172:175], v[188:191], 0
	v_mfma_f32_16x16x32_bf16 v[84:87], v[164:167], v[196:199], 0
	v_mfma_f32_16x16x32_bf16 v[76:79], v[172:175], v[196:199], 0
	v_mfma_f32_16x16x32_bf16 v[68:71], v[164:167], v[204:207], 0
	v_mfma_f32_16x16x32_bf16 v[64:67], v[172:175], v[204:207], 0
	v_mfma_f32_16x16x32_bf16 v[116:119], v[168:171], v[184:187], v[116:119]
	v_mfma_f32_16x16x32_bf16 v[108:111], v[176:179], v[184:187], v[108:111]
	v_mfma_f32_16x16x32_bf16 v[100:103], v[168:171], v[192:195], v[100:103]
	v_mfma_f32_16x16x32_bf16 v[92:95], v[176:179], v[192:195], v[92:95]
	v_mfma_f32_16x16x32_bf16 v[84:87], v[168:171], v[200:203], v[84:87]
	v_mfma_f32_16x16x32_bf16 v[76:79], v[176:179], v[200:203], v[76:79]
	v_mfma_f32_16x16x32_bf16 v[68:71], v[168:171], v[208:211], v[68:71]
	v_mfma_f32_16x16x32_bf16 v[64:67], v[176:179], v[208:211], v[64:67]
	s_setprio 0
	s_barrier
	s_add_i32 s83, s83, s69
	v_lshl_add_u64 v[140:141], s[84:85], 0, v[128:129]
	s_mov_b32 m0, s83
	ds_read_b128 v[180:183], v150 offset:16384
	ds_read_b128 v[184:187], v150 offset:17408
	ds_read_b128 v[188:191], v150 offset:18432
	ds_read_b128 v[192:195], v150 offset:19456
	ds_read_b128 v[196:199], v150 offset:20480
	ds_read_b128 v[200:203], v150 offset:21504
	ds_read_b128 v[204:207], v150 offset:22528
	ds_read_b128 v[208:211], v150 offset:23552
	global_load_lds_dwordx4 v[140:141], off
	v_lshl_add_u64 v[212:213], v[140:141], 0, s[12:13]
	s_add_i32 m0, s83, 0x2000
	s_add_i32 s83, s86, s69
	global_load_lds_dwordx4 v[212:213], off
	v_lshl_add_u64 v[212:213], v[140:141], 0, s[14:15]
	s_mov_b32 m0, s83
	s_nop 0
	global_load_lds_dwordx4 v[212:213], off
	v_lshl_add_u64 v[212:213], v[140:141], 0, s[16:17]
	s_add_i32 m0, s83, 0x2000
	s_nop 0
	global_load_lds_dwordx4 v[212:213], off
	v_lshl_add_u64 v[212:213], s[48:49], 0, v[130:131]
	s_mov_b32 m0, s45
	v_lshl_add_u64 v[214:215], v[212:213], 0, s[12:13]
	global_load_lds_dwordx4 v[212:213], off
	s_mov_b32 m0, s71
	s_nop 0
	global_load_lds_dwordx4 v[214:215], off
	s_waitcnt vmcnt(8)
	s_waitcnt lgkmcnt(0)
	s_barrier
	s_setprio 1
	s_waitcnt lgkmcnt(0)
	v_mfma_f32_16x16x32_bf16 v[60:63], v[136:139], v[180:183], 0
	v_mfma_f32_16x16x32_bf16 v[56:59], v[156:159], v[180:183], 0
	v_mfma_f32_16x16x32_bf16 v[48:51], v[136:139], v[188:191], 0
	v_mfma_f32_16x16x32_bf16 v[40:43], v[156:159], v[188:191], 0
	v_mfma_f32_16x16x32_bf16 v[32:35], v[136:139], v[196:199], 0
	v_mfma_f32_16x16x32_bf16 v[24:27], v[156:159], v[196:199], 0
	v_mfma_f32_16x16x32_bf16 v[16:19], v[136:139], v[204:207], 0
	v_mfma_f32_16x16x32_bf16 v[8:11], v[156:159], v[204:207], 0
	v_mfma_f32_16x16x32_bf16 v[60:63], v[152:155], v[184:187], v[60:63]
	v_mfma_f32_16x16x32_bf16 v[56:59], v[160:163], v[184:187], v[56:59]
	v_mfma_f32_16x16x32_bf16 v[48:51], v[152:155], v[192:195], v[48:51]
	v_mfma_f32_16x16x32_bf16 v[40:43], v[160:163], v[192:195], v[40:43]
	v_mfma_f32_16x16x32_bf16 v[32:35], v[152:155], v[200:203], v[32:35]
	v_mfma_f32_16x16x32_bf16 v[24:27], v[160:163], v[200:203], v[24:27]
	v_mfma_f32_16x16x32_bf16 v[16:19], v[152:155], v[208:211], v[16:19]
	v_mfma_f32_16x16x32_bf16 v[8:11], v[160:163], v[208:211], v[8:11]
	s_setprio 0
	s_setprio 1
	v_mfma_f32_16x16x32_bf16 v[52:55], v[164:167], v[180:183], 0
	v_mfma_f32_16x16x32_bf16 v[44:47], v[172:175], v[180:183], 0
	v_mfma_f32_16x16x32_bf16 v[36:39], v[164:167], v[188:191], 0
	v_mfma_f32_16x16x32_bf16 v[28:31], v[172:175], v[188:191], 0
	v_mfma_f32_16x16x32_bf16 v[20:23], v[164:167], v[196:199], 0
	v_mfma_f32_16x16x32_bf16 v[12:15], v[172:175], v[196:199], 0
	v_mfma_f32_16x16x32_bf16 v[4:7], v[164:167], v[204:207], 0
	v_mfma_f32_16x16x32_bf16 v[0:3], v[172:175], v[204:207], 0
	v_mfma_f32_16x16x32_bf16 v[52:55], v[168:171], v[184:187], v[52:55]
	v_mfma_f32_16x16x32_bf16 v[44:47], v[176:179], v[184:187], v[44:47]
	v_mfma_f32_16x16x32_bf16 v[36:39], v[168:171], v[192:195], v[36:39]
	v_mfma_f32_16x16x32_bf16 v[28:31], v[176:179], v[192:195], v[28:31]
	v_mfma_f32_16x16x32_bf16 v[20:23], v[168:171], v[200:203], v[20:23]
	v_mfma_f32_16x16x32_bf16 v[12:15], v[176:179], v[200:203], v[12:15]
	v_mfma_f32_16x16x32_bf16 v[4:7], v[168:171], v[208:211], v[4:7]
	v_mfma_f32_16x16x32_bf16 v[0:3], v[176:179], v[208:211], v[0:3]
	s_setprio 0
	s_barrier
	s_add_i32 s48, 0, 0x18000
	v_add_u32_e32 v151, s48, v146
	s_add_i32 s49, 0, 0x1c000
	ds_read_b128 v[136:139], v151
	ds_read_b128 v[152:155], v151 offset:1024
	ds_read_b128 v[156:159], v151 offset:2048
	ds_read_b128 v[160:163], v151 offset:3072
	v_add_u32_e32 v151, s49, v146
	ds_read_b128 v[164:167], v151
	ds_read_b128 v[168:171], v151 offset:1024
	ds_read_b128 v[172:175], v151 offset:2048
	ds_read_b128 v[176:179], v151 offset:3072
	s_mov_b32 m0, s72
	v_lshl_add_u64 v[214:215], v[212:213], 0, s[14:15]
	ds_read_b128 v[180:183], v150 offset:32768
	ds_read_b128 v[184:187], v150 offset:33792
	ds_read_b128 v[188:191], v150 offset:34816
	ds_read_b128 v[192:195], v150 offset:35840
	ds_read_b128 v[196:199], v150 offset:36864
	ds_read_b128 v[200:203], v150 offset:37888
	ds_read_b128 v[204:207], v150 offset:38912
	ds_read_b128 v[208:211], v150 offset:39936
	global_load_lds_dwordx4 v[214:215], off
	v_lshl_add_u64 v[214:215], v[212:213], 0, s[16:17]
	s_mov_b32 m0, s73
	s_nop 0
	global_load_lds_dwordx4 v[214:215], off
	s_waitcnt vmcnt(8)
	s_waitcnt lgkmcnt(0)
	s_barrier
	s_setprio 1
	s_waitcnt lgkmcnt(0)
	v_mfma_f32_16x16x32_bf16 v[124:127], v[136:139], v[180:183], v[124:127]
	v_mfma_f32_16x16x32_bf16 v[120:123], v[156:159], v[180:183], v[120:123]
	v_mfma_f32_16x16x32_bf16 v[112:115], v[136:139], v[188:191], v[112:115]
	v_mfma_f32_16x16x32_bf16 v[104:107], v[156:159], v[188:191], v[104:107]
	v_mfma_f32_16x16x32_bf16 v[96:99], v[136:139], v[196:199], v[96:99]
	v_mfma_f32_16x16x32_bf16 v[88:91], v[156:159], v[196:199], v[88:91]
	v_mfma_f32_16x16x32_bf16 v[80:83], v[136:139], v[204:207], v[80:83]
	v_mfma_f32_16x16x32_bf16 v[72:75], v[156:159], v[204:207], v[72:75]
	v_mfma_f32_16x16x32_bf16 v[124:127], v[152:155], v[184:187], v[124:127]
	v_mfma_f32_16x16x32_bf16 v[120:123], v[160:163], v[184:187], v[120:123]
	v_mfma_f32_16x16x32_bf16 v[112:115], v[152:155], v[192:195], v[112:115]
	v_mfma_f32_16x16x32_bf16 v[104:107], v[160:163], v[192:195], v[104:107]
	v_mfma_f32_16x16x32_bf16 v[96:99], v[152:155], v[200:203], v[96:99]
	v_mfma_f32_16x16x32_bf16 v[88:91], v[160:163], v[200:203], v[88:91]
	v_mfma_f32_16x16x32_bf16 v[80:83], v[152:155], v[208:211], v[80:83]
	v_mfma_f32_16x16x32_bf16 v[72:75], v[160:163], v[208:211], v[72:75]
	s_setprio 0
	s_setprio 1
	v_mfma_f32_16x16x32_bf16 v[116:119], v[164:167], v[180:183], v[116:119]
	v_mfma_f32_16x16x32_bf16 v[108:111], v[172:175], v[180:183], v[108:111]
	v_mfma_f32_16x16x32_bf16 v[100:103], v[164:167], v[188:191], v[100:103]
	v_mfma_f32_16x16x32_bf16 v[92:95], v[172:175], v[188:191], v[92:95]
	v_mfma_f32_16x16x32_bf16 v[84:87], v[164:167], v[196:199], v[84:87]
	v_mfma_f32_16x16x32_bf16 v[76:79], v[172:175], v[196:199], v[76:79]
	v_mfma_f32_16x16x32_bf16 v[68:71], v[164:167], v[204:207], v[68:71]
	v_mfma_f32_16x16x32_bf16 v[64:67], v[172:175], v[204:207], v[64:67]
	v_mfma_f32_16x16x32_bf16 v[116:119], v[168:171], v[184:187], v[116:119]
	v_mfma_f32_16x16x32_bf16 v[108:111], v[176:179], v[184:187], v[108:111]
	v_mfma_f32_16x16x32_bf16 v[100:103], v[168:171], v[192:195], v[100:103]
	v_mfma_f32_16x16x32_bf16 v[92:95], v[176:179], v[192:195], v[92:95]
	v_mfma_f32_16x16x32_bf16 v[84:87], v[168:171], v[200:203], v[84:87]
	v_mfma_f32_16x16x32_bf16 v[76:79], v[176:179], v[200:203], v[76:79]
	v_mfma_f32_16x16x32_bf16 v[68:71], v[168:171], v[208:211], v[68:71]
	v_mfma_f32_16x16x32_bf16 v[64:67], v[176:179], v[208:211], v[64:67]
	s_setprio 0
	s_barrier
	s_add_i32 s48, s48, s69
	v_lshl_add_u64 v[214:215], v[140:141], 0, s[18:19]
	s_mov_b32 m0, s48
	ds_read_b128 v[180:183], v150 offset:49152
	ds_read_b128 v[184:187], v150 offset:50176
	ds_read_b128 v[188:191], v150 offset:51200
	ds_read_b128 v[192:195], v150 offset:52224
	ds_read_b128 v[196:199], v150 offset:53248
	ds_read_b128 v[200:203], v150 offset:54272
	ds_read_b128 v[204:207], v150 offset:55296
	ds_read_b128 v[208:211], v150 offset:56320
	global_load_lds_dwordx4 v[214:215], off
	v_lshl_add_u64 v[214:215], v[140:141], 0, s[20:21]
	s_add_i32 m0, s48, 0x2000
	s_add_i32 s48, s49, s69
	global_load_lds_dwordx4 v[214:215], off
	v_lshl_add_u64 v[214:215], v[140:141], 0, s[22:23]
	s_mov_b32 m0, s48
	v_lshl_add_u64 v[140:141], v[140:141], 0, s[24:25]
	global_load_lds_dwordx4 v[214:215], off
	s_add_i32 m0, s48, 0x2000
	s_nop 0
	global_load_lds_dwordx4 v[140:141], off
	v_lshl_add_u64 v[140:141], v[212:213], 0, s[18:19]
	s_mov_b32 m0, s10
	s_nop 0
	global_load_lds_dwordx4 v[140:141], off
	v_lshl_add_u64 v[140:141], v[212:213], 0, s[20:21]
	s_mov_b32 m0, s74
	s_nop 0
	global_load_lds_dwordx4 v[140:141], off
	s_waitcnt vmcnt(8)
	s_waitcnt lgkmcnt(0)
	s_barrier
	s_setprio 1
	s_waitcnt lgkmcnt(0)
	v_mfma_f32_16x16x32_bf16 v[60:63], v[136:139], v[180:183], v[60:63]
	v_mfma_f32_16x16x32_bf16 v[56:59], v[156:159], v[180:183], v[56:59]
	v_mfma_f32_16x16x32_bf16 v[48:51], v[136:139], v[188:191], v[48:51]
	v_mfma_f32_16x16x32_bf16 v[40:43], v[156:159], v[188:191], v[40:43]
	v_mfma_f32_16x16x32_bf16 v[32:35], v[136:139], v[196:199], v[32:35]
	v_mfma_f32_16x16x32_bf16 v[24:27], v[156:159], v[196:199], v[24:27]
	v_mfma_f32_16x16x32_bf16 v[16:19], v[136:139], v[204:207], v[16:19]
	v_mfma_f32_16x16x32_bf16 v[8:11], v[156:159], v[204:207], v[8:11]
	v_mfma_f32_16x16x32_bf16 v[60:63], v[152:155], v[184:187], v[60:63]
	v_mfma_f32_16x16x32_bf16 v[56:59], v[160:163], v[184:187], v[56:59]
	v_mfma_f32_16x16x32_bf16 v[48:51], v[152:155], v[192:195], v[48:51]
	v_mfma_f32_16x16x32_bf16 v[40:43], v[160:163], v[192:195], v[40:43]
	v_mfma_f32_16x16x32_bf16 v[32:35], v[152:155], v[200:203], v[32:35]
	v_mfma_f32_16x16x32_bf16 v[24:27], v[160:163], v[200:203], v[24:27]
	v_mfma_f32_16x16x32_bf16 v[16:19], v[152:155], v[208:211], v[16:19]
	v_mfma_f32_16x16x32_bf16 v[8:11], v[160:163], v[208:211], v[8:11]
	s_setprio 0
	s_setprio 1
	v_mfma_f32_16x16x32_bf16 v[52:55], v[164:167], v[180:183], v[52:55]
	v_mfma_f32_16x16x32_bf16 v[44:47], v[172:175], v[180:183], v[44:47]
	v_mfma_f32_16x16x32_bf16 v[36:39], v[164:167], v[188:191], v[36:39]
	v_mfma_f32_16x16x32_bf16 v[28:31], v[172:175], v[188:191], v[28:31]
	v_mfma_f32_16x16x32_bf16 v[20:23], v[164:167], v[196:199], v[20:23]
	v_mfma_f32_16x16x32_bf16 v[12:15], v[172:175], v[196:199], v[12:15]
	v_mfma_f32_16x16x32_bf16 v[4:7], v[164:167], v[204:207], v[4:7]
	v_mfma_f32_16x16x32_bf16 v[0:3], v[172:175], v[204:207], v[0:3]
	v_mfma_f32_16x16x32_bf16 v[52:55], v[168:171], v[184:187], v[52:55]
	v_mfma_f32_16x16x32_bf16 v[44:47], v[176:179], v[184:187], v[44:47]
	v_mfma_f32_16x16x32_bf16 v[36:39], v[168:171], v[192:195], v[36:39]
	v_mfma_f32_16x16x32_bf16 v[28:31], v[176:179], v[192:195], v[28:31]
	v_mfma_f32_16x16x32_bf16 v[20:23], v[168:171], v[200:203], v[20:23]
	v_mfma_f32_16x16x32_bf16 v[12:15], v[176:179], v[200:203], v[12:15]
	v_mfma_f32_16x16x32_bf16 v[4:7], v[168:171], v[208:211], v[4:7]
	v_mfma_f32_16x16x32_bf16 v[0:3], v[176:179], v[208:211], v[0:3]
	s_setprio 0
	s_barrier
	s_add_i32 s82, s82, 2
	s_add_u32 s46, s46, 0x100
	s_addc_u32 s47, s47, 0
	s_add_u32 s80, s80, 0x100
	s_addc_u32 s81, s81, 0
	s_cmp_gt_u32 s82, 13

.LBB0_195:
	s_and_saveexec_b64 s[46:47], s[0:1]
	ds_write_b32 v147, v143
	s_or_b64 exec, exec, s[46:47]
	s_waitcnt lgkmcnt(0)
	s_barrier
	ds_read2_b32 v[152:153], v148 offset1:16
	ds_read2_b32 v[154:155], v148 offset0:32 offset1:48
	ds_read2_b32 v[140:141], v148 offset0:128 offset1:144
	ds_read2_b32 v[138:139], v148 offset0:160 offset1:176
	v_lshl_add_u32 v136, s44, 8, v145
	v_lshl_or_b32 v156, s77, 8, v149
	v_ashrrev_i32_e32 v137, 31, v136
	s_waitcnt lgkmcnt(0)
	v_pk_mul_f32 v[124:125], v[124:125], v[152:153] op_sel_hi:[1,0]
	v_pk_mul_f32 v[120:121], v[120:121], v[152:153] op_sel_hi:[1,0]
	v_ashrrev_i32_e32 v157, 31, v156
	v_pk_mul_f32 v[126:127], v[126:127], v[152:153] op_sel_hi:[1,0]
	v_pk_mul_f32 v[158:159], v[122:123], v[152:153] op_sel_hi:[1,0]
	v_cvt_pk_bf16_f32 v122, v124, v125
	v_cvt_pk_bf16_f32 v123, v126, v127
	v_cvt_pk_bf16_f32 v124, v120, v121
	v_lshlrev_b64 v[120:121], s75, v[136:137]
	v_lshl_add_u64 v[126:127], v[120:121], 1, s[28:29]
	v_lshlrev_b64 v[120:121], 1, v[156:157]
	v_lshl_add_u64 v[126:127], v[126:127], 0, v[120:121]
	v_cvt_pk_bf16_f32 v125, v158, v159
	global_store_dwordx4 v[126:127], v[122:125], off
	v_pk_mul_f32 v[116:117], v[116:117], v[152:153] op_sel_hi:[1,0]
	v_pk_mul_f32 v[118:119], v[118:119], v[152:153] op_sel_hi:[1,0]
	v_pk_mul_f32 v[122:123], v[110:111], v[152:153] op_sel_hi:[1,0]
	v_pk_mul_f32 v[110:111], v[108:109], v[152:153] op_sel_hi:[1,0]
	v_cvt_pk_bf16_f32 v108, v116, v117
	v_cvt_pk_bf16_f32 v109, v118, v119
	v_pk_mul_f32 v[96:97], v[96:97], v[154:155] op_sel_hi:[1,0]
	v_cvt_pk_bf16_f32 v110, v110, v111
	v_cvt_pk_bf16_f32 v111, v122, v123
	global_store_dwordx4 v[126:127], v[108:111], off offset:256
	v_pk_mul_f32 v[84:85], v[84:85], v[154:155] op_sel_hi:[1,0]
	v_pk_mul_f32 v[86:87], v[86:87], v[154:155] op_sel_hi:[1,0]
	v_or_b32_e32 v108, 16, v136
	v_ashrrev_i32_e32 v109, 31, v108
	v_lshlrev_b64 v[108:109], s75, v[108:109]
	v_mov_b32_e32 v110, v153
	v_lshl_add_u64 v[108:109], v[108:109], 1, s[28:29]
	v_pk_mul_f32 v[114:115], v[114:115], v[110:111] op_sel_hi:[1,0]
	v_pk_mul_f32 v[112:113], v[112:113], v[110:111] op_sel_hi:[1,0]
	v_pk_mul_f32 v[116:117], v[106:107], v[110:111] op_sel_hi:[1,0]
	v_pk_mul_f32 v[106:107], v[104:105], v[110:111] op_sel_hi:[1,0]
	v_cvt_pk_bf16_f32 v104, v112, v113
	v_cvt_pk_bf16_f32 v105, v114, v115
	v_lshl_add_u64 v[108:109], v[108:109], 0, v[120:121]
	v_cvt_pk_bf16_f32 v106, v106, v107
	v_cvt_pk_bf16_f32 v107, v116, v117
	global_store_dwordx4 v[108:109], v[104:107], off
	v_pk_mul_f32 v[100:101], v[100:101], v[110:111] op_sel_hi:[1,0]
	v_pk_mul_f32 v[102:103], v[102:103], v[110:111] op_sel_hi:[1,0]
	v_pk_mul_f32 v[104:105], v[94:95], v[110:111] op_sel_hi:[1,0]
	v_pk_mul_f32 v[94:95], v[92:93], v[110:111] op_sel_hi:[1,0]
	v_cvt_pk_bf16_f32 v92, v100, v101
	v_cvt_pk_bf16_f32 v93, v102, v103
	v_pk_mul_f32 v[60:61], v[60:61], v[140:141] op_sel_hi:[1,0]
	v_cvt_pk_bf16_f32 v94, v94, v95
	v_cvt_pk_bf16_f32 v95, v104, v105
	global_store_dwordx4 v[108:109], v[92:95], off offset:256
	v_pk_mul_f32 v[62:63], v[62:63], v[140:141] op_sel_hi:[1,0]
	v_pk_mul_f32 v[52:53], v[52:53], v[140:141] op_sel_hi:[1,0]
	v_or_b32_e32 v92, 32, v136
	v_ashrrev_i32_e32 v93, 31, v92
	v_lshlrev_b64 v[92:93], s75, v[92:93]
	v_lshl_add_u64 v[92:93], v[92:93], 1, s[28:29]
	v_pk_mul_f32 v[94:95], v[98:99], v[154:155] op_sel_hi:[1,0]
	v_pk_mul_f32 v[98:99], v[90:91], v[154:155] op_sel_hi:[1,0]
	v_pk_mul_f32 v[90:91], v[88:89], v[154:155] op_sel_hi:[1,0]
	v_cvt_pk_bf16_f32 v88, v96, v97
	v_cvt_pk_bf16_f32 v89, v94, v95
	v_lshl_add_u64 v[92:93], v[92:93], 0, v[120:121]
	v_cvt_pk_bf16_f32 v90, v90, v91
	v_cvt_pk_bf16_f32 v91, v98, v99
	global_store_dwordx4 v[92:93], v[88:91], off
	v_pk_mul_f32 v[54:55], v[54:55], v[140:141] op_sel_hi:[1,0]
	v_pk_mul_f32 v[32:33], v[32:33], v[138:139] op_sel_hi:[1,0]
	v_pk_mul_f32 v[88:89], v[78:79], v[154:155] op_sel_hi:[1,0]
	v_pk_mul_f32 v[78:79], v[76:77], v[154:155] op_sel_hi:[1,0]
	v_cvt_pk_bf16_f32 v76, v84, v85
	v_cvt_pk_bf16_f32 v77, v86, v87
	v_pk_mul_f32 v[20:21], v[20:21], v[138:139] op_sel_hi:[1,0]
	v_cvt_pk_bf16_f32 v78, v78, v79
	v_cvt_pk_bf16_f32 v79, v88, v89
	global_store_dwordx4 v[92:93], v[76:79], off offset:256
	v_pk_mul_f32 v[22:23], v[22:23], v[138:139] op_sel_hi:[1,0]
	s_andn2_b64 vcc, exec, s[4:5]
	v_or_b32_e32 v76, 48, v136
	v_ashrrev_i32_e32 v77, 31, v76
	v_lshlrev_b64 v[76:77], s75, v[76:77]
	v_mov_b32_e32 v78, v155
	v_lshl_add_u64 v[76:77], v[76:77], 1, s[28:29]
	v_pk_mul_f32 v[82:83], v[82:83], v[78:79] op_sel_hi:[1,0]
	v_pk_mul_f32 v[80:81], v[80:81], v[78:79] op_sel_hi:[1,0]
	v_pk_mul_f32 v[84:85], v[74:75], v[78:79] op_sel_hi:[1,0]
	v_pk_mul_f32 v[74:75], v[72:73], v[78:79] op_sel_hi:[1,0]
	v_cvt_pk_bf16_f32 v72, v80, v81
	v_cvt_pk_bf16_f32 v73, v82, v83
	v_lshl_add_u64 v[76:77], v[76:77], 0, v[120:121]
	v_cvt_pk_bf16_f32 v74, v74, v75
	v_cvt_pk_bf16_f32 v75, v84, v85
	global_store_dwordx4 v[76:77], v[72:75], off
	v_pk_mul_f32 v[68:69], v[68:69], v[78:79] op_sel_hi:[1,0]
	v_pk_mul_f32 v[70:71], v[70:71], v[78:79] op_sel_hi:[1,0]
	v_pk_mul_f32 v[72:73], v[66:67], v[78:79] op_sel_hi:[1,0]
	v_pk_mul_f32 v[66:67], v[64:65], v[78:79] op_sel_hi:[1,0]
	v_cvt_pk_bf16_f32 v64, v68, v69
	v_cvt_pk_bf16_f32 v65, v70, v71
	s_mov_b64 s[4:5], -1
	v_cvt_pk_bf16_f32 v66, v66, v67
	v_cvt_pk_bf16_f32 v67, v72, v73
	global_store_dwordx4 v[76:77], v[64:67], off offset:256
	s_nop 1
	v_add_u32_e32 v64, 0x80, v136
	v_ashrrev_i32_e32 v65, 31, v64
	v_pk_mul_f32 v[66:67], v[58:59], v[140:141] op_sel_hi:[1,0]
	v_pk_mul_f32 v[58:59], v[56:57], v[140:141] op_sel_hi:[1,0]
	v_cvt_pk_bf16_f32 v56, v60, v61
	v_lshlrev_b64 v[60:61], s75, v[64:65]
	v_lshl_add_u64 v[60:61], v[60:61], 1, s[28:29]
	v_cvt_pk_bf16_f32 v57, v62, v63
	v_lshl_add_u64 v[60:61], v[60:61], 0, v[120:121]
	v_cvt_pk_bf16_f32 v58, v58, v59
	v_cvt_pk_bf16_f32 v59, v66, v67
	global_store_dwordx4 v[60:61], v[56:59], off
	s_nop 1
	v_pk_mul_f32 v[56:57], v[46:47], v[140:141] op_sel_hi:[1,0]
	v_pk_mul_f32 v[46:47], v[44:45], v[140:141] op_sel_hi:[1,0]
	v_cvt_pk_bf16_f32 v44, v52, v53
	v_cvt_pk_bf16_f32 v45, v54, v55
	s_nop 0
	v_cvt_pk_bf16_f32 v46, v46, v47
	v_cvt_pk_bf16_f32 v47, v56, v57
	global_store_dwordx4 v[60:61], v[44:47], off offset:256
	s_nop 1
	v_add_u32_e32 v44, 0x90, v136
	v_ashrrev_i32_e32 v45, 31, v44
	v_lshlrev_b64 v[44:45], s75, v[44:45]
	v_mov_b32_e32 v46, v141
	v_lshl_add_u64 v[44:45], v[44:45], 1, s[28:29]
	v_pk_mul_f32 v[50:51], v[50:51], v[46:47] op_sel_hi:[1,0]
	v_pk_mul_f32 v[48:49], v[48:49], v[46:47] op_sel_hi:[1,0]
	v_pk_mul_f32 v[52:53], v[42:43], v[46:47] op_sel_hi:[1,0]
	v_pk_mul_f32 v[42:43], v[40:41], v[46:47] op_sel_hi:[1,0]
	v_cvt_pk_bf16_f32 v40, v48, v49
	v_cvt_pk_bf16_f32 v41, v50, v51
	v_lshl_add_u64 v[44:45], v[44:45], 0, v[120:121]
	v_cvt_pk_bf16_f32 v42, v42, v43
	v_cvt_pk_bf16_f32 v43, v52, v53
	global_store_dwordx4 v[44:45], v[40:43], off
	v_pk_mul_f32 v[36:37], v[36:37], v[46:47] op_sel_hi:[1,0]
	v_pk_mul_f32 v[38:39], v[38:39], v[46:47] op_sel_hi:[1,0]
	v_pk_mul_f32 v[40:41], v[30:31], v[46:47] op_sel_hi:[1,0]
	v_pk_mul_f32 v[30:31], v[28:29], v[46:47] op_sel_hi:[1,0]
	v_cvt_pk_bf16_f32 v28, v36, v37
	v_cvt_pk_bf16_f32 v29, v38, v39
	s_nop 0
	v_cvt_pk_bf16_f32 v30, v30, v31
	v_cvt_pk_bf16_f32 v31, v40, v41
	global_store_dwordx4 v[44:45], v[28:31], off offset:256
	s_nop 1
	v_add_u32_e32 v28, 0xa0, v136
	v_ashrrev_i32_e32 v29, 31, v28
	v_lshlrev_b64 v[28:29], s75, v[28:29]
	v_lshl_add_u64 v[28:29], v[28:29], 1, s[28:29]
	v_pk_mul_f32 v[30:31], v[34:35], v[138:139] op_sel_hi:[1,0]
	v_pk_mul_f32 v[34:35], v[26:27], v[138:139] op_sel_hi:[1,0]
	v_pk_mul_f32 v[26:27], v[24:25], v[138:139] op_sel_hi:[1,0]
	v_cvt_pk_bf16_f32 v24, v32, v33
	v_cvt_pk_bf16_f32 v25, v30, v31
	v_lshl_add_u64 v[28:29], v[28:29], 0, v[120:121]
	v_cvt_pk_bf16_f32 v26, v26, v27
	v_cvt_pk_bf16_f32 v27, v34, v35
	global_store_dwordx4 v[28:29], v[24:27], off
	s_nop 1
	v_pk_mul_f32 v[24:25], v[14:15], v[138:139] op_sel_hi:[1,0]
	v_pk_mul_f32 v[14:15], v[12:13], v[138:139] op_sel_hi:[1,0]
	v_cvt_pk_bf16_f32 v12, v20, v21
	v_cvt_pk_bf16_f32 v13, v22, v23
	s_nop 0
	v_cvt_pk_bf16_f32 v14, v14, v15
	v_cvt_pk_bf16_f32 v15, v24, v25
	global_store_dwordx4 v[28:29], v[12:15], off offset:256
	s_nop 1
	v_add_u32_e32 v12, 0xb0, v136
	v_ashrrev_i32_e32 v13, 31, v12
	v_lshlrev_b64 v[12:13], s75, v[12:13]
	v_mov_b32_e32 v14, v139
	v_lshl_add_u64 v[12:13], v[12:13], 1, s[28:29]
	v_pk_mul_f32 v[18:19], v[18:19], v[14:15] op_sel_hi:[1,0]
	v_pk_mul_f32 v[16:17], v[16:17], v[14:15] op_sel_hi:[1,0]
	v_pk_mul_f32 v[20:21], v[10:11], v[14:15] op_sel_hi:[1,0]
	v_pk_mul_f32 v[10:11], v[8:9], v[14:15] op_sel_hi:[1,0]
	v_cvt_pk_bf16_f32 v8, v16, v17
	v_cvt_pk_bf16_f32 v9, v18, v19
	v_lshl_add_u64 v[12:13], v[12:13], 0, v[120:121]
	v_cvt_pk_bf16_f32 v10, v10, v11
	v_cvt_pk_bf16_f32 v11, v20, v21
	global_store_dwordx4 v[12:13], v[8:11], off
	v_pk_mul_f32 v[6:7], v[6:7], v[14:15] op_sel_hi:[1,0]
	v_pk_mul_f32 v[4:5], v[4:5], v[14:15] op_sel_hi:[1,0]
	v_pk_mul_f32 v[8:9], v[2:3], v[14:15] op_sel_hi:[1,0]
	v_pk_mul_f32 v[2:3], v[0:1], v[14:15] op_sel_hi:[1,0]
	v_cvt_pk_bf16_f32 v0, v4, v5
	v_cvt_pk_bf16_f32 v1, v6, v7
	s_nop 0
	v_cvt_pk_bf16_f32 v2, v2, v3
	v_cvt_pk_bf16_f32 v3, v8, v9
	global_store_dwordx4 v[12:13], v[0:3], off offset:256
	s_cbranch_vccnz .LBB0_184
	s_andn2_b64 vcc, exec, s[26:27]
	s_cbranch_vccnz .LBB0_183
	s_mov_b32 s98, 1
	s_branch .LBB0_183

.LBB0_228:
	s_ashr_i32 s45, s44, 31
	s_lshl_b64 s[46:47], s[44:45], 19
	s_add_u32 s46, s64, s46
	s_addc_u32 s47, s65, s47
	s_and_b64 s[48:49], s[38:39], exec
	s_cselect_b32 s22, s47, s15
	s_cselect_b32 s45, s46, s14
	s_ashr_i32 s43, s42, 31
	s_lshl_b64 s[48:49], s[42:43], 19
	s_add_u32 s48, s6, s48
	s_addc_u32 s49, s19, s49
	s_and_b64 s[60:61], s[38:39], exec
	s_cselect_b32 s43, s49, s17
	s_cselect_b32 s84, s48, s16
	s_add_u32 s60, s14, 0x40080
	s_addc_u32 s61, s15, 0
	s_add_u32 s16, s16, 0x100
	s_addc_u32 s17, s17, 0
	s_mov_b32 s85, -2
	s_cmp_eq_u32 s98, 1
	s_cbranch_scc0 .Lnostb1
	s_mov_b32 s98, 0
	s_barrier
.Lnostb1:
	s_add_u32 s14, s60, 0xfffc0080
	s_addc_u32 s15, s61, -1
	s_add_i32 s18, 0, 0x10000
	s_cmp_eq_u32 s85, 12
	s_cselect_b32 s15, s22, s15
	s_cselect_b32 s14, s45, s14
	v_add_u32_e32 v137, s18, v141
	s_cselect_b32 vcc_hi, s43, s17
	s_cselect_b32 vcc_lo, s84, s16
	s_add_i32 s21, 0, 0x14000
	ds_read_b128 v[146:149], v137
	ds_read_b128 v[150:153], v137 offset:1024
	ds_read_b128 v[154:157], v137 offset:2048
	ds_read_b128 v[158:161], v137 offset:3072
	v_add_u32_e32 v137, s21, v141
	ds_read_b128 v[162:165], v137
	ds_read_b128 v[166:169], v137 offset:1024
	ds_read_b128 v[170:173], v137 offset:2048
	ds_read_b128 v[174:177], v137 offset:3072
	v_lshl_add_u64 v[138:139], s[60:61], 0, v[184:185]
	s_add_i32 m0, s25, 0xc000
	ds_read_b128 v[178:181], v145
	ds_read_b128 v[194:197], v145 offset:1024
	ds_read_b128 v[198:201], v145 offset:2048
	ds_read_b128 v[202:205], v145 offset:3072
	ds_read_b128 v[206:209], v145 offset:4096
	ds_read_b128 v[210:213], v145 offset:5120
	ds_read_b128 v[214:217], v145 offset:6144
	ds_read_b128 v[218:221], v145 offset:7168
	global_load_lds_dwordx4 v[138:139], off
	v_lshl_add_u64 v[138:139], v[138:139], 0, s[34:35]
	s_add_i32 m0, s25, 0xe000
	s_nop 0
	global_load_lds_dwordx4 v[138:139], off
	s_waitcnt vmcnt(8)
	s_waitcnt lgkmcnt(0)
	s_barrier
	s_setprio 1
	s_waitcnt lgkmcnt(0)
	v_mfma_f32_16x16x32_bf16 v[124:127], v[146:149], v[178:181], 0
	v_mfma_f32_16x16x32_bf16 v[120:123], v[154:157], v[178:181], 0
	v_mfma_f32_16x16x32_bf16 v[112:115], v[146:149], v[198:201], 0
	v_mfma_f32_16x16x32_bf16 v[104:107], v[154:157], v[198:201], 0
	v_mfma_f32_16x16x32_bf16 v[96:99], v[146:149], v[206:209], 0
	v_mfma_f32_16x16x32_bf16 v[88:91], v[154:157], v[206:209], 0
	v_mfma_f32_16x16x32_bf16 v[80:83], v[146:149], v[214:217], 0
	v_mfma_f32_16x16x32_bf16 v[72:75], v[154:157], v[214:217], 0
	v_mfma_f32_16x16x32_bf16 v[124:127], v[150:153], v[194:197], v[124:127]
	v_mfma_f32_16x16x32_bf16 v[120:123], v[158:161], v[194:197], v[120:123]
	v_mfma_f32_16x16x32_bf16 v[112:115], v[150:153], v[202:205], v[112:115]
	v_mfma_f32_16x16x32_bf16 v[104:107], v[158:161], v[202:205], v[104:107]
	v_mfma_f32_16x16x32_bf16 v[96:99], v[150:153], v[210:213], v[96:99]
	v_mfma_f32_16x16x32_bf16 v[88:91], v[158:161], v[210:213], v[88:91]
	v_mfma_f32_16x16x32_bf16 v[80:83], v[150:153], v[218:221], v[80:83]
	v_mfma_f32_16x16x32_bf16 v[72:75], v[158:161], v[218:221], v[72:75]
	s_setprio 0
	s_setprio 1
	v_mfma_f32_16x16x32_bf16 v[116:119], v[162:165], v[178:181], 0
	v_mfma_f32_16x16x32_bf16 v[108:111], v[170:173], v[178:181], 0
	v_mfma_f32_16x16x32_bf16 v[100:103], v[162:165], v[198:201], 0
	v_mfma_f32_16x16x32_bf16 v[92:95], v[170:173], v[198:201], 0
	v_mfma_f32_16x16x32_bf16 v[84:87], v[162:165], v[206:209], 0
	v_mfma_f32_16x16x32_bf16 v[76:79], v[170:173], v[206:209], 0
	v_mfma_f32_16x16x32_bf16 v[68:71], v[162:165], v[214:217], 0
	v_mfma_f32_16x16x32_bf16 v[64:67], v[170:173], v[214:217], 0
	v_mfma_f32_16x16x32_bf16 v[116:119], v[166:169], v[194:197], v[116:119]
	v_mfma_f32_16x16x32_bf16 v[108:111], v[174:177], v[194:197], v[108:111]
	v_mfma_f32_16x16x32_bf16 v[100:103], v[166:169], v[202:205], v[100:103]
	v_mfma_f32_16x16x32_bf16 v[92:95], v[174:177], v[202:205], v[92:95]
	v_mfma_f32_16x16x32_bf16 v[84:87], v[166:169], v[210:213], v[84:87]
	v_mfma_f32_16x16x32_bf16 v[76:79], v[174:177], v[210:213], v[76:79]
	v_mfma_f32_16x16x32_bf16 v[68:71], v[166:169], v[218:221], v[68:71]
	v_mfma_f32_16x16x32_bf16 v[64:67], v[174:177], v[218:221], v[64:67]
	s_setprio 0
	s_barrier
	s_add_i32 s18, s18, s23
	v_lshl_add_u64 v[138:139], vcc, 0, v[128:129]
	s_mov_b32 m0, s18
	ds_read_b128 v[178:181], v145 offset:16384
	ds_read_b128 v[194:197], v145 offset:17408
	ds_read_b128 v[198:201], v145 offset:18432
	ds_read_b128 v[202:205], v145 offset:19456
	ds_read_b128 v[206:209], v145 offset:20480
	ds_read_b128 v[210:213], v145 offset:21504
	ds_read_b128 v[214:217], v145 offset:22528
	ds_read_b128 v[218:221], v145 offset:23552
	global_load_lds_dwordx4 v[138:139], off
	v_lshl_add_u64 v[182:183], v[138:139], 0, s[34:35]
	s_add_i32 m0, s18, 0x2000
	s_add_i32 s18, s21, s23
	global_load_lds_dwordx4 v[182:183], off
	v_lshl_add_u64 v[182:183], v[138:139], 0, s[92:93]
	s_mov_b32 m0, s18
	s_nop 0
	global_load_lds_dwordx4 v[182:183], off
	v_lshl_add_u64 v[182:183], v[138:139], 0, s[52:53]
	s_add_i32 m0, s18, 0x2000
	s_nop 0
	global_load_lds_dwordx4 v[182:183], off
	v_lshl_add_u64 v[182:183], s[14:15], 0, v[130:131]
	s_mov_b32 m0, s25
	v_lshl_add_u64 v[186:187], v[182:183], 0, s[34:35]
	global_load_lds_dwordx4 v[182:183], off
	s_mov_b32 m0, s26
	s_nop 0
	global_load_lds_dwordx4 v[186:187], off
	s_waitcnt vmcnt(8)
	s_waitcnt lgkmcnt(0)
	s_barrier
	s_setprio 1
	s_waitcnt lgkmcnt(0)
	v_mfma_f32_16x16x32_bf16 v[60:63], v[146:149], v[178:181], 0
	v_mfma_f32_16x16x32_bf16 v[56:59], v[154:157], v[178:181], 0
	v_mfma_f32_16x16x32_bf16 v[48:51], v[146:149], v[198:201], 0
	v_mfma_f32_16x16x32_bf16 v[40:43], v[154:157], v[198:201], 0
	v_mfma_f32_16x16x32_bf16 v[32:35], v[146:149], v[206:209], 0
	v_mfma_f32_16x16x32_bf16 v[24:27], v[154:157], v[206:209], 0
	v_mfma_f32_16x16x32_bf16 v[16:19], v[146:149], v[214:217], 0
	v_mfma_f32_16x16x32_bf16 v[8:11], v[154:157], v[214:217], 0
	v_mfma_f32_16x16x32_bf16 v[60:63], v[150:153], v[194:197], v[60:63]
	v_mfma_f32_16x16x32_bf16 v[56:59], v[158:161], v[194:197], v[56:59]
	v_mfma_f32_16x16x32_bf16 v[48:51], v[150:153], v[202:205], v[48:51]
	v_mfma_f32_16x16x32_bf16 v[40:43], v[158:161], v[202:205], v[40:43]
	v_mfma_f32_16x16x32_bf16 v[32:35], v[150:153], v[210:213], v[32:35]
	v_mfma_f32_16x16x32_bf16 v[24:27], v[158:161], v[210:213], v[24:27]
	v_mfma_f32_16x16x32_bf16 v[16:19], v[150:153], v[218:221], v[16:19]
	v_mfma_f32_16x16x32_bf16 v[8:11], v[158:161], v[218:221], v[8:11]
	s_setprio 0
	s_setprio 1
	v_mfma_f32_16x16x32_bf16 v[52:55], v[162:165], v[178:181], 0
	v_mfma_f32_16x16x32_bf16 v[44:47], v[170:173], v[178:181], 0
	v_mfma_f32_16x16x32_bf16 v[36:39], v[162:165], v[198:201], 0
	v_mfma_f32_16x16x32_bf16 v[28:31], v[170:173], v[198:201], 0
	v_mfma_f32_16x16x32_bf16 v[20:23], v[162:165], v[206:209], 0
	v_mfma_f32_16x16x32_bf16 v[12:15], v[170:173], v[206:209], 0
	v_mfma_f32_16x16x32_bf16 v[4:7], v[162:165], v[214:217], 0
	v_mfma_f32_16x16x32_bf16 v[0:3], v[170:173], v[214:217], 0
	v_mfma_f32_16x16x32_bf16 v[52:55], v[166:169], v[194:197], v[52:55]
	v_mfma_f32_16x16x32_bf16 v[44:47], v[174:177], v[194:197], v[44:47]
	v_mfma_f32_16x16x32_bf16 v[36:39], v[166:169], v[202:205], v[36:39]
	v_mfma_f32_16x16x32_bf16 v[28:31], v[174:177], v[202:205], v[28:31]
	v_mfma_f32_16x16x32_bf16 v[20:23], v[166:169], v[210:213], v[20:23]
	v_mfma_f32_16x16x32_bf16 v[12:15], v[174:177], v[210:213], v[12:15]
	v_mfma_f32_16x16x32_bf16 v[4:7], v[166:169], v[218:221], v[4:7]
	v_mfma_f32_16x16x32_bf16 v[0:3], v[174:177], v[218:221], v[0:3]
	s_setprio 0
	s_barrier
	s_add_i32 s14, 0, 0x18000
	v_add_u32_e32 v137, s14, v141
	s_add_i32 s15, 0, 0x1c000
	ds_read_b128 v[146:149], v137
	ds_read_b128 v[150:153], v137 offset:1024
	ds_read_b128 v[154:157], v137 offset:2048
	ds_read_b128 v[158:161], v137 offset:3072
	v_add_u32_e32 v137, s15, v141
	ds_read_b128 v[162:165], v137
	ds_read_b128 v[166:169], v137 offset:1024
	ds_read_b128 v[170:173], v137 offset:2048
	ds_read_b128 v[174:177], v137 offset:3072
	s_mov_b32 m0, s27
	v_lshl_add_u64 v[186:187], v[182:183], 0, s[92:93]
	ds_read_b128 v[178:181], v145 offset:32768
	ds_read_b128 v[194:197], v145 offset:33792
	ds_read_b128 v[198:201], v145 offset:34816
	ds_read_b128 v[202:205], v145 offset:35840
	ds_read_b128 v[206:209], v145 offset:36864
	ds_read_b128 v[210:213], v145 offset:37888
	ds_read_b128 v[214:217], v145 offset:38912
	ds_read_b128 v[218:221], v145 offset:39936
	global_load_lds_dwordx4 v[186:187], off
	v_lshl_add_u64 v[186:187], v[182:183], 0, s[52:53]
	s_mov_b32 m0, s28
	s_nop 0
	global_load_lds_dwordx4 v[186:187], off
	s_waitcnt vmcnt(8)
	s_waitcnt lgkmcnt(0)
	s_barrier
	s_setprio 1
	s_waitcnt lgkmcnt(0)
	v_mfma_f32_16x16x32_bf16 v[124:127], v[146:149], v[178:181], v[124:127]
	v_mfma_f32_16x16x32_bf16 v[120:123], v[154:157], v[178:181], v[120:123]
	v_mfma_f32_16x16x32_bf16 v[112:115], v[146:149], v[198:201], v[112:115]
	v_mfma_f32_16x16x32_bf16 v[104:107], v[154:157], v[198:201], v[104:107]
	v_mfma_f32_16x16x32_bf16 v[96:99], v[146:149], v[206:209], v[96:99]
	v_mfma_f32_16x16x32_bf16 v[88:91], v[154:157], v[206:209], v[88:91]
	v_mfma_f32_16x16x32_bf16 v[80:83], v[146:149], v[214:217], v[80:83]
	v_mfma_f32_16x16x32_bf16 v[72:75], v[154:157], v[214:217], v[72:75]
	v_mfma_f32_16x16x32_bf16 v[124:127], v[150:153], v[194:197], v[124:127]
	v_mfma_f32_16x16x32_bf16 v[120:123], v[158:161], v[194:197], v[120:123]
	v_mfma_f32_16x16x32_bf16 v[112:115], v[150:153], v[202:205], v[112:115]
	v_mfma_f32_16x16x32_bf16 v[104:107], v[158:161], v[202:205], v[104:107]
	v_mfma_f32_16x16x32_bf16 v[96:99], v[150:153], v[210:213], v[96:99]
	v_mfma_f32_16x16x32_bf16 v[88:91], v[158:161], v[210:213], v[88:91]
	v_mfma_f32_16x16x32_bf16 v[80:83], v[150:153], v[218:221], v[80:83]
	v_mfma_f32_16x16x32_bf16 v[72:75], v[158:161], v[218:221], v[72:75]
	s_setprio 0
	s_setprio 1
	v_mfma_f32_16x16x32_bf16 v[116:119], v[162:165], v[178:181], v[116:119]
	v_mfma_f32_16x16x32_bf16 v[108:111], v[170:173], v[178:181], v[108:111]
	v_mfma_f32_16x16x32_bf16 v[100:103], v[162:165], v[198:201], v[100:103]
	v_mfma_f32_16x16x32_bf16 v[92:95], v[170:173], v[198:201], v[92:95]
	v_mfma_f32_16x16x32_bf16 v[84:87], v[162:165], v[206:209], v[84:87]
	v_mfma_f32_16x16x32_bf16 v[76:79], v[170:173], v[206:209], v[76:79]
	v_mfma_f32_16x16x32_bf16 v[68:71], v[162:165], v[214:217], v[68:71]
	v_mfma_f32_16x16x32_bf16 v[64:67], v[170:173], v[214:217], v[64:67]
	v_mfma_f32_16x16x32_bf16 v[116:119], v[166:169], v[194:197], v[116:119]
	v_mfma_f32_16x16x32_bf16 v[108:111], v[174:177], v[194:197], v[108:111]
	v_mfma_f32_16x16x32_bf16 v[100:103], v[166:169], v[202:205], v[100:103]
	v_mfma_f32_16x16x32_bf16 v[92:95], v[174:177], v[202:205], v[92:95]
	v_mfma_f32_16x16x32_bf16 v[84:87], v[166:169], v[210:213], v[84:87]
	v_mfma_f32_16x16x32_bf16 v[76:79], v[174:177], v[210:213], v[76:79]
	v_mfma_f32_16x16x32_bf16 v[68:71], v[166:169], v[218:221], v[68:71]
	v_mfma_f32_16x16x32_bf16 v[64:67], v[174:177], v[218:221], v[64:67]
	s_setprio 0
	s_barrier
	s_add_i32 s14, s14, s23
	v_lshl_add_u64 v[186:187], v[138:139], 0, s[56:57]
	s_mov_b32 m0, s14
	ds_read_b128 v[178:181], v145 offset:49152
	ds_read_b128 v[194:197], v145 offset:50176
	ds_read_b128 v[198:201], v145 offset:51200
	ds_read_b128 v[202:205], v145 offset:52224
	ds_read_b128 v[206:209], v145 offset:53248
	ds_read_b128 v[210:213], v145 offset:54272
	ds_read_b128 v[214:217], v145 offset:55296
	ds_read_b128 v[218:221], v145 offset:56320
	global_load_lds_dwordx4 v[186:187], off
	v_lshl_add_u64 v[186:187], v[138:139], 0, s[96:97]
	s_add_i32 m0, s14, 0x2000
	s_add_i32 s14, s15, s23
	global_load_lds_dwordx4 v[186:187], off
	v_lshl_add_u64 v[186:187], v[138:139], 0, s[88:89]
	s_mov_b32 m0, s14
	v_lshl_add_u64 v[138:139], v[138:139], 0, s[68:69]
	global_load_lds_dwordx4 v[186:187], off
	s_add_i32 m0, s14, 0x2000
	s_nop 0
	global_load_lds_dwordx4 v[138:139], off
	v_lshl_add_u64 v[138:139], v[182:183], 0, s[56:57]
	s_mov_b32 m0, s29
	s_nop 0
	global_load_lds_dwordx4 v[138:139], off
	v_lshl_add_u64 v[138:139], v[182:183], 0, s[96:97]
	s_mov_b32 m0, s30
	s_nop 0
	global_load_lds_dwordx4 v[138:139], off
	s_waitcnt vmcnt(8)
	s_waitcnt lgkmcnt(0)
	s_barrier
	s_setprio 1
	s_waitcnt lgkmcnt(0)
	v_mfma_f32_16x16x32_bf16 v[60:63], v[146:149], v[178:181], v[60:63]
	v_mfma_f32_16x16x32_bf16 v[56:59], v[154:157], v[178:181], v[56:59]
	v_mfma_f32_16x16x32_bf16 v[48:51], v[146:149], v[198:201], v[48:51]
	v_mfma_f32_16x16x32_bf16 v[40:43], v[154:157], v[198:201], v[40:43]
	v_mfma_f32_16x16x32_bf16 v[32:35], v[146:149], v[206:209], v[32:35]
	v_mfma_f32_16x16x32_bf16 v[24:27], v[154:157], v[206:209], v[24:27]
	v_mfma_f32_16x16x32_bf16 v[16:19], v[146:149], v[214:217], v[16:19]
	v_mfma_f32_16x16x32_bf16 v[8:11], v[154:157], v[214:217], v[8:11]
	v_mfma_f32_16x16x32_bf16 v[60:63], v[150:153], v[194:197], v[60:63]
	v_mfma_f32_16x16x32_bf16 v[56:59], v[158:161], v[194:197], v[56:59]
	v_mfma_f32_16x16x32_bf16 v[48:51], v[150:153], v[202:205], v[48:51]
	v_mfma_f32_16x16x32_bf16 v[40:43], v[158:161], v[202:205], v[40:43]
	v_mfma_f32_16x16x32_bf16 v[32:35], v[150:153], v[210:213], v[32:35]
	v_mfma_f32_16x16x32_bf16 v[24:27], v[158:161], v[210:213], v[24:27]
	v_mfma_f32_16x16x32_bf16 v[16:19], v[150:153], v[218:221], v[16:19]
	v_mfma_f32_16x16x32_bf16 v[8:11], v[158:161], v[218:221], v[8:11]
	s_setprio 0
	s_setprio 1
	v_mfma_f32_16x16x32_bf16 v[52:55], v[162:165], v[178:181], v[52:55]
	v_mfma_f32_16x16x32_bf16 v[44:47], v[170:173], v[178:181], v[44:47]
	v_mfma_f32_16x16x32_bf16 v[36:39], v[162:165], v[198:201], v[36:39]
	v_mfma_f32_16x16x32_bf16 v[28:31], v[170:173], v[198:201], v[28:31]
	v_mfma_f32_16x16x32_bf16 v[20:23], v[162:165], v[206:209], v[20:23]
	v_mfma_f32_16x16x32_bf16 v[12:15], v[170:173], v[206:209], v[12:15]
	v_mfma_f32_16x16x32_bf16 v[4:7], v[162:165], v[214:217], v[4:7]
	v_mfma_f32_16x16x32_bf16 v[0:3], v[170:173], v[214:217], v[0:3]
	v_mfma_f32_16x16x32_bf16 v[52:55], v[166:169], v[194:197], v[52:55]
	v_mfma_f32_16x16x32_bf16 v[44:47], v[174:177], v[194:197], v[44:47]
	v_mfma_f32_16x16x32_bf16 v[36:39], v[166:169], v[202:205], v[36:39]
	v_mfma_f32_16x16x32_bf16 v[28:31], v[174:177], v[202:205], v[28:31]
	v_mfma_f32_16x16x32_bf16 v[20:23], v[166:169], v[210:213], v[20:23]
	v_mfma_f32_16x16x32_bf16 v[12:15], v[174:177], v[210:213], v[12:15]
	v_mfma_f32_16x16x32_bf16 v[4:7], v[166:169], v[218:221], v[4:7]
	v_mfma_f32_16x16x32_bf16 v[0:3], v[174:177], v[218:221], v[0:3]
	s_setprio 0
	s_barrier
	s_add_i32 s85, s85, 2
	s_add_u32 s60, s60, 0x100
	s_addc_u32 s61, s61, 0
	s_add_u32 s16, s16, 0x100
	s_addc_u32 s17, s17, 0
	s_cmp_gt_u32 s85, 13

.LBB0_234:
	s_or_b64 exec, exec, s[14:15]
	s_waitcnt lgkmcnt(0)
	s_barrier
	ds_read2_b32 v[148:149], v143 offset1:16
	ds_read2_b32 v[150:151], v143 offset0:32 offset1:48
	ds_read2_b32 v[138:139], v143 offset0:128 offset1:144
	ds_read2_b32 v[136:137], v143 offset0:160 offset1:176
	v_lshl_add_u32 v146, s50, 8, v140
	v_lshl_or_b32 v152, s51, 8, v144
	v_ashrrev_i32_e32 v147, 31, v146
	s_waitcnt lgkmcnt(0)
	v_pk_mul_f32 v[124:125], v[124:125], v[148:149] op_sel_hi:[1,0]
	v_pk_mul_f32 v[120:121], v[120:121], v[148:149] op_sel_hi:[1,0]
	v_ashrrev_i32_e32 v153, 31, v152
	v_pk_mul_f32 v[126:127], v[126:127], v[148:149] op_sel_hi:[1,0]
	v_pk_mul_f32 v[154:155], v[122:123], v[148:149] op_sel_hi:[1,0]
	v_cvt_pk_bf16_f32 v122, v124, v125
	v_cvt_pk_bf16_f32 v123, v126, v127
	v_cvt_pk_bf16_f32 v124, v120, v121
	v_lshlrev_b64 v[120:121], 11, v[146:147]
	v_lshl_add_u64 v[120:121], s[72:73], 0, v[120:121]
	v_lshlrev_b64 v[126:127], 1, v[152:153]
	v_lshl_add_u64 v[120:121], v[120:121], 0, v[126:127]
	v_cvt_pk_bf16_f32 v125, v154, v155
	global_store_dwordx4 v[120:121], v[122:125], off
	v_pk_mul_f32 v[116:117], v[116:117], v[148:149] op_sel_hi:[1,0]
	v_pk_mul_f32 v[118:119], v[118:119], v[148:149] op_sel_hi:[1,0]
	v_pk_mul_f32 v[122:123], v[110:111], v[148:149] op_sel_hi:[1,0]
	v_pk_mul_f32 v[110:111], v[108:109], v[148:149] op_sel_hi:[1,0]
	v_cvt_pk_bf16_f32 v108, v116, v117
	v_cvt_pk_bf16_f32 v109, v118, v119
	v_pk_mul_f32 v[96:97], v[96:97], v[150:151] op_sel_hi:[1,0]
	v_cvt_pk_bf16_f32 v110, v110, v111
	v_cvt_pk_bf16_f32 v111, v122, v123
	global_store_dwordx4 v[120:121], v[108:111], off offset:256
	v_pk_mul_f32 v[84:85], v[84:85], v[150:151] op_sel_hi:[1,0]
	v_pk_mul_f32 v[86:87], v[86:87], v[150:151] op_sel_hi:[1,0]
	v_or_b32_e32 v108, 16, v146
	v_ashrrev_i32_e32 v109, 31, v108
	v_lshlrev_b64 v[108:109], 11, v[108:109]
	v_mov_b32_e32 v110, v149
	v_lshl_add_u64 v[108:109], s[72:73], 0, v[108:109]
	v_pk_mul_f32 v[114:115], v[114:115], v[110:111] op_sel_hi:[1,0]
	v_pk_mul_f32 v[112:113], v[112:113], v[110:111] op_sel_hi:[1,0]
	v_pk_mul_f32 v[116:117], v[106:107], v[110:111] op_sel_hi:[1,0]
	v_pk_mul_f32 v[106:107], v[104:105], v[110:111] op_sel_hi:[1,0]
	v_cvt_pk_bf16_f32 v104, v112, v113
	v_cvt_pk_bf16_f32 v105, v114, v115
	v_lshl_add_u64 v[108:109], v[108:109], 0, v[126:127]
	v_cvt_pk_bf16_f32 v106, v106, v107
	v_cvt_pk_bf16_f32 v107, v116, v117
	global_store_dwordx4 v[108:109], v[104:107], off
	v_pk_mul_f32 v[100:101], v[100:101], v[110:111] op_sel_hi:[1,0]
	v_pk_mul_f32 v[102:103], v[102:103], v[110:111] op_sel_hi:[1,0]
	v_pk_mul_f32 v[104:105], v[94:95], v[110:111] op_sel_hi:[1,0]
	v_pk_mul_f32 v[94:95], v[92:93], v[110:111] op_sel_hi:[1,0]
	v_cvt_pk_bf16_f32 v92, v100, v101
	v_cvt_pk_bf16_f32 v93, v102, v103
	v_pk_mul_f32 v[62:63], v[62:63], v[138:139] op_sel_hi:[1,0]
	v_cvt_pk_bf16_f32 v94, v94, v95
	v_cvt_pk_bf16_f32 v95, v104, v105
	global_store_dwordx4 v[108:109], v[92:95], off offset:256
	s_mov_b32 s14, 0x40000
	v_pk_mul_f32 v[60:61], v[60:61], v[138:139] op_sel_hi:[1,0]
	v_or_b32_e32 v92, 32, v146
	v_ashrrev_i32_e32 v93, 31, v92
	v_lshlrev_b64 v[92:93], 11, v[92:93]
	v_lshl_add_u64 v[92:93], s[72:73], 0, v[92:93]
	v_pk_mul_f32 v[94:95], v[98:99], v[150:151] op_sel_hi:[1,0]
	v_pk_mul_f32 v[98:99], v[90:91], v[150:151] op_sel_hi:[1,0]
	v_pk_mul_f32 v[90:91], v[88:89], v[150:151] op_sel_hi:[1,0]
	v_cvt_pk_bf16_f32 v88, v96, v97
	v_cvt_pk_bf16_f32 v89, v94, v95
	v_lshl_add_u64 v[92:93], v[92:93], 0, v[126:127]
	v_cvt_pk_bf16_f32 v90, v90, v91
	v_cvt_pk_bf16_f32 v91, v98, v99
	global_store_dwordx4 v[92:93], v[88:91], off
	v_pk_mul_f32 v[52:53], v[52:53], v[138:139] op_sel_hi:[1,0]
	v_pk_mul_f32 v[54:55], v[54:55], v[138:139] op_sel_hi:[1,0]
	v_pk_mul_f32 v[88:89], v[78:79], v[150:151] op_sel_hi:[1,0]
	v_pk_mul_f32 v[78:79], v[76:77], v[150:151] op_sel_hi:[1,0]
	v_cvt_pk_bf16_f32 v76, v84, v85
	v_cvt_pk_bf16_f32 v77, v86, v87
	v_pk_mul_f32 v[20:21], v[20:21], v[136:137] op_sel_hi:[1,0]
	v_cvt_pk_bf16_f32 v78, v78, v79
	v_cvt_pk_bf16_f32 v79, v88, v89
	global_store_dwordx4 v[92:93], v[76:79], off offset:256
	v_pk_mul_f32 v[22:23], v[22:23], v[136:137] op_sel_hi:[1,0]
	s_nop 0
	v_or_b32_e32 v76, 48, v146
	v_ashrrev_i32_e32 v77, 31, v76
	v_lshlrev_b64 v[76:77], 11, v[76:77]
	v_mov_b32_e32 v78, v151
	v_lshl_add_u64 v[76:77], s[72:73], 0, v[76:77]
	v_pk_mul_f32 v[82:83], v[82:83], v[78:79] op_sel_hi:[1,0]
	v_pk_mul_f32 v[80:81], v[80:81], v[78:79] op_sel_hi:[1,0]
	v_pk_mul_f32 v[84:85], v[74:75], v[78:79] op_sel_hi:[1,0]
	v_pk_mul_f32 v[74:75], v[72:73], v[78:79] op_sel_hi:[1,0]
	v_cvt_pk_bf16_f32 v72, v80, v81
	v_cvt_pk_bf16_f32 v73, v82, v83
	v_lshl_add_u64 v[76:77], v[76:77], 0, v[126:127]
	v_cvt_pk_bf16_f32 v74, v74, v75
	v_cvt_pk_bf16_f32 v75, v84, v85
	global_store_dwordx4 v[76:77], v[72:75], off
	v_pk_mul_f32 v[70:71], v[70:71], v[78:79] op_sel_hi:[1,0]
	v_pk_mul_f32 v[68:69], v[68:69], v[78:79] op_sel_hi:[1,0]
	v_pk_mul_f32 v[72:73], v[66:67], v[78:79] op_sel_hi:[1,0]
	v_pk_mul_f32 v[66:67], v[64:65], v[78:79] op_sel_hi:[1,0]
	v_cvt_pk_bf16_f32 v64, v68, v69
	v_cvt_pk_bf16_f32 v65, v70, v71
	s_nop 0
	v_cvt_pk_bf16_f32 v66, v66, v67
	v_cvt_pk_bf16_f32 v67, v72, v73
	global_store_dwordx4 v[76:77], v[64:67], off offset:256
	s_nop 1
	v_pk_mul_f32 v[64:65], v[58:59], v[138:139] op_sel_hi:[1,0]
	v_pk_mul_f32 v[58:59], v[56:57], v[138:139] op_sel_hi:[1,0]
	v_cvt_pk_bf16_f32 v56, v60, v61
	v_cvt_pk_bf16_f32 v57, v62, v63
	v_add_co_u32_e32 v62, vcc, s14, v120
	v_cvt_pk_bf16_f32 v58, v58, v59
	v_cvt_pk_bf16_f32 v59, v64, v65
	v_lshl_add_u64 v[60:61], v[120:121], 0, s[92:93]
	s_nop 0
	v_addc_co_u32_e32 v63, vcc, 0, v121, vcc
	global_store_dwordx4 v[62:63], v[56:59], off
	s_mov_b64 s[14:15], 0x48000
	s_nop 0
	v_pk_mul_f32 v[56:57], v[46:47], v[138:139] op_sel_hi:[1,0]
	v_pk_mul_f32 v[46:47], v[44:45], v[138:139] op_sel_hi:[1,0]
	v_cvt_pk_bf16_f32 v44, v52, v53
	v_cvt_pk_bf16_f32 v45, v54, v55
	s_nop 0
	v_cvt_pk_bf16_f32 v46, v46, v47
	v_cvt_pk_bf16_f32 v47, v56, v57
	global_store_dwordx4 v[60:61], v[44:47], off offset:256
	s_nop 1
	v_mov_b32_e32 v44, v139
	v_pk_mul_f32 v[46:47], v[50:51], v[44:45] op_sel_hi:[1,0]
	v_pk_mul_f32 v[48:49], v[48:49], v[44:45] op_sel_hi:[1,0]
	v_pk_mul_f32 v[50:51], v[42:43], v[44:45] op_sel_hi:[1,0]
	v_pk_mul_f32 v[42:43], v[40:41], v[44:45] op_sel_hi:[1,0]
	v_cvt_pk_bf16_f32 v40, v48, v49
	v_cvt_pk_bf16_f32 v41, v46, v47
	v_lshl_add_u64 v[46:47], v[120:121], 0, s[14:15]
	s_mov_b32 s14, 0x48000
	v_add_co_u32_e32 v48, vcc, s14, v120
	v_cvt_pk_bf16_f32 v42, v42, v43
	v_cvt_pk_bf16_f32 v43, v50, v51
	v_pk_mul_f32 v[38:39], v[38:39], v[44:45] op_sel_hi:[1,0]
	s_nop 0
	v_addc_co_u32_e32 v49, vcc, 0, v121, vcc
	global_store_dwordx4 v[48:49], v[40:43], off
	v_pk_mul_f32 v[36:37], v[36:37], v[44:45] op_sel_hi:[1,0]
	s_mov_b64 s[14:15], 0x50000
	v_pk_mul_f32 v[40:41], v[30:31], v[44:45] op_sel_hi:[1,0]
	v_pk_mul_f32 v[30:31], v[28:29], v[44:45] op_sel_hi:[1,0]
	v_cvt_pk_bf16_f32 v28, v36, v37
	v_cvt_pk_bf16_f32 v29, v38, v39
	s_nop 0
	v_cvt_pk_bf16_f32 v30, v30, v31
	v_cvt_pk_bf16_f32 v31, v40, v41
	global_store_dwordx4 v[46:47], v[28:31], off offset:256
	s_nop 1
	v_pk_mul_f32 v[28:29], v[34:35], v[136:137] op_sel_hi:[1,0]
	v_pk_mul_f32 v[30:31], v[32:33], v[136:137] op_sel_hi:[1,0]
	v_pk_mul_f32 v[32:33], v[26:27], v[136:137] op_sel_hi:[1,0]
	v_pk_mul_f32 v[26:27], v[24:25], v[136:137] op_sel_hi:[1,0]
	v_cvt_pk_bf16_f32 v24, v30, v31
	v_cvt_pk_bf16_f32 v25, v28, v29
	v_lshl_add_u64 v[28:29], v[120:121], 0, s[14:15]
	s_mov_b32 s14, 0x50000
	v_add_co_u32_e32 v30, vcc, s14, v120
	v_cvt_pk_bf16_f32 v26, v26, v27
	v_cvt_pk_bf16_f32 v27, v32, v33
	s_mov_b32 s14, 0x58000
	s_nop 0
	v_addc_co_u32_e32 v31, vcc, 0, v121, vcc
	global_store_dwordx4 v[30:31], v[24:27], off
	s_nop 1
	v_pk_mul_f32 v[24:25], v[14:15], v[136:137] op_sel_hi:[1,0]
	v_pk_mul_f32 v[14:15], v[12:13], v[136:137] op_sel_hi:[1,0]
	v_cvt_pk_bf16_f32 v12, v20, v21
	v_cvt_pk_bf16_f32 v13, v22, v23
	s_nop 0
	v_cvt_pk_bf16_f32 v14, v14, v15
	v_cvt_pk_bf16_f32 v15, v24, v25
	global_store_dwordx4 v[28:29], v[12:15], off offset:256
	s_nop 1
	v_mov_b32_e32 v12, v137
	v_pk_mul_f32 v[16:17], v[16:17], v[12:13] op_sel_hi:[1,0]
	v_pk_mul_f32 v[14:15], v[18:19], v[12:13] op_sel_hi:[1,0]
	v_pk_mul_f32 v[18:19], v[10:11], v[12:13] op_sel_hi:[1,0]
	v_pk_mul_f32 v[10:11], v[8:9], v[12:13] op_sel_hi:[1,0]
	v_cvt_pk_bf16_f32 v8, v16, v17
	v_add_co_u32_e32 v16, vcc, s14, v120
	v_cvt_pk_bf16_f32 v9, v14, v15
	v_cvt_pk_bf16_f32 v10, v10, v11
	v_cvt_pk_bf16_f32 v11, v18, v19
	v_lshl_add_u64 v[14:15], v[120:121], 0, s[2:3]
	s_nop 0
	v_addc_co_u32_e32 v17, vcc, 0, v121, vcc
	global_store_dwordx4 v[16:17], v[8:11], off
	s_andn2_b64 vcc, exec, s[38:39]
	s_mov_b64 s[14:15], -1
	v_pk_mul_f32 v[8:9], v[2:3], v[12:13] op_sel_hi:[1,0]
	v_pk_mul_f32 v[2:3], v[0:1], v[12:13] op_sel_hi:[1,0]
	v_pk_mul_f32 v[6:7], v[6:7], v[12:13] op_sel_hi:[1,0]
	v_pk_mul_f32 v[4:5], v[4:5], v[12:13] op_sel_hi:[1,0]
	s_nop 0
	v_cvt_pk_bf16_f32 v0, v4, v5
	v_cvt_pk_bf16_f32 v1, v6, v7
	v_cvt_pk_bf16_f32 v2, v2, v3
	v_cvt_pk_bf16_f32 v3, v8, v9
	global_store_dwordx4 v[14:15], v[0:3], off offset:256
	s_cbranch_vccnz .LBB0_225
	s_lshl_b32 s14, s44, 8
	s_ashr_i32 s15, s14, 31
	v_lshl_add_u64 v[0:1], s[14:15], 2, v[132:133]
	global_load_dword v136, v[0:1], off
	s_andn2_b64 vcc, exec, s[12:13]
	s_cbranch_vccnz .LBB0_224
	s_mov_b32 s98, 1
	s_branch .LBB0_224

.Lnostb2:
	s_add_u32 s14, s60, 0xfffc0080
	s_addc_u32 s15, s61, -1
	s_add_i32 s18, 0, 0x10000
	s_cmp_eq_u32 s85, 12
	s_cselect_b32 s15, s22, s15
	s_cselect_b32 s14, s45, s14
	s_waitcnt lgkmcnt(0)
	v_add_u32_e32 v137, s18, v149
	s_cselect_b32 vcc_hi, s43, s17
	s_cselect_b32 vcc_lo, s84, s16
	s_add_i32 s21, 0, 0x14000
	ds_read_b128 v[138:141], v137
	ds_read_b128 v[142:145], v137 offset:1024
	ds_read_b128 v[154:157], v137 offset:2048
	ds_read_b128 v[158:161], v137 offset:3072
	v_add_u32_e32 v137, s21, v149
	ds_read_b128 v[162:165], v137
	ds_read_b128 v[166:169], v137 offset:1024
	ds_read_b128 v[170:173], v137 offset:2048
	ds_read_b128 v[174:177], v137 offset:3072
	v_lshl_add_u64 v[146:147], s[60:61], 0, v[134:135]
	s_add_i32 m0, s25, 0xc000
	ds_read_b128 v[178:181], v153
	ds_read_b128 v[194:197], v153 offset:1024
	ds_read_b128 v[198:201], v153 offset:2048
	ds_read_b128 v[202:205], v153 offset:3072
	ds_read_b128 v[206:209], v153 offset:4096
	ds_read_b128 v[210:213], v153 offset:5120
	ds_read_b128 v[214:217], v153 offset:6144
	ds_read_b128 v[218:221], v153 offset:7168
	global_load_lds_dwordx4 v[146:147], off
	v_lshl_add_u64 v[146:147], v[146:147], 0, s[34:35]
	s_add_i32 m0, s25, 0xe000
	s_nop 0
	global_load_lds_dwordx4 v[146:147], off
	s_waitcnt vmcnt(8)
	s_waitcnt lgkmcnt(0)
	s_barrier
	s_setprio 1
	s_waitcnt lgkmcnt(0)
	v_mfma_f32_16x16x32_bf16 v[124:127], v[138:141], v[178:181], 0
	v_mfma_f32_16x16x32_bf16 v[120:123], v[154:157], v[178:181], 0
	v_mfma_f32_16x16x32_bf16 v[108:111], v[138:141], v[198:201], 0
	v_mfma_f32_16x16x32_bf16 v[104:107], v[154:157], v[198:201], 0
	v_mfma_f32_16x16x32_bf16 v[96:99], v[138:141], v[206:209], 0
	v_mfma_f32_16x16x32_bf16 v[88:91], v[154:157], v[206:209], 0
	v_mfma_f32_16x16x32_bf16 v[80:83], v[138:141], v[214:217], 0
	v_mfma_f32_16x16x32_bf16 v[72:75], v[154:157], v[214:217], 0
	v_mfma_f32_16x16x32_bf16 v[124:127], v[142:145], v[194:197], v[124:127]
	v_mfma_f32_16x16x32_bf16 v[120:123], v[158:161], v[194:197], v[120:123]
	v_mfma_f32_16x16x32_bf16 v[108:111], v[142:145], v[202:205], v[108:111]
	v_mfma_f32_16x16x32_bf16 v[104:107], v[158:161], v[202:205], v[104:107]
	v_mfma_f32_16x16x32_bf16 v[96:99], v[142:145], v[210:213], v[96:99]
	v_mfma_f32_16x16x32_bf16 v[88:91], v[158:161], v[210:213], v[88:91]
	v_mfma_f32_16x16x32_bf16 v[80:83], v[142:145], v[218:221], v[80:83]
	v_mfma_f32_16x16x32_bf16 v[72:75], v[158:161], v[218:221], v[72:75]
	s_setprio 0
	s_setprio 1
	v_mfma_f32_16x16x32_bf16 v[116:119], v[162:165], v[178:181], 0
	v_mfma_f32_16x16x32_bf16 v[112:115], v[170:173], v[178:181], 0
	v_mfma_f32_16x16x32_bf16 v[100:103], v[162:165], v[198:201], 0
	v_mfma_f32_16x16x32_bf16 v[92:95], v[170:173], v[198:201], 0
	v_mfma_f32_16x16x32_bf16 v[84:87], v[162:165], v[206:209], 0
	v_mfma_f32_16x16x32_bf16 v[76:79], v[170:173], v[206:209], 0
	v_mfma_f32_16x16x32_bf16 v[68:71], v[162:165], v[214:217], 0
	v_mfma_f32_16x16x32_bf16 v[64:67], v[170:173], v[214:217], 0
	v_mfma_f32_16x16x32_bf16 v[116:119], v[166:169], v[194:197], v[116:119]
	v_mfma_f32_16x16x32_bf16 v[112:115], v[174:177], v[194:197], v[112:115]
	v_mfma_f32_16x16x32_bf16 v[100:103], v[166:169], v[202:205], v[100:103]
	v_mfma_f32_16x16x32_bf16 v[92:95], v[174:177], v[202:205], v[92:95]
	v_mfma_f32_16x16x32_bf16 v[84:87], v[166:169], v[210:213], v[84:87]
	v_mfma_f32_16x16x32_bf16 v[76:79], v[174:177], v[210:213], v[76:79]
	v_mfma_f32_16x16x32_bf16 v[68:71], v[166:169], v[218:221], v[68:71]
	v_mfma_f32_16x16x32_bf16 v[64:67], v[174:177], v[218:221], v[64:67]
	s_setprio 0
	s_barrier
	s_add_i32 s18, s18, s23
	v_lshl_add_u64 v[146:147], vcc, 0, v[128:129]
	s_mov_b32 m0, s18
	ds_read_b128 v[178:181], v153 offset:16384
	ds_read_b128 v[194:197], v153 offset:17408
	ds_read_b128 v[198:201], v153 offset:18432
	ds_read_b128 v[202:205], v153 offset:19456
	ds_read_b128 v[206:209], v153 offset:20480
	ds_read_b128 v[210:213], v153 offset:21504
	ds_read_b128 v[214:217], v153 offset:22528
	ds_read_b128 v[218:221], v153 offset:23552
	global_load_lds_dwordx4 v[146:147], off
	v_lshl_add_u64 v[182:183], v[146:147], 0, s[34:35]
	s_add_i32 m0, s18, 0x2000
	s_add_i32 s18, s21, s23
	global_load_lds_dwordx4 v[182:183], off
	v_lshl_add_u64 v[182:183], v[146:147], 0, s[92:93]
	s_mov_b32 m0, s18
	s_nop 0
	global_load_lds_dwordx4 v[182:183], off
	v_lshl_add_u64 v[182:183], v[146:147], 0, s[52:53]
	s_add_i32 m0, s18, 0x2000
	s_nop 0
	global_load_lds_dwordx4 v[182:183], off
	v_lshl_add_u64 v[182:183], s[14:15], 0, v[130:131]
	s_mov_b32 m0, s25
	v_lshl_add_u64 v[186:187], v[182:183], 0, s[34:35]
	global_load_lds_dwordx4 v[182:183], off
	s_mov_b32 m0, s26
	s_nop 0
	global_load_lds_dwordx4 v[186:187], off
	s_waitcnt vmcnt(8)
	s_waitcnt lgkmcnt(0)
	s_barrier
	s_setprio 1
	s_waitcnt lgkmcnt(0)
	v_mfma_f32_16x16x32_bf16 v[60:63], v[138:141], v[178:181], 0
	v_mfma_f32_16x16x32_bf16 v[56:59], v[154:157], v[178:181], 0
	v_mfma_f32_16x16x32_bf16 v[48:51], v[138:141], v[198:201], 0
	v_mfma_f32_16x16x32_bf16 v[40:43], v[154:157], v[198:201], 0
	v_mfma_f32_16x16x32_bf16 v[32:35], v[138:141], v[206:209], 0
	v_mfma_f32_16x16x32_bf16 v[24:27], v[154:157], v[206:209], 0
	v_mfma_f32_16x16x32_bf16 v[16:19], v[138:141], v[214:217], 0
	v_mfma_f32_16x16x32_bf16 v[8:11], v[154:157], v[214:217], 0
	v_mfma_f32_16x16x32_bf16 v[60:63], v[142:145], v[194:197], v[60:63]
	v_mfma_f32_16x16x32_bf16 v[56:59], v[158:161], v[194:197], v[56:59]
	v_mfma_f32_16x16x32_bf16 v[48:51], v[142:145], v[202:205], v[48:51]
	v_mfma_f32_16x16x32_bf16 v[40:43], v[158:161], v[202:205], v[40:43]
	v_mfma_f32_16x16x32_bf16 v[32:35], v[142:145], v[210:213], v[32:35]
	v_mfma_f32_16x16x32_bf16 v[24:27], v[158:161], v[210:213], v[24:27]
	v_mfma_f32_16x16x32_bf16 v[16:19], v[142:145], v[218:221], v[16:19]
	v_mfma_f32_16x16x32_bf16 v[8:11], v[158:161], v[218:221], v[8:11]
	s_setprio 0
	s_setprio 1
	v_mfma_f32_16x16x32_bf16 v[52:55], v[162:165], v[178:181], 0
	v_mfma_f32_16x16x32_bf16 v[44:47], v[170:173], v[178:181], 0
	v_mfma_f32_16x16x32_bf16 v[36:39], v[162:165], v[198:201], 0
	v_mfma_f32_16x16x32_bf16 v[28:31], v[170:173], v[198:201], 0
	v_mfma_f32_16x16x32_bf16 v[20:23], v[162:165], v[206:209], 0
	v_mfma_f32_16x16x32_bf16 v[12:15], v[170:173], v[206:209], 0
	v_mfma_f32_16x16x32_bf16 v[4:7], v[162:165], v[214:217], 0
	v_mfma_f32_16x16x32_bf16 v[0:3], v[170:173], v[214:217], 0
	v_mfma_f32_16x16x32_bf16 v[52:55], v[166:169], v[194:197], v[52:55]
	v_mfma_f32_16x16x32_bf16 v[44:47], v[174:177], v[194:197], v[44:47]
	v_mfma_f32_16x16x32_bf16 v[36:39], v[166:169], v[202:205], v[36:39]
	v_mfma_f32_16x16x32_bf16 v[28:31], v[174:177], v[202:205], v[28:31]
	v_mfma_f32_16x16x32_bf16 v[20:23], v[166:169], v[210:213], v[20:23]
	v_mfma_f32_16x16x32_bf16 v[12:15], v[174:177], v[210:213], v[12:15]
	v_mfma_f32_16x16x32_bf16 v[4:7], v[166:169], v[218:221], v[4:7]
	v_mfma_f32_16x16x32_bf16 v[0:3], v[174:177], v[218:221], v[0:3]
	s_setprio 0
	s_barrier
	s_add_i32 s14, 0, 0x18000
	v_add_u32_e32 v137, s14, v149
	s_add_i32 s15, 0, 0x1c000
	ds_read_b128 v[138:141], v137
	ds_read_b128 v[142:145], v137 offset:1024
	ds_read_b128 v[154:157], v137 offset:2048
	ds_read_b128 v[158:161], v137 offset:3072
	v_add_u32_e32 v137, s15, v149
	ds_read_b128 v[162:165], v137
	ds_read_b128 v[166:169], v137 offset:1024
	ds_read_b128 v[170:173], v137 offset:2048
	ds_read_b128 v[174:177], v137 offset:3072
	s_mov_b32 m0, s27
	v_lshl_add_u64 v[186:187], v[182:183], 0, s[92:93]
	ds_read_b128 v[178:181], v153 offset:32768
	ds_read_b128 v[194:197], v153 offset:33792
	ds_read_b128 v[198:201], v153 offset:34816
	ds_read_b128 v[202:205], v153 offset:35840
	ds_read_b128 v[206:209], v153 offset:36864
	ds_read_b128 v[210:213], v153 offset:37888
	ds_read_b128 v[214:217], v153 offset:38912
	ds_read_b128 v[218:221], v153 offset:39936
	global_load_lds_dwordx4 v[186:187], off
	v_lshl_add_u64 v[186:187], v[182:183], 0, s[52:53]
	s_mov_b32 m0, s28
	s_nop 0
	global_load_lds_dwordx4 v[186:187], off
	s_waitcnt vmcnt(8)
	s_waitcnt lgkmcnt(0)
	s_barrier
	s_setprio 1
	s_waitcnt lgkmcnt(0)
	v_mfma_f32_16x16x32_bf16 v[124:127], v[138:141], v[178:181], v[124:127]
	v_mfma_f32_16x16x32_bf16 v[120:123], v[154:157], v[178:181], v[120:123]
	v_mfma_f32_16x16x32_bf16 v[108:111], v[138:141], v[198:201], v[108:111]
	v_mfma_f32_16x16x32_bf16 v[104:107], v[154:157], v[198:201], v[104:107]
	v_mfma_f32_16x16x32_bf16 v[96:99], v[138:141], v[206:209], v[96:99]
	v_mfma_f32_16x16x32_bf16 v[88:91], v[154:157], v[206:209], v[88:91]
	v_mfma_f32_16x16x32_bf16 v[80:83], v[138:141], v[214:217], v[80:83]
	v_mfma_f32_16x16x32_bf16 v[72:75], v[154:157], v[214:217], v[72:75]
	v_mfma_f32_16x16x32_bf16 v[124:127], v[142:145], v[194:197], v[124:127]
	v_mfma_f32_16x16x32_bf16 v[120:123], v[158:161], v[194:197], v[120:123]
	v_mfma_f32_16x16x32_bf16 v[108:111], v[142:145], v[202:205], v[108:111]
	v_mfma_f32_16x16x32_bf16 v[104:107], v[158:161], v[202:205], v[104:107]
	v_mfma_f32_16x16x32_bf16 v[96:99], v[142:145], v[210:213], v[96:99]
	v_mfma_f32_16x16x32_bf16 v[88:91], v[158:161], v[210:213], v[88:91]
	v_mfma_f32_16x16x32_bf16 v[80:83], v[142:145], v[218:221], v[80:83]
	v_mfma_f32_16x16x32_bf16 v[72:75], v[158:161], v[218:221], v[72:75]
	s_setprio 0
	s_setprio 1
	v_mfma_f32_16x16x32_bf16 v[116:119], v[162:165], v[178:181], v[116:119]
	v_mfma_f32_16x16x32_bf16 v[112:115], v[170:173], v[178:181], v[112:115]
	v_mfma_f32_16x16x32_bf16 v[100:103], v[162:165], v[198:201], v[100:103]
	v_mfma_f32_16x16x32_bf16 v[92:95], v[170:173], v[198:201], v[92:95]
	v_mfma_f32_16x16x32_bf16 v[84:87], v[162:165], v[206:209], v[84:87]
	v_mfma_f32_16x16x32_bf16 v[76:79], v[170:173], v[206:209], v[76:79]
	v_mfma_f32_16x16x32_bf16 v[68:71], v[162:165], v[214:217], v[68:71]
	v_mfma_f32_16x16x32_bf16 v[64:67], v[170:173], v[214:217], v[64:67]
	v_mfma_f32_16x16x32_bf16 v[116:119], v[166:169], v[194:197], v[116:119]
	v_mfma_f32_16x16x32_bf16 v[112:115], v[174:177], v[194:197], v[112:115]
	v_mfma_f32_16x16x32_bf16 v[100:103], v[166:169], v[202:205], v[100:103]
	v_mfma_f32_16x16x32_bf16 v[92:95], v[174:177], v[202:205], v[92:95]
	v_mfma_f32_16x16x32_bf16 v[84:87], v[166:169], v[210:213], v[84:87]
	v_mfma_f32_16x16x32_bf16 v[76:79], v[174:177], v[210:213], v[76:79]
	v_mfma_f32_16x16x32_bf16 v[68:71], v[166:169], v[218:221], v[68:71]
	v_mfma_f32_16x16x32_bf16 v[64:67], v[174:177], v[218:221], v[64:67]
	s_setprio 0
	s_barrier
	s_add_i32 s14, s14, s23
	v_lshl_add_u64 v[186:187], v[146:147], 0, s[56:57]
	s_mov_b32 m0, s14
	ds_read_b128 v[178:181], v153 offset:49152
	ds_read_b128 v[194:197], v153 offset:50176
	ds_read_b128 v[198:201], v153 offset:51200
	ds_read_b128 v[202:205], v153 offset:52224
	ds_read_b128 v[206:209], v153 offset:53248
	ds_read_b128 v[210:213], v153 offset:54272
	ds_read_b128 v[214:217], v153 offset:55296
	ds_read_b128 v[218:221], v153 offset:56320
	global_load_lds_dwordx4 v[186:187], off
	v_lshl_add_u64 v[186:187], v[146:147], 0, s[96:97]
	s_add_i32 m0, s14, 0x2000
	s_add_i32 s14, s15, s23
	global_load_lds_dwordx4 v[186:187], off
	v_lshl_add_u64 v[186:187], v[146:147], 0, s[88:89]
	s_mov_b32 m0, s14
	v_lshl_add_u64 v[146:147], v[146:147], 0, s[68:69]
	global_load_lds_dwordx4 v[186:187], off
	s_add_i32 m0, s14, 0x2000
	s_nop 0
	global_load_lds_dwordx4 v[146:147], off
	v_lshl_add_u64 v[146:147], v[182:183], 0, s[56:57]
	s_mov_b32 m0, s29
	s_nop 0
	global_load_lds_dwordx4 v[146:147], off
	v_lshl_add_u64 v[146:147], v[182:183], 0, s[96:97]
	s_mov_b32 m0, s30
	s_nop 0
	global_load_lds_dwordx4 v[146:147], off
	s_waitcnt vmcnt(8)
	s_waitcnt lgkmcnt(0)
	s_barrier
	s_setprio 1
	s_waitcnt lgkmcnt(0)
	v_mfma_f32_16x16x32_bf16 v[60:63], v[138:141], v[178:181], v[60:63]
	v_mfma_f32_16x16x32_bf16 v[56:59], v[154:157], v[178:181], v[56:59]
	v_mfma_f32_16x16x32_bf16 v[48:51], v[138:141], v[198:201], v[48:51]
	v_mfma_f32_16x16x32_bf16 v[40:43], v[154:157], v[198:201], v[40:43]
	v_mfma_f32_16x16x32_bf16 v[32:35], v[138:141], v[206:209], v[32:35]
	v_mfma_f32_16x16x32_bf16 v[24:27], v[154:157], v[206:209], v[24:27]
	v_mfma_f32_16x16x32_bf16 v[16:19], v[138:141], v[214:217], v[16:19]
	v_mfma_f32_16x16x32_bf16 v[8:11], v[154:157], v[214:217], v[8:11]
	v_mfma_f32_16x16x32_bf16 v[60:63], v[142:145], v[194:197], v[60:63]
	v_mfma_f32_16x16x32_bf16 v[56:59], v[158:161], v[194:197], v[56:59]
	v_mfma_f32_16x16x32_bf16 v[48:51], v[142:145], v[202:205], v[48:51]
	v_mfma_f32_16x16x32_bf16 v[40:43], v[158:161], v[202:205], v[40:43]
	v_mfma_f32_16x16x32_bf16 v[32:35], v[142:145], v[210:213], v[32:35]
	v_mfma_f32_16x16x32_bf16 v[24:27], v[158:161], v[210:213], v[24:27]
	v_mfma_f32_16x16x32_bf16 v[16:19], v[142:145], v[218:221], v[16:19]
	v_mfma_f32_16x16x32_bf16 v[8:11], v[158:161], v[218:221], v[8:11]
	s_setprio 0
	s_setprio 1
	v_mfma_f32_16x16x32_bf16 v[52:55], v[162:165], v[178:181], v[52:55]
	v_mfma_f32_16x16x32_bf16 v[44:47], v[170:173], v[178:181], v[44:47]
	v_mfma_f32_16x16x32_bf16 v[36:39], v[162:165], v[198:201], v[36:39]
	v_mfma_f32_16x16x32_bf16 v[28:31], v[170:173], v[198:201], v[28:31]
	v_mfma_f32_16x16x32_bf16 v[20:23], v[162:165], v[206:209], v[20:23]
	v_mfma_f32_16x16x32_bf16 v[12:15], v[170:173], v[206:209], v[12:15]
	v_mfma_f32_16x16x32_bf16 v[4:7], v[162:165], v[214:217], v[4:7]
	v_mfma_f32_16x16x32_bf16 v[0:3], v[170:173], v[214:217], v[0:3]
	v_mfma_f32_16x16x32_bf16 v[52:55], v[166:169], v[194:197], v[52:55]
	v_mfma_f32_16x16x32_bf16 v[44:47], v[174:177], v[194:197], v[44:47]
	v_mfma_f32_16x16x32_bf16 v[36:39], v[166:169], v[202:205], v[36:39]
	v_mfma_f32_16x16x32_bf16 v[28:31], v[174:177], v[202:205], v[28:31]
	v_mfma_f32_16x16x32_bf16 v[20:23], v[166:169], v[210:213], v[20:23]
	v_mfma_f32_16x16x32_bf16 v[12:15], v[174:177], v[210:213], v[12:15]
	v_mfma_f32_16x16x32_bf16 v[4:7], v[166:169], v[218:221], v[4:7]
	v_mfma_f32_16x16x32_bf16 v[0:3], v[174:177], v[218:221], v[0:3]
	s_setprio 0
	s_barrier
	s_add_i32 s85, s85, 2
	s_add_u32 s60, s60, 0x100
	s_addc_u32 s61, s61, 0
	s_add_u32 s16, s16, 0x100
	s_addc_u32 s17, s17, 0
	s_cmp_gt_u32 s85, 13

.LBB0_259:
	s_lshl_b32 s14, s44, 8
	s_ashr_i32 s15, s14, 31
	v_lshl_add_u64 v[0:1], s[14:15], 2, v[132:133]
	s_waitcnt lgkmcnt(0)
	global_load_dword v136, v[0:1], off
	s_andn2_b64 vcc, exec, s[12:13]
	s_cbranch_vccnz .LBB0_244
	s_mov_b32 s98, 1
	s_branch .LBB0_244

.LBB0_316:
	s_add_u32 s50, s16, 0x58080
	s_addc_u32 s51, s17, 0
	s_add_u32 s70, s14, 0x100
	s_addc_u32 s84, s15, 0
	s_mov_b32 s85, -2
	s_waitcnt lgkmcnt(0)
	s_mov_b64 vcc, 0x2c000
	s_mov_b64 s[82:83], 0x84000
	s_mov_b64 s[80:81], 0x2c080
	s_mov_b64 s[74:75], 0x58080
	s_mov_b64 s[62:63], 0x84080
	s_cmp_eq_u32 s98, 1
	s_cbranch_scc0 .Lnostb3
	s_mov_b32 s98, 0
	s_barrier
.Lnostb3:
	s_add_u32 s14, s50, 0xfffa8080
	s_addc_u32 s15, s51, -1
	s_add_i32 s22, 0, 0x10000
	s_cmp_eq_u32 s85, 18
	s_cselect_b32 s15, s1, s15
	s_cselect_b32 s14, s0, s14
	s_cselect_b32 s17, s49, s84
	s_cselect_b32 s16, s48, s70
	s_add_i32 s23, 0, 0x14000
	v_add_u32_e32 v0, s22, v221
	v_add_u32_e32 v4, s23, v221
	ds_read_b128 v[24:27], v0
	ds_read_b128 v[28:31], v0 offset:1024
	ds_read_b128 v[16:19], v0 offset:2048
	ds_read_b128 v[20:23], v0 offset:3072
	ds_read_b128 v[8:11], v4
	ds_read_b128 v[12:15], v4 offset:1024
	ds_read_b128 v[0:3], v4 offset:2048
	ds_read_b128 v[4:7], v4 offset:3072
	v_lshl_add_u64 v[206:207], s[50:51], 0, v[196:197]
	s_add_i32 m0, s19, 0xc000
	ds_read_b128 v[160:163], v223
	ds_read_b128 v[164:167], v223 offset:1024
	ds_read_b128 v[168:171], v223 offset:2048
	ds_read_b128 v[172:175], v223 offset:3072
	ds_read_b128 v[176:179], v223 offset:4096
	ds_read_b128 v[180:183], v223 offset:5120
	ds_read_b128 v[198:201], v223 offset:6144
	ds_read_b128 v[202:205], v223 offset:7168
	global_load_lds_dwordx4 v[206:207], off
	v_lshl_add_u64 v[206:207], v[206:207], 0, vcc
	s_add_i32 m0, s19, 0xe000
	s_nop 0
	global_load_lds_dwordx4 v[206:207], off
	s_waitcnt vmcnt(8)
	s_waitcnt lgkmcnt(0)
	s_barrier
	s_setprio 1
	s_waitcnt lgkmcnt(0)
	v_mfma_scale_f32_16x16x128_f8f6f4 v[156:159], v[24:31], v[160:167], 0, v240, v240 op_sel_hi:[0,0,0]
	v_mfma_scale_f32_16x16x128_f8f6f4 v[152:155], v[16:23], v[160:167], 0, v240, v240 op_sel_hi:[0,0,0]
	v_mfma_scale_f32_16x16x128_f8f6f4 v[140:143], v[24:31], v[168:175], 0, v240, v240 op_sel_hi:[0,0,0]
	v_mfma_scale_f32_16x16x128_f8f6f4 v[136:139], v[16:23], v[168:175], 0, v240, v240 op_sel_hi:[0,0,0]
	v_mfma_scale_f32_16x16x128_f8f6f4 v[124:127], v[24:31], v[176:183], 0, v240, v240 op_sel_hi:[0,0,0]
	v_mfma_scale_f32_16x16x128_f8f6f4 v[120:123], v[16:23], v[176:183], 0, v240, v240 op_sel_hi:[0,0,0]
	v_mfma_scale_f32_16x16x128_f8f6f4 v[108:111], v[24:31], v[198:205], 0, v240, v240 op_sel_hi:[0,0,0]
	v_mfma_scale_f32_16x16x128_f8f6f4 v[104:107], v[16:23], v[198:205], 0, v240, v240 op_sel_hi:[0,0,0]
	s_setprio 0
	s_setprio 1
	v_mfma_scale_f32_16x16x128_f8f6f4 v[148:151], v[8:15], v[160:167], 0, v240, v240 op_sel_hi:[0,0,0]
	v_mfma_scale_f32_16x16x128_f8f6f4 v[144:147], v[0:7], v[160:167], 0, v240, v240 op_sel_hi:[0,0,0]
	v_mfma_scale_f32_16x16x128_f8f6f4 v[132:135], v[8:15], v[168:175], 0, v240, v240 op_sel_hi:[0,0,0]
	v_mfma_scale_f32_16x16x128_f8f6f4 v[128:131], v[0:7], v[168:175], 0, v240, v240 op_sel_hi:[0,0,0]
	v_mfma_scale_f32_16x16x128_f8f6f4 v[116:119], v[8:15], v[176:183], 0, v240, v240 op_sel_hi:[0,0,0]
	v_mfma_scale_f32_16x16x128_f8f6f4 v[112:115], v[0:7], v[176:183], 0, v240, v240 op_sel_hi:[0,0,0]
	v_mfma_scale_f32_16x16x128_f8f6f4 v[100:103], v[8:15], v[198:205], 0, v240, v240 op_sel_hi:[0,0,0]
	v_mfma_scale_f32_16x16x128_f8f6f4 v[96:99], v[0:7], v[198:205], 0, v240, v240 op_sel_hi:[0,0,0]
	s_setprio 0
	s_barrier
	v_lshl_add_u64 v[160:161], s[16:17], 0, v[184:185]
	s_add_i32 s16, s22, s6
	s_mov_b32 m0, s16
	ds_read_b128 v[164:167], v223 offset:16384
	ds_read_b128 v[168:171], v223 offset:17408
	ds_read_b128 v[172:175], v223 offset:18432
	ds_read_b128 v[176:179], v223 offset:19456
	ds_read_b128 v[198:201], v223 offset:20480
	ds_read_b128 v[202:205], v223 offset:21504
	ds_read_b128 v[206:209], v223 offset:22528
	ds_read_b128 v[210:213], v223 offset:23552
	global_load_lds_dwordx4 v[160:161], off
	v_lshl_add_u64 v[162:163], v[160:161], 0, vcc
	s_add_i32 m0, s16, 0x2000
	s_add_i32 s16, s23, s6
	global_load_lds_dwordx4 v[162:163], off
	v_lshl_add_u64 v[162:163], v[160:161], 0, s[2:3]
	s_mov_b32 m0, s16
	s_nop 0
	global_load_lds_dwordx4 v[162:163], off
	v_lshl_add_u64 v[162:163], v[160:161], 0, s[82:83]
	s_add_i32 m0, s16, 0x2000
	s_nop 0
	global_load_lds_dwordx4 v[162:163], off
	v_lshl_add_u64 v[162:163], s[14:15], 0, v[194:195]
	s_mov_b32 m0, s19
	v_lshl_add_u64 v[180:181], v[162:163], 0, vcc
	global_load_lds_dwordx4 v[162:163], off
	s_mov_b32 m0, s20
	s_nop 0
	global_load_lds_dwordx4 v[180:181], off
	s_waitcnt vmcnt(8)
	s_waitcnt lgkmcnt(0)
	s_barrier
	s_setprio 1
	s_waitcnt lgkmcnt(0)
	v_mfma_scale_f32_16x16x128_f8f6f4 v[92:95], v[24:31], v[164:171], 0, v240, v240 op_sel_hi:[0,0,0]
	v_mfma_scale_f32_16x16x128_f8f6f4 v[88:91], v[16:23], v[164:171], 0, v240, v240 op_sel_hi:[0,0,0]
	v_mfma_scale_f32_16x16x128_f8f6f4 v[76:79], v[24:31], v[172:179], 0, v240, v240 op_sel_hi:[0,0,0]
	v_mfma_scale_f32_16x16x128_f8f6f4 v[72:75], v[16:23], v[172:179], 0, v240, v240 op_sel_hi:[0,0,0]
	v_mfma_scale_f32_16x16x128_f8f6f4 v[60:63], v[24:31], v[198:205], 0, v240, v240 op_sel_hi:[0,0,0]
	v_mfma_scale_f32_16x16x128_f8f6f4 v[56:59], v[16:23], v[198:205], 0, v240, v240 op_sel_hi:[0,0,0]
	v_mfma_scale_f32_16x16x128_f8f6f4 v[44:47], v[24:31], v[206:213], 0, v240, v240 op_sel_hi:[0,0,0]
	v_mfma_scale_f32_16x16x128_f8f6f4 v[40:43], v[16:23], v[206:213], 0, v240, v240 op_sel_hi:[0,0,0]
	s_setprio 0
	s_setprio 1
	v_mfma_scale_f32_16x16x128_f8f6f4 v[84:87], v[8:15], v[164:171], 0, v240, v240 op_sel_hi:[0,0,0]
	v_mfma_scale_f32_16x16x128_f8f6f4 v[80:83], v[0:7], v[164:171], 0, v240, v240 op_sel_hi:[0,0,0]
	v_mfma_scale_f32_16x16x128_f8f6f4 v[68:71], v[8:15], v[172:179], 0, v240, v240 op_sel_hi:[0,0,0]
	v_mfma_scale_f32_16x16x128_f8f6f4 v[64:67], v[0:7], v[172:179], 0, v240, v240 op_sel_hi:[0,0,0]
	v_mfma_scale_f32_16x16x128_f8f6f4 v[52:55], v[8:15], v[198:205], 0, v240, v240 op_sel_hi:[0,0,0]
	v_mfma_scale_f32_16x16x128_f8f6f4 v[48:51], v[0:7], v[198:205], 0, v240, v240 op_sel_hi:[0,0,0]
	v_mfma_scale_f32_16x16x128_f8f6f4 v[36:39], v[8:15], v[206:213], 0, v240, v240 op_sel_hi:[0,0,0]
	v_mfma_scale_f32_16x16x128_f8f6f4 v[32:35], v[0:7], v[206:213], 0, v240, v240 op_sel_hi:[0,0,0]
	s_setprio 0
	s_barrier
	s_add_i32 s14, 0, 0x18000
	s_add_i32 s15, 0, 0x1c000
	v_add_u32_e32 v12, s14, v221
	v_add_u32_e32 v28, s15, v221
	ds_read_b128 v[0:3], v12
	ds_read_b128 v[4:7], v12 offset:1024
	ds_read_b128 v[8:11], v12 offset:2048
	ds_read_b128 v[12:15], v12 offset:3072
	ds_read_b128 v[16:19], v28
	ds_read_b128 v[20:23], v28 offset:1024
	ds_read_b128 v[24:27], v28 offset:2048
	ds_read_b128 v[28:31], v28 offset:3072
	s_mov_b32 m0, s25
	v_lshl_add_u64 v[180:181], v[162:163], 0, s[2:3]
	ds_read_b128 v[164:167], v223 offset:32768
	ds_read_b128 v[168:171], v223 offset:33792
	ds_read_b128 v[172:175], v223 offset:34816
	ds_read_b128 v[176:179], v223 offset:35840
	ds_read_b128 v[198:201], v223 offset:36864
	ds_read_b128 v[202:205], v223 offset:37888
	ds_read_b128 v[206:209], v223 offset:38912
	ds_read_b128 v[210:213], v223 offset:39936
	global_load_lds_dwordx4 v[180:181], off
	v_lshl_add_u64 v[180:181], v[162:163], 0, s[82:83]
	s_mov_b32 m0, s26
	s_nop 0
	global_load_lds_dwordx4 v[180:181], off
	s_waitcnt vmcnt(8)
	s_waitcnt lgkmcnt(0)
	s_barrier
	s_setprio 1
	s_waitcnt lgkmcnt(0)
	v_mfma_scale_f32_16x16x128_f8f6f4 v[156:159], v[0:7], v[164:171], v[156:159], v240, v240 op_sel_hi:[0,0,0]
	v_mfma_scale_f32_16x16x128_f8f6f4 v[152:155], v[8:15], v[164:171], v[152:155], v240, v240 op_sel_hi:[0,0,0]
	v_mfma_scale_f32_16x16x128_f8f6f4 v[140:143], v[0:7], v[172:179], v[140:143], v240, v240 op_sel_hi:[0,0,0]
	v_mfma_scale_f32_16x16x128_f8f6f4 v[136:139], v[8:15], v[172:179], v[136:139], v240, v240 op_sel_hi:[0,0,0]
	v_mfma_scale_f32_16x16x128_f8f6f4 v[124:127], v[0:7], v[198:205], v[124:127], v240, v240 op_sel_hi:[0,0,0]
	v_mfma_scale_f32_16x16x128_f8f6f4 v[120:123], v[8:15], v[198:205], v[120:123], v240, v240 op_sel_hi:[0,0,0]
	v_mfma_scale_f32_16x16x128_f8f6f4 v[108:111], v[0:7], v[206:213], v[108:111], v240, v240 op_sel_hi:[0,0,0]
	v_mfma_scale_f32_16x16x128_f8f6f4 v[104:107], v[8:15], v[206:213], v[104:107], v240, v240 op_sel_hi:[0,0,0]
	s_setprio 0
	s_setprio 1
	v_mfma_scale_f32_16x16x128_f8f6f4 v[148:151], v[16:23], v[164:171], v[148:151], v240, v240 op_sel_hi:[0,0,0]
	v_mfma_scale_f32_16x16x128_f8f6f4 v[144:147], v[24:31], v[164:171], v[144:147], v240, v240 op_sel_hi:[0,0,0]
	v_mfma_scale_f32_16x16x128_f8f6f4 v[132:135], v[16:23], v[172:179], v[132:135], v240, v240 op_sel_hi:[0,0,0]
	v_mfma_scale_f32_16x16x128_f8f6f4 v[128:131], v[24:31], v[172:179], v[128:131], v240, v240 op_sel_hi:[0,0,0]
	v_mfma_scale_f32_16x16x128_f8f6f4 v[116:119], v[16:23], v[198:205], v[116:119], v240, v240 op_sel_hi:[0,0,0]
	v_mfma_scale_f32_16x16x128_f8f6f4 v[112:115], v[24:31], v[198:205], v[112:115], v240, v240 op_sel_hi:[0,0,0]
	v_mfma_scale_f32_16x16x128_f8f6f4 v[100:103], v[16:23], v[206:213], v[100:103], v240, v240 op_sel_hi:[0,0,0]
	v_mfma_scale_f32_16x16x128_f8f6f4 v[96:99], v[24:31], v[206:213], v[96:99], v240, v240 op_sel_hi:[0,0,0]
	s_setprio 0
	s_barrier
	s_add_i32 s14, s14, s6
	v_lshl_add_u64 v[180:181], v[160:161], 0, s[56:57]
	s_mov_b32 m0, s14
	ds_read_b128 v[164:167], v223 offset:49152
	ds_read_b128 v[168:171], v223 offset:50176
	ds_read_b128 v[172:175], v223 offset:51200
	ds_read_b128 v[176:179], v223 offset:52224
	ds_read_b128 v[198:201], v223 offset:53248
	ds_read_b128 v[202:205], v223 offset:54272
	ds_read_b128 v[206:209], v223 offset:55296
	ds_read_b128 v[210:213], v223 offset:56320
	global_load_lds_dwordx4 v[180:181], off
	v_lshl_add_u64 v[180:181], v[160:161], 0, s[80:81]
	s_add_i32 m0, s14, 0x2000
	s_add_i32 s14, s15, s6
	global_load_lds_dwordx4 v[180:181], off
	v_lshl_add_u64 v[180:181], v[160:161], 0, s[74:75]
	s_mov_b32 m0, s14
	v_lshl_add_u64 v[160:161], v[160:161], 0, s[62:63]
	global_load_lds_dwordx4 v[180:181], off
	s_add_i32 m0, s14, 0x2000
	s_nop 0
	global_load_lds_dwordx4 v[160:161], off
	v_lshl_add_u64 v[160:161], v[162:163], 0, s[56:57]
	s_mov_b32 m0, s28
	s_nop 0
	global_load_lds_dwordx4 v[160:161], off
	v_lshl_add_u64 v[160:161], v[162:163], 0, s[80:81]
	s_mov_b32 m0, s29
	s_nop 0
	global_load_lds_dwordx4 v[160:161], off
	s_waitcnt vmcnt(8)
	s_waitcnt lgkmcnt(0)
	s_barrier
	s_setprio 1
	s_waitcnt lgkmcnt(0)
	v_mfma_scale_f32_16x16x128_f8f6f4 v[92:95], v[0:7], v[164:171], v[92:95], v240, v240 op_sel_hi:[0,0,0]
	v_mfma_scale_f32_16x16x128_f8f6f4 v[88:91], v[8:15], v[164:171], v[88:91], v240, v240 op_sel_hi:[0,0,0]
	v_mfma_scale_f32_16x16x128_f8f6f4 v[76:79], v[0:7], v[172:179], v[76:79], v240, v240 op_sel_hi:[0,0,0]
	v_mfma_scale_f32_16x16x128_f8f6f4 v[72:75], v[8:15], v[172:179], v[72:75], v240, v240 op_sel_hi:[0,0,0]
	v_mfma_scale_f32_16x16x128_f8f6f4 v[60:63], v[0:7], v[198:205], v[60:63], v240, v240 op_sel_hi:[0,0,0]
	v_mfma_scale_f32_16x16x128_f8f6f4 v[56:59], v[8:15], v[198:205], v[56:59], v240, v240 op_sel_hi:[0,0,0]
	v_mfma_scale_f32_16x16x128_f8f6f4 v[44:47], v[0:7], v[206:213], v[44:47], v240, v240 op_sel_hi:[0,0,0]
	v_mfma_scale_f32_16x16x128_f8f6f4 v[40:43], v[8:15], v[206:213], v[40:43], v240, v240 op_sel_hi:[0,0,0]
	s_setprio 0
	s_setprio 1
	v_mfma_scale_f32_16x16x128_f8f6f4 v[84:87], v[16:23], v[164:171], v[84:87], v240, v240 op_sel_hi:[0,0,0]
	v_mfma_scale_f32_16x16x128_f8f6f4 v[80:83], v[24:31], v[164:171], v[80:83], v240, v240 op_sel_hi:[0,0,0]
	v_mfma_scale_f32_16x16x128_f8f6f4 v[68:71], v[16:23], v[172:179], v[68:71], v240, v240 op_sel_hi:[0,0,0]
	v_mfma_scale_f32_16x16x128_f8f6f4 v[64:67], v[24:31], v[172:179], v[64:67], v240, v240 op_sel_hi:[0,0,0]
	v_mfma_scale_f32_16x16x128_f8f6f4 v[52:55], v[16:23], v[198:205], v[52:55], v240, v240 op_sel_hi:[0,0,0]
	v_mfma_scale_f32_16x16x128_f8f6f4 v[48:51], v[24:31], v[198:205], v[48:51], v240, v240 op_sel_hi:[0,0,0]
	v_mfma_scale_f32_16x16x128_f8f6f4 v[36:39], v[16:23], v[206:213], v[36:39], v240, v240 op_sel_hi:[0,0,0]
	v_mfma_scale_f32_16x16x128_f8f6f4 v[32:35], v[24:31], v[206:213], v[32:35], v240, v240 op_sel_hi:[0,0,0]
	s_setprio 0
	s_barrier
	s_add_i32 s85, s85, 2
	s_add_u32 s50, s50, 0x100
	s_addc_u32 s51, s51, 0
	s_add_u32 s70, s70, 0x100
	s_addc_u32 s84, s84, 0
	s_cmp_gt_u32 s85, 19

.LBB0_336:
	s_or_b64 exec, exec, s[14:15]
	s_and_b64 vcc, exec, s[38:39]
	s_mov_b64 s[14:15], -1
	s_cbranch_vccnz .LBB0_305
	s_andn2_b64 vcc, exec, s[42:43]
	s_cbranch_vccnz .LBB0_304
	s_mov_b32 s98, 1
	s_branch .LBB0_304

.LBB0_361:
	s_add_u32 vcc_lo, s16, 0x80
	s_addc_u32 vcc_hi, s17, 0
	s_add_u32 s16, s14, 0x100
	s_addc_u32 s17, s15, 0
	s_mov_b32 s14, 0
	s_cmp_eq_u32 s98, 1
	s_cbranch_scc0 .Lnostb4
	s_mov_b32 s98, 0
	s_barrier
.Lnostb4:
	s_add_i32 s24, s14, 2
	s_add_u32 s46, vcc_lo, 0x80
	s_addc_u32 s15, vcc_hi, 0
	s_add_i32 s18, 0, 0x10000
	s_cmp_eq_u32 s6, s14
	s_cselect_b32 s15, s1, s15
	s_cselect_b32 s14, s0, s46
	s_cselect_b32 s47, s13, s17
	s_cselect_b32 s46, s12, s16
	s_add_i32 s21, 0, 0x14000
	v_add_u32_e32 v140, s18, v223
	v_add_u32_e32 v156, s21, v223
	s_waitcnt lgkmcnt(0)
	ds_read_b128 v[128:131], v140
	ds_read_b128 v[132:135], v140 offset:1024
	ds_read_b128 v[136:139], v140 offset:2048
	ds_read_b128 v[140:143], v140 offset:3072
	ds_read_b128 v[144:147], v156
	ds_read_b128 v[148:151], v156 offset:1024
	ds_read_b128 v[152:155], v156 offset:2048
	ds_read_b128 v[156:159], v156 offset:3072
	v_lshl_add_u64 v[186:187], vcc, 0, v[196:197]
	s_add_i32 m0, s28, 0xc000
	ds_read_b128 v[160:163], v225
	ds_read_b128 v[164:167], v225 offset:1024
	ds_read_b128 v[168:171], v225 offset:2048
	ds_read_b128 v[172:175], v225 offset:3072
	ds_read_b128 v[176:179], v225 offset:4096
	ds_read_b128 v[180:183], v225 offset:5120
	ds_read_b128 v[200:203], v225 offset:6144
	ds_read_b128 v[204:207], v225 offset:7168
	global_load_lds_dwordx4 v[186:187], off
	v_lshl_add_u64 v[186:187], vcc, 0, v[198:199]
	s_add_i32 m0, s28, 0xe000
	s_nop 0
	global_load_lds_dwordx4 v[186:187], off
	s_waitcnt vmcnt(8)
	s_waitcnt lgkmcnt(0)
	s_barrier
	s_setprio 1
	s_waitcnt lgkmcnt(0)
	v_mfma_f32_16x16x32_bf16 v[124:127], v[128:131], v[160:163], 0
	v_mfma_f32_16x16x32_bf16 v[120:123], v[136:139], v[160:163], 0
	v_mfma_f32_16x16x32_bf16 v[108:111], v[128:131], v[168:171], 0
	v_mfma_f32_16x16x32_bf16 v[104:107], v[136:139], v[168:171], 0
	v_mfma_f32_16x16x32_bf16 v[92:95], v[128:131], v[176:179], 0
	v_mfma_f32_16x16x32_bf16 v[88:91], v[136:139], v[176:179], 0
	v_mfma_f32_16x16x32_bf16 v[76:79], v[128:131], v[200:203], 0
	v_mfma_f32_16x16x32_bf16 v[72:75], v[136:139], v[200:203], 0
	v_mfma_f32_16x16x32_bf16 v[124:127], v[132:135], v[164:167], v[124:127]
	v_mfma_f32_16x16x32_bf16 v[120:123], v[140:143], v[164:167], v[120:123]
	v_mfma_f32_16x16x32_bf16 v[108:111], v[132:135], v[172:175], v[108:111]
	v_mfma_f32_16x16x32_bf16 v[104:107], v[140:143], v[172:175], v[104:107]
	v_mfma_f32_16x16x32_bf16 v[92:95], v[132:135], v[180:183], v[92:95]
	v_mfma_f32_16x16x32_bf16 v[88:91], v[140:143], v[180:183], v[88:91]
	v_mfma_f32_16x16x32_bf16 v[76:79], v[132:135], v[204:207], v[76:79]
	v_mfma_f32_16x16x32_bf16 v[72:75], v[140:143], v[204:207], v[72:75]
	s_setprio 0
	s_setprio 1
	v_mfma_f32_16x16x32_bf16 v[116:119], v[144:147], v[160:163], 0
	v_mfma_f32_16x16x32_bf16 v[112:115], v[152:155], v[160:163], 0
	v_mfma_f32_16x16x32_bf16 v[100:103], v[144:147], v[168:171], 0
	v_mfma_f32_16x16x32_bf16 v[96:99], v[152:155], v[168:171], 0
	v_mfma_f32_16x16x32_bf16 v[84:87], v[144:147], v[176:179], 0
	v_mfma_f32_16x16x32_bf16 v[80:83], v[152:155], v[176:179], 0
	v_mfma_f32_16x16x32_bf16 v[68:71], v[144:147], v[200:203], 0
	v_mfma_f32_16x16x32_bf16 v[64:67], v[152:155], v[200:203], 0
	v_mfma_f32_16x16x32_bf16 v[116:119], v[148:151], v[164:167], v[116:119]
	v_mfma_f32_16x16x32_bf16 v[112:115], v[156:159], v[164:167], v[112:115]
	v_mfma_f32_16x16x32_bf16 v[100:103], v[148:151], v[172:175], v[100:103]
	v_mfma_f32_16x16x32_bf16 v[96:99], v[156:159], v[172:175], v[96:99]
	v_mfma_f32_16x16x32_bf16 v[84:87], v[148:151], v[180:183], v[84:87]
	v_mfma_f32_16x16x32_bf16 v[80:83], v[156:159], v[180:183], v[80:83]
	v_mfma_f32_16x16x32_bf16 v[68:71], v[148:151], v[204:207], v[68:71]
	v_mfma_f32_16x16x32_bf16 v[64:67], v[156:159], v[204:207], v[64:67]
	s_setprio 0
	s_barrier
	s_add_i32 s18, s18, s27
	v_lshl_add_u64 v[186:187], s[46:47], 0, v[184:185]
	s_mov_b32 m0, s18
	ds_read_b128 v[160:163], v225 offset:16384
	ds_read_b128 v[164:167], v225 offset:17408
	ds_read_b128 v[168:171], v225 offset:18432
	ds_read_b128 v[172:175], v225 offset:19456
	ds_read_b128 v[176:179], v225 offset:20480
	ds_read_b128 v[180:183], v225 offset:21504
	ds_read_b128 v[200:203], v225 offset:22528
	ds_read_b128 v[204:207], v225 offset:23552
	global_load_lds_dwordx4 v[186:187], off
	s_add_i32 m0, s18, 0x2000
	s_add_u32 s46, s46, s44
	v_lshl_add_u64 v[188:189], v[186:187], 0, s[70:71]
	s_addc_u32 s47, s47, 0
	s_add_i32 s18, s21, s27
	global_load_lds_dwordx4 v[188:189], off
	v_lshl_add_u64 v[208:209], s[46:47], 0, v[184:185]
	s_mov_b32 m0, s18
	v_lshl_add_u64 v[210:211], v[208:209], 0, s[70:71]
	global_load_lds_dwordx4 v[208:209], off
	s_add_i32 m0, s18, 0x2000
	v_lshl_add_u64 v[212:213], s[14:15], 0, v[194:195]
	global_load_lds_dwordx4 v[210:211], off
	s_mov_b32 m0, s28
	v_lshl_add_u64 v[214:215], v[212:213], 0, s[70:71]
	global_load_lds_dwordx4 v[212:213], off
	s_mov_b32 m0, s29
	s_nop 0
	global_load_lds_dwordx4 v[214:215], off
	s_waitcnt vmcnt(8)
	s_waitcnt lgkmcnt(0)
	s_barrier
	s_setprio 1
	s_waitcnt lgkmcnt(0)
	v_mfma_f32_16x16x32_bf16 v[60:63], v[128:131], v[160:163], 0
	v_mfma_f32_16x16x32_bf16 v[56:59], v[136:139], v[160:163], 0
	v_mfma_f32_16x16x32_bf16 v[44:47], v[128:131], v[168:171], 0
	v_mfma_f32_16x16x32_bf16 v[40:43], v[136:139], v[168:171], 0
	v_mfma_f32_16x16x32_bf16 v[28:31], v[128:131], v[176:179], 0
	v_mfma_f32_16x16x32_bf16 v[24:27], v[136:139], v[176:179], 0
	v_mfma_f32_16x16x32_bf16 v[12:15], v[128:131], v[200:203], 0
	v_mfma_f32_16x16x32_bf16 v[8:11], v[136:139], v[200:203], 0
	v_mfma_f32_16x16x32_bf16 v[60:63], v[132:135], v[164:167], v[60:63]
	v_mfma_f32_16x16x32_bf16 v[56:59], v[140:143], v[164:167], v[56:59]
	v_mfma_f32_16x16x32_bf16 v[44:47], v[132:135], v[172:175], v[44:47]
	v_mfma_f32_16x16x32_bf16 v[40:43], v[140:143], v[172:175], v[40:43]
	v_mfma_f32_16x16x32_bf16 v[28:31], v[132:135], v[180:183], v[28:31]
	v_mfma_f32_16x16x32_bf16 v[24:27], v[140:143], v[180:183], v[24:27]
	v_mfma_f32_16x16x32_bf16 v[12:15], v[132:135], v[204:207], v[12:15]
	v_mfma_f32_16x16x32_bf16 v[8:11], v[140:143], v[204:207], v[8:11]
	s_setprio 0
	s_setprio 1
	v_mfma_f32_16x16x32_bf16 v[52:55], v[144:147], v[160:163], 0
	v_mfma_f32_16x16x32_bf16 v[48:51], v[152:155], v[160:163], 0
	v_mfma_f32_16x16x32_bf16 v[36:39], v[144:147], v[168:171], 0
	v_mfma_f32_16x16x32_bf16 v[32:35], v[152:155], v[168:171], 0
	v_mfma_f32_16x16x32_bf16 v[20:23], v[144:147], v[176:179], 0
	v_mfma_f32_16x16x32_bf16 v[16:19], v[152:155], v[176:179], 0
	v_mfma_f32_16x16x32_bf16 v[4:7], v[144:147], v[200:203], 0
	v_mfma_f32_16x16x32_bf16 v[0:3], v[152:155], v[200:203], 0
	v_mfma_f32_16x16x32_bf16 v[52:55], v[148:151], v[164:167], v[52:55]
	v_mfma_f32_16x16x32_bf16 v[48:51], v[156:159], v[164:167], v[48:51]
	v_mfma_f32_16x16x32_bf16 v[36:39], v[148:151], v[172:175], v[36:39]
	v_mfma_f32_16x16x32_bf16 v[32:35], v[156:159], v[172:175], v[32:35]
	v_mfma_f32_16x16x32_bf16 v[20:23], v[148:151], v[180:183], v[20:23]
	v_mfma_f32_16x16x32_bf16 v[16:19], v[156:159], v[180:183], v[16:19]
	v_mfma_f32_16x16x32_bf16 v[4:7], v[148:151], v[204:207], v[4:7]
	v_mfma_f32_16x16x32_bf16 v[0:3], v[156:159], v[204:207], v[0:3]
	s_setprio 0
	s_barrier
	s_add_i32 s18, 0, 0x18000
	s_add_i32 s21, 0, 0x1c000
	v_add_u32_e32 v140, s18, v223
	v_add_u32_e32 v156, s21, v223
	ds_read_b128 v[128:131], v140
	ds_read_b128 v[132:135], v140 offset:1024
	ds_read_b128 v[136:139], v140 offset:2048
	ds_read_b128 v[140:143], v140 offset:3072
	ds_read_b128 v[144:147], v156
	ds_read_b128 v[148:151], v156 offset:1024
	ds_read_b128 v[152:155], v156 offset:2048
	ds_read_b128 v[156:159], v156 offset:3072
	s_add_u32 s14, s14, s44
	s_addc_u32 s15, s15, 0
	s_mov_b32 m0, s30
	v_lshl_add_u64 v[216:217], s[14:15], 0, v[194:195]
	ds_read_b128 v[160:163], v225 offset:32768
	ds_read_b128 v[164:167], v225 offset:33792
	ds_read_b128 v[168:171], v225 offset:34816
	ds_read_b128 v[172:175], v225 offset:35840
	ds_read_b128 v[176:179], v225 offset:36864
	ds_read_b128 v[180:183], v225 offset:37888
	ds_read_b128 v[200:203], v225 offset:38912
	ds_read_b128 v[204:207], v225 offset:39936
	global_load_lds_dwordx4 v[216:217], off
	v_lshl_add_u64 v[216:217], v[216:217], 0, s[70:71]
	s_mov_b32 m0, s31
	s_nop 0
	global_load_lds_dwordx4 v[216:217], off
	s_waitcnt vmcnt(8)
	s_waitcnt lgkmcnt(0)
	s_barrier
	s_setprio 1
	s_waitcnt lgkmcnt(0)
	v_mfma_f32_16x16x32_bf16 v[124:127], v[128:131], v[160:163], v[124:127]
	v_mfma_f32_16x16x32_bf16 v[120:123], v[136:139], v[160:163], v[120:123]
	v_mfma_f32_16x16x32_bf16 v[108:111], v[128:131], v[168:171], v[108:111]
	v_mfma_f32_16x16x32_bf16 v[104:107], v[136:139], v[168:171], v[104:107]
	v_mfma_f32_16x16x32_bf16 v[92:95], v[128:131], v[176:179], v[92:95]
	v_mfma_f32_16x16x32_bf16 v[88:91], v[136:139], v[176:179], v[88:91]
	v_mfma_f32_16x16x32_bf16 v[76:79], v[128:131], v[200:203], v[76:79]
	v_mfma_f32_16x16x32_bf16 v[72:75], v[136:139], v[200:203], v[72:75]
	v_mfma_f32_16x16x32_bf16 v[124:127], v[132:135], v[164:167], v[124:127]
	v_mfma_f32_16x16x32_bf16 v[120:123], v[140:143], v[164:167], v[120:123]
	v_mfma_f32_16x16x32_bf16 v[108:111], v[132:135], v[172:175], v[108:111]
	v_mfma_f32_16x16x32_bf16 v[104:107], v[140:143], v[172:175], v[104:107]
	v_mfma_f32_16x16x32_bf16 v[92:95], v[132:135], v[180:183], v[92:95]
	v_mfma_f32_16x16x32_bf16 v[88:91], v[140:143], v[180:183], v[88:91]
	v_mfma_f32_16x16x32_bf16 v[76:79], v[132:135], v[204:207], v[76:79]
	v_mfma_f32_16x16x32_bf16 v[72:75], v[140:143], v[204:207], v[72:75]
	s_setprio 0
	s_setprio 1
	v_mfma_f32_16x16x32_bf16 v[116:119], v[144:147], v[160:163], v[116:119]
	v_mfma_f32_16x16x32_bf16 v[112:115], v[152:155], v[160:163], v[112:115]
	v_mfma_f32_16x16x32_bf16 v[100:103], v[144:147], v[168:171], v[100:103]
	v_mfma_f32_16x16x32_bf16 v[96:99], v[152:155], v[168:171], v[96:99]
	v_mfma_f32_16x16x32_bf16 v[84:87], v[144:147], v[176:179], v[84:87]
	v_mfma_f32_16x16x32_bf16 v[80:83], v[152:155], v[176:179], v[80:83]
	v_mfma_f32_16x16x32_bf16 v[68:71], v[144:147], v[200:203], v[68:71]
	v_mfma_f32_16x16x32_bf16 v[64:67], v[152:155], v[200:203], v[64:67]
	v_mfma_f32_16x16x32_bf16 v[116:119], v[148:151], v[164:167], v[116:119]
	v_mfma_f32_16x16x32_bf16 v[112:115], v[156:159], v[164:167], v[112:115]
	v_mfma_f32_16x16x32_bf16 v[100:103], v[148:151], v[172:175], v[100:103]
	v_mfma_f32_16x16x32_bf16 v[96:99], v[156:159], v[172:175], v[96:99]
	v_mfma_f32_16x16x32_bf16 v[84:87], v[148:151], v[180:183], v[84:87]
	v_mfma_f32_16x16x32_bf16 v[80:83], v[156:159], v[180:183], v[80:83]
	v_mfma_f32_16x16x32_bf16 v[68:71], v[148:151], v[204:207], v[68:71]
	v_mfma_f32_16x16x32_bf16 v[64:67], v[156:159], v[204:207], v[64:67]
	s_setprio 0
	s_barrier
	s_add_i32 s14, s18, s27
	v_lshl_add_u64 v[186:187], v[186:187], 0, s[56:57]
	s_mov_b32 m0, s14
	ds_read_b128 v[160:163], v225 offset:49152
	ds_read_b128 v[164:167], v225 offset:50176
	ds_read_b128 v[168:171], v225 offset:51200
	ds_read_b128 v[172:175], v225 offset:52224
	ds_read_b128 v[176:179], v225 offset:53248
	ds_read_b128 v[180:183], v225 offset:54272
	ds_read_b128 v[200:203], v225 offset:55296
	ds_read_b128 v[204:207], v225 offset:56320
	global_load_lds_dwordx4 v[186:187], off
	v_lshl_add_u64 v[186:187], v[188:189], 0, s[56:57]
	s_add_i32 m0, s14, 0x2000
	s_add_i32 s14, s21, s27
	global_load_lds_dwordx4 v[186:187], off
	v_lshl_add_u64 v[186:187], v[208:209], 0, s[56:57]
	s_mov_b32 m0, s14
	s_nop 0
	global_load_lds_dwordx4 v[186:187], off
	v_lshl_add_u64 v[186:187], v[210:211], 0, s[56:57]
	s_add_i32 m0, s14, 0x2000
	s_nop 0
	global_load_lds_dwordx4 v[186:187], off
	v_lshl_add_u64 v[186:187], v[212:213], 0, s[56:57]
	s_mov_b32 m0, s19
	s_nop 0
	global_load_lds_dwordx4 v[186:187], off
	v_lshl_add_u64 v[186:187], v[214:215], 0, s[56:57]
	s_mov_b32 m0, s20
	s_nop 0
	global_load_lds_dwordx4 v[186:187], off
	s_waitcnt vmcnt(8)
	s_waitcnt lgkmcnt(0)
	s_barrier
	s_setprio 1
	s_waitcnt lgkmcnt(0)
	v_mfma_f32_16x16x32_bf16 v[60:63], v[128:131], v[160:163], v[60:63]
	v_mfma_f32_16x16x32_bf16 v[56:59], v[136:139], v[160:163], v[56:59]
	v_mfma_f32_16x16x32_bf16 v[44:47], v[128:131], v[168:171], v[44:47]
	v_mfma_f32_16x16x32_bf16 v[40:43], v[136:139], v[168:171], v[40:43]
	v_mfma_f32_16x16x32_bf16 v[28:31], v[128:131], v[176:179], v[28:31]
	v_mfma_f32_16x16x32_bf16 v[24:27], v[136:139], v[176:179], v[24:27]
	v_mfma_f32_16x16x32_bf16 v[12:15], v[128:131], v[200:203], v[12:15]
	v_mfma_f32_16x16x32_bf16 v[8:11], v[136:139], v[200:203], v[8:11]
	v_mfma_f32_16x16x32_bf16 v[60:63], v[132:135], v[164:167], v[60:63]
	v_mfma_f32_16x16x32_bf16 v[56:59], v[140:143], v[164:167], v[56:59]
	v_mfma_f32_16x16x32_bf16 v[44:47], v[132:135], v[172:175], v[44:47]
	v_mfma_f32_16x16x32_bf16 v[40:43], v[140:143], v[172:175], v[40:43]
	v_mfma_f32_16x16x32_bf16 v[28:31], v[132:135], v[180:183], v[28:31]
	v_mfma_f32_16x16x32_bf16 v[24:27], v[140:143], v[180:183], v[24:27]
	v_mfma_f32_16x16x32_bf16 v[12:15], v[132:135], v[204:207], v[12:15]
	v_mfma_f32_16x16x32_bf16 v[8:11], v[140:143], v[204:207], v[8:11]
	s_setprio 0
	s_setprio 1
	v_mfma_f32_16x16x32_bf16 v[52:55], v[144:147], v[160:163], v[52:55]
	v_mfma_f32_16x16x32_bf16 v[48:51], v[152:155], v[160:163], v[48:51]
	v_mfma_f32_16x16x32_bf16 v[36:39], v[144:147], v[168:171], v[36:39]
	v_mfma_f32_16x16x32_bf16 v[32:35], v[152:155], v[168:171], v[32:35]
	v_mfma_f32_16x16x32_bf16 v[20:23], v[144:147], v[176:179], v[20:23]
	v_mfma_f32_16x16x32_bf16 v[16:19], v[152:155], v[176:179], v[16:19]
	v_mfma_f32_16x16x32_bf16 v[4:7], v[144:147], v[200:203], v[4:7]
	v_mfma_f32_16x16x32_bf16 v[0:3], v[152:155], v[200:203], v[0:3]
	v_mfma_f32_16x16x32_bf16 v[52:55], v[148:151], v[164:167], v[52:55]
	v_mfma_f32_16x16x32_bf16 v[48:51], v[156:159], v[164:167], v[48:51]
	v_mfma_f32_16x16x32_bf16 v[36:39], v[148:151], v[172:175], v[36:39]
	v_mfma_f32_16x16x32_bf16 v[32:35], v[156:159], v[172:175], v[32:35]
	v_mfma_f32_16x16x32_bf16 v[20:23], v[148:151], v[180:183], v[20:23]
	v_mfma_f32_16x16x32_bf16 v[16:19], v[156:159], v[180:183], v[16:19]
	v_mfma_f32_16x16x32_bf16 v[4:7], v[148:151], v[204:207], v[4:7]
	v_mfma_f32_16x16x32_bf16 v[0:3], v[156:159], v[204:207], v[0:3]
	s_setprio 0
	s_barrier
	s_add_u32 vcc_lo, vcc_lo, 0x100
	s_addc_u32 vcc_hi, vcc_hi, 0
	s_add_u32 s16, s16, 0x100
	s_addc_u32 s17, s17, 0
	s_cmp_ge_u32 s24, s84
	s_mov_b32 s14, s24

.LBB0_400:
	s_andn2_b64 vcc, exec, s[50:51]
	s_cbranch_vccnz .LBB0_349
	s_mov_b32 s98, 1
	s_branch .LBB0_349

.LBB0_421:
	s_add_u32 s44, s16, 0x80
	s_addc_u32 s45, s17, 0
	s_add_u32 s16, s14, 0x100
	s_addc_u32 s17, s15, 0
	s_mov_b32 s14, 0
	s_waitcnt lgkmcnt(0)
	s_cmp_eq_u32 s98, 1
	s_cbranch_scc0 .Lnostb5
	s_mov_b32 s98, 0
	s_barrier
.Lnostb5:
	s_add_i32 s23, s14, 2
	s_add_u32 s24, s44, 0x80
	s_addc_u32 s15, s45, 0
	s_add_i32 s49, 0, 0x10000
	s_cmp_eq_u32 s31, s14
	s_cselect_b32 s15, s1, s15
	s_cselect_b32 s14, s0, s24
	s_cselect_b32 s51, s43, s17
	s_cselect_b32 s50, s42, s16
	s_add_i32 s24, 0, 0x14000
	v_add_u32_e32 v108, s49, v249
	v_add_u32_e32 v140, s24, v249
	ds_read_b128 v[80:83], v108
	ds_read_b128 v[84:87], v108 offset:1024
	ds_read_b128 v[104:107], v108 offset:2048
	ds_read_b128 v[108:111], v108 offset:3072
	ds_read_b128 v[124:127], v140
	ds_read_b128 v[132:135], v140 offset:1024
	ds_read_b128 v[136:139], v140 offset:2048
	ds_read_b128 v[140:143], v140 offset:3072
	v_lshl_add_u64 v[208:209], s[44:45], 0, v[196:197]
	s_add_i32 m0, s20, 0xc000
	ds_read_b128 v[144:147], v251
	ds_read_b128 v[148:151], v251 offset:1024
	ds_read_b128 v[152:155], v251 offset:2048
	ds_read_b128 v[156:159], v251 offset:3072
	ds_read_b128 v[160:163], v251 offset:4096
	ds_read_b128 v[164:167], v251 offset:5120
	ds_read_b128 v[200:203], v251 offset:6144
	ds_read_b128 v[204:207], v251 offset:7168
	global_load_lds_dwordx4 v[208:209], off
	v_lshl_add_u64 v[208:209], s[44:45], 0, v[198:199]
	s_add_i32 m0, s20, 0xe000
	s_nop 0
	global_load_lds_dwordx4 v[208:209], off
	s_waitcnt vmcnt(8)
	s_waitcnt lgkmcnt(0)
	s_barrier
	s_setprio 1
	s_waitcnt lgkmcnt(0)
	v_mfma_f32_16x16x32_bf16 v[180:183], v[80:83], v[144:147], 0
	v_mfma_f32_16x16x32_bf16 v[176:179], v[104:107], v[144:147], 0
	v_mfma_f32_16x16x32_bf16 v[128:131], v[80:83], v[152:155], 0
	v_mfma_f32_16x16x32_bf16 v[120:123], v[104:107], v[152:155], 0
	v_mfma_f32_16x16x32_bf16 v[100:103], v[80:83], v[160:163], 0
	v_mfma_f32_16x16x32_bf16 v[96:99], v[104:107], v[160:163], 0
	v_mfma_f32_16x16x32_bf16 v[76:79], v[80:83], v[200:203], 0
	v_mfma_f32_16x16x32_bf16 v[72:75], v[104:107], v[200:203], 0
	v_mfma_f32_16x16x32_bf16 v[180:183], v[84:87], v[148:151], v[180:183]
	v_mfma_f32_16x16x32_bf16 v[176:179], v[108:111], v[148:151], v[176:179]
	v_mfma_f32_16x16x32_bf16 v[128:131], v[84:87], v[156:159], v[128:131]
	v_mfma_f32_16x16x32_bf16 v[120:123], v[108:111], v[156:159], v[120:123]
	v_mfma_f32_16x16x32_bf16 v[100:103], v[84:87], v[164:167], v[100:103]
	v_mfma_f32_16x16x32_bf16 v[96:99], v[108:111], v[164:167], v[96:99]
	v_mfma_f32_16x16x32_bf16 v[76:79], v[84:87], v[204:207], v[76:79]
	v_mfma_f32_16x16x32_bf16 v[72:75], v[108:111], v[204:207], v[72:75]
	s_setprio 0
	s_setprio 1
	v_mfma_f32_16x16x32_bf16 v[172:175], v[124:127], v[144:147], 0
	v_mfma_f32_16x16x32_bf16 v[116:119], v[124:127], v[152:155], 0
	v_mfma_f32_16x16x32_bf16 v[112:115], v[136:139], v[152:155], 0
	v_mfma_f32_16x16x32_bf16 v[92:95], v[124:127], v[160:163], 0
	v_mfma_f32_16x16x32_bf16 v[88:91], v[136:139], v[160:163], 0
	v_mfma_f32_16x16x32_bf16 v[68:71], v[124:127], v[200:203], 0
	v_mfma_f32_16x16x32_bf16 v[64:67], v[136:139], v[200:203], 0
	v_mfma_f32_16x16x32_bf16 v[172:175], v[132:135], v[148:151], v[172:175]
	v_mfma_f32_16x16x32_bf16 v[144:147], v[136:139], v[144:147], 0
	v_mfma_f32_16x16x32_bf16 v[116:119], v[132:135], v[156:159], v[116:119]
	v_mfma_f32_16x16x32_bf16 v[112:115], v[140:143], v[156:159], v[112:115]
	v_mfma_f32_16x16x32_bf16 v[92:95], v[132:135], v[164:167], v[92:95]
	v_mfma_f32_16x16x32_bf16 v[88:91], v[140:143], v[164:167], v[88:91]
	v_mfma_f32_16x16x32_bf16 v[68:71], v[132:135], v[204:207], v[68:71]
	v_mfma_f32_16x16x32_bf16 v[64:67], v[140:143], v[204:207], v[64:67]
	v_mfma_f32_16x16x32_bf16 v[144:147], v[140:143], v[148:151], v[144:147]
	s_setprio 0
	s_barrier
	s_add_i32 s49, s49, s19
	v_lshl_add_u64 v[212:213], s[50:51], 0, v[184:185]
	s_mov_b32 m0, s49
	ds_read_b128 v[148:151], v251 offset:16384
	ds_read_b128 v[152:155], v251 offset:17408
	ds_read_b128 v[156:159], v251 offset:18432
	ds_read_b128 v[160:163], v251 offset:19456
	ds_read_b128 v[164:167], v251 offset:20480
	ds_read_b128 v[168:171], v251 offset:21504
	ds_read_b128 v[200:203], v251 offset:22528
	ds_read_b128 v[204:207], v251 offset:23552
	global_load_lds_dwordx4 v[212:213], off
	s_add_i32 m0, s49, 0x2000
	s_add_u32 s50, s50, s8
	v_lshl_add_u64 v[214:215], v[212:213], 0, s[70:71]
	s_addc_u32 s51, s51, 0
	s_add_i32 s24, s24, s19
	global_load_lds_dwordx4 v[214:215], off
	v_lshl_add_u64 v[216:217], s[50:51], 0, v[184:185]
	s_mov_b32 m0, s24
	v_lshl_add_u64 v[218:219], v[216:217], 0, s[70:71]
	global_load_lds_dwordx4 v[216:217], off
	s_add_i32 m0, s24, 0x2000
	v_lshl_add_u64 v[220:221], s[14:15], 0, v[194:195]
	global_load_lds_dwordx4 v[218:219], off
	s_mov_b32 m0, s20
	v_lshl_add_u64 v[222:223], v[220:221], 0, s[70:71]
	global_load_lds_dwordx4 v[220:221], off
	s_mov_b32 m0, s25
	s_nop 0
	global_load_lds_dwordx4 v[222:223], off
	s_waitcnt vmcnt(8)
	s_waitcnt lgkmcnt(0)
	s_barrier
	s_setprio 1
	s_waitcnt lgkmcnt(0)
	v_mfma_f32_16x16x32_bf16 v[60:63], v[80:83], v[148:151], 0
	v_mfma_f32_16x16x32_bf16 v[56:59], v[104:107], v[148:151], 0
	v_mfma_f32_16x16x32_bf16 v[44:47], v[80:83], v[156:159], 0
	v_mfma_f32_16x16x32_bf16 v[40:43], v[104:107], v[156:159], 0
	v_mfma_f32_16x16x32_bf16 v[28:31], v[80:83], v[164:167], 0
	v_mfma_f32_16x16x32_bf16 v[24:27], v[104:107], v[164:167], 0
	v_mfma_f32_16x16x32_bf16 v[12:15], v[80:83], v[200:203], 0
	v_mfma_f32_16x16x32_bf16 v[8:11], v[104:107], v[200:203], 0
	v_mfma_f32_16x16x32_bf16 v[60:63], v[84:87], v[152:155], v[60:63]
	v_mfma_f32_16x16x32_bf16 v[56:59], v[108:111], v[152:155], v[56:59]
	v_mfma_f32_16x16x32_bf16 v[44:47], v[84:87], v[160:163], v[44:47]
	v_mfma_f32_16x16x32_bf16 v[40:43], v[108:111], v[160:163], v[40:43]
	v_mfma_f32_16x16x32_bf16 v[28:31], v[84:87], v[168:171], v[28:31]
	v_mfma_f32_16x16x32_bf16 v[24:27], v[108:111], v[168:171], v[24:27]
	v_mfma_f32_16x16x32_bf16 v[12:15], v[84:87], v[204:207], v[12:15]
	v_mfma_f32_16x16x32_bf16 v[8:11], v[108:111], v[204:207], v[8:11]
	s_setprio 0
	s_setprio 1
	v_mfma_f32_16x16x32_bf16 v[52:55], v[124:127], v[148:151], 0
	v_mfma_f32_16x16x32_bf16 v[48:51], v[136:139], v[148:151], 0
	v_mfma_f32_16x16x32_bf16 v[36:39], v[124:127], v[156:159], 0
	v_mfma_f32_16x16x32_bf16 v[32:35], v[136:139], v[156:159], 0
	v_mfma_f32_16x16x32_bf16 v[20:23], v[124:127], v[164:167], 0
	v_mfma_f32_16x16x32_bf16 v[16:19], v[136:139], v[164:167], 0
	v_mfma_f32_16x16x32_bf16 v[4:7], v[124:127], v[200:203], 0
	v_mfma_f32_16x16x32_bf16 v[0:3], v[136:139], v[200:203], 0
	v_mfma_f32_16x16x32_bf16 v[52:55], v[132:135], v[152:155], v[52:55]
	v_mfma_f32_16x16x32_bf16 v[48:51], v[140:143], v[152:155], v[48:51]
	v_mfma_f32_16x16x32_bf16 v[36:39], v[132:135], v[160:163], v[36:39]
	v_mfma_f32_16x16x32_bf16 v[32:35], v[140:143], v[160:163], v[32:35]
	v_mfma_f32_16x16x32_bf16 v[20:23], v[132:135], v[168:171], v[20:23]
	v_mfma_f32_16x16x32_bf16 v[16:19], v[140:143], v[168:171], v[16:19]
	v_mfma_f32_16x16x32_bf16 v[4:7], v[132:135], v[204:207], v[4:7]
	v_mfma_f32_16x16x32_bf16 v[0:3], v[140:143], v[204:207], v[0:3]
	s_setprio 0
	s_barrier
	s_add_i32 s24, 0, 0x18000
	s_add_i32 s49, 0, 0x1c000
	v_add_u32_e32 v108, s24, v249
	v_add_u32_e32 v140, s49, v249
	ds_read_b128 v[80:83], v108
	ds_read_b128 v[84:87], v108 offset:1024
	ds_read_b128 v[104:107], v108 offset:2048
	ds_read_b128 v[108:111], v108 offset:3072
	ds_read_b128 v[124:127], v140
	ds_read_b128 v[132:135], v140 offset:1024
	ds_read_b128 v[136:139], v140 offset:2048
	ds_read_b128 v[140:143], v140 offset:3072
	s_add_u32 s14, s14, s8
	s_addc_u32 s15, s15, 0
	s_mov_b32 m0, s26
	v_lshl_add_u64 v[168:169], s[14:15], 0, v[194:195]
	ds_read_b128 v[148:151], v251 offset:32768
	ds_read_b128 v[152:155], v251 offset:33792
	ds_read_b128 v[156:159], v251 offset:34816
	ds_read_b128 v[160:163], v251 offset:35840
	ds_read_b128 v[164:167], v251 offset:36864
	ds_read_b128 v[200:203], v251 offset:37888
	ds_read_b128 v[204:207], v251 offset:38912
	ds_read_b128 v[208:211], v251 offset:39936
	global_load_lds_dwordx4 v[168:169], off
	v_lshl_add_u64 v[168:169], v[168:169], 0, s[70:71]
	s_mov_b32 m0, s27
	s_nop 0
	global_load_lds_dwordx4 v[168:169], off
	s_waitcnt vmcnt(8)
	s_waitcnt lgkmcnt(0)
	s_barrier
	s_setprio 1
	s_waitcnt lgkmcnt(0)
	v_mfma_f32_16x16x32_bf16 v[168:171], v[80:83], v[148:151], v[180:183]
	v_mfma_f32_16x16x32_bf16 v[180:183], v[84:87], v[152:155], v[168:171]
	v_mfma_f32_16x16x32_bf16 v[168:171], v[104:107], v[148:151], v[176:179]
	v_mfma_f32_16x16x32_bf16 v[128:131], v[80:83], v[156:159], v[128:131]
	v_mfma_f32_16x16x32_bf16 v[120:123], v[104:107], v[156:159], v[120:123]
	v_mfma_f32_16x16x32_bf16 v[100:103], v[80:83], v[164:167], v[100:103]
	v_mfma_f32_16x16x32_bf16 v[96:99], v[104:107], v[164:167], v[96:99]
	v_mfma_f32_16x16x32_bf16 v[76:79], v[80:83], v[204:207], v[76:79]
	v_mfma_f32_16x16x32_bf16 v[72:75], v[104:107], v[204:207], v[72:75]
	v_mfma_f32_16x16x32_bf16 v[176:179], v[108:111], v[152:155], v[168:171]
	v_mfma_f32_16x16x32_bf16 v[128:131], v[84:87], v[160:163], v[128:131]
	v_mfma_f32_16x16x32_bf16 v[120:123], v[108:111], v[160:163], v[120:123]
	v_mfma_f32_16x16x32_bf16 v[100:103], v[84:87], v[200:203], v[100:103]
	v_mfma_f32_16x16x32_bf16 v[96:99], v[108:111], v[200:203], v[96:99]
	v_mfma_f32_16x16x32_bf16 v[76:79], v[84:87], v[208:211], v[76:79]
	v_mfma_f32_16x16x32_bf16 v[72:75], v[108:111], v[208:211], v[72:75]
	s_setprio 0
	s_setprio 1
	v_mfma_f32_16x16x32_bf16 v[168:171], v[124:127], v[148:151], v[172:175]
	v_mfma_f32_16x16x32_bf16 v[144:147], v[136:139], v[148:151], v[144:147]
	v_mfma_f32_16x16x32_bf16 v[116:119], v[124:127], v[156:159], v[116:119]
	v_mfma_f32_16x16x32_bf16 v[112:115], v[136:139], v[156:159], v[112:115]
	v_mfma_f32_16x16x32_bf16 v[92:95], v[124:127], v[164:167], v[92:95]
	v_mfma_f32_16x16x32_bf16 v[88:91], v[136:139], v[164:167], v[88:91]
	v_mfma_f32_16x16x32_bf16 v[68:71], v[124:127], v[204:207], v[68:71]
	v_mfma_f32_16x16x32_bf16 v[64:67], v[136:139], v[204:207], v[64:67]
	v_mfma_f32_16x16x32_bf16 v[172:175], v[132:135], v[152:155], v[168:171]
	v_mfma_f32_16x16x32_bf16 v[168:171], v[140:143], v[152:155], v[144:147]
	v_mfma_f32_16x16x32_bf16 v[116:119], v[132:135], v[160:163], v[116:119]
	v_mfma_f32_16x16x32_bf16 v[112:115], v[140:143], v[160:163], v[112:115]
	v_mfma_f32_16x16x32_bf16 v[92:95], v[132:135], v[200:203], v[92:95]
	v_mfma_f32_16x16x32_bf16 v[88:91], v[140:143], v[200:203], v[88:91]
	v_mfma_f32_16x16x32_bf16 v[68:71], v[132:135], v[208:211], v[68:71]
	v_mfma_f32_16x16x32_bf16 v[64:67], v[140:143], v[208:211], v[64:67]
	s_setprio 0
	s_barrier
	s_add_i32 s14, s24, s19
	v_lshl_add_u64 v[208:209], v[212:213], 0, s[56:57]
	s_mov_b32 m0, s14
	ds_read_b128 v[144:147], v251 offset:49152
	ds_read_b128 v[148:151], v251 offset:50176
	ds_read_b128 v[152:155], v251 offset:51200
	ds_read_b128 v[156:159], v251 offset:52224
	ds_read_b128 v[160:163], v251 offset:53248
	ds_read_b128 v[164:167], v251 offset:54272
	ds_read_b128 v[200:203], v251 offset:55296
	ds_read_b128 v[204:207], v251 offset:56320
	global_load_lds_dwordx4 v[208:209], off
	v_lshl_add_u64 v[208:209], v[214:215], 0, s[56:57]
	s_add_i32 m0, s14, 0x2000
	s_add_i32 s14, s49, s19
	global_load_lds_dwordx4 v[208:209], off
	v_lshl_add_u64 v[208:209], v[216:217], 0, s[56:57]
	s_mov_b32 m0, s14
	s_nop 0
	global_load_lds_dwordx4 v[208:209], off
	v_lshl_add_u64 v[208:209], v[218:219], 0, s[56:57]
	s_add_i32 m0, s14, 0x2000
	s_nop 0
	global_load_lds_dwordx4 v[208:209], off
	v_lshl_add_u64 v[208:209], v[220:221], 0, s[56:57]
	s_mov_b32 m0, s29
	s_nop 0
	global_load_lds_dwordx4 v[208:209], off
	v_lshl_add_u64 v[208:209], v[222:223], 0, s[56:57]
	s_mov_b32 m0, s30
	s_nop 0
	global_load_lds_dwordx4 v[208:209], off
	s_waitcnt vmcnt(8)
	s_waitcnt lgkmcnt(0)
	s_barrier
	s_setprio 1
	s_waitcnt lgkmcnt(0)
	v_mfma_f32_16x16x32_bf16 v[60:63], v[80:83], v[144:147], v[60:63]
	v_mfma_f32_16x16x32_bf16 v[56:59], v[104:107], v[144:147], v[56:59]
	v_mfma_f32_16x16x32_bf16 v[44:47], v[80:83], v[152:155], v[44:47]
	v_mfma_f32_16x16x32_bf16 v[40:43], v[104:107], v[152:155], v[40:43]
	v_mfma_f32_16x16x32_bf16 v[28:31], v[80:83], v[160:163], v[28:31]
	v_mfma_f32_16x16x32_bf16 v[24:27], v[104:107], v[160:163], v[24:27]
	v_mfma_f32_16x16x32_bf16 v[12:15], v[80:83], v[200:203], v[12:15]
	v_mfma_f32_16x16x32_bf16 v[8:11], v[104:107], v[200:203], v[8:11]
	v_mfma_f32_16x16x32_bf16 v[60:63], v[84:87], v[148:151], v[60:63]
	v_mfma_f32_16x16x32_bf16 v[56:59], v[108:111], v[148:151], v[56:59]
	v_mfma_f32_16x16x32_bf16 v[44:47], v[84:87], v[156:159], v[44:47]
	v_mfma_f32_16x16x32_bf16 v[40:43], v[108:111], v[156:159], v[40:43]
	v_mfma_f32_16x16x32_bf16 v[28:31], v[84:87], v[164:167], v[28:31]
	v_mfma_f32_16x16x32_bf16 v[24:27], v[108:111], v[164:167], v[24:27]
	v_mfma_f32_16x16x32_bf16 v[12:15], v[84:87], v[204:207], v[12:15]
	v_mfma_f32_16x16x32_bf16 v[8:11], v[108:111], v[204:207], v[8:11]
	s_setprio 0
	s_setprio 1
	v_mfma_f32_16x16x32_bf16 v[52:55], v[124:127], v[144:147], v[52:55]
	v_mfma_f32_16x16x32_bf16 v[48:51], v[136:139], v[144:147], v[48:51]
	v_mfma_f32_16x16x32_bf16 v[36:39], v[124:127], v[152:155], v[36:39]
	v_mfma_f32_16x16x32_bf16 v[32:35], v[136:139], v[152:155], v[32:35]
	v_mfma_f32_16x16x32_bf16 v[20:23], v[124:127], v[160:163], v[20:23]
	v_mfma_f32_16x16x32_bf16 v[16:19], v[136:139], v[160:163], v[16:19]
	v_mfma_f32_16x16x32_bf16 v[4:7], v[124:127], v[200:203], v[4:7]
	v_mfma_f32_16x16x32_bf16 v[0:3], v[136:139], v[200:203], v[0:3]
	v_mfma_f32_16x16x32_bf16 v[52:55], v[132:135], v[148:151], v[52:55]
	v_mfma_f32_16x16x32_bf16 v[48:51], v[140:143], v[148:151], v[48:51]
	v_mfma_f32_16x16x32_bf16 v[36:39], v[132:135], v[156:159], v[36:39]
	v_mfma_f32_16x16x32_bf16 v[32:35], v[140:143], v[156:159], v[32:35]
	v_mfma_f32_16x16x32_bf16 v[20:23], v[132:135], v[164:167], v[20:23]
	v_mfma_f32_16x16x32_bf16 v[16:19], v[140:143], v[164:167], v[16:19]
	v_mfma_f32_16x16x32_bf16 v[4:7], v[132:135], v[204:207], v[4:7]
	v_mfma_f32_16x16x32_bf16 v[0:3], v[140:143], v[204:207], v[0:3]
	s_setprio 0
	s_barrier
	s_add_u32 s44, s44, 0x100
	s_addc_u32 s45, s45, 0
	s_add_u32 s16, s16, 0x100
	s_addc_u32 s17, s17, 0
	s_cmp_ge_u32 s23, s28
	s_mov_b32 s14, s23

.LBB0_441:
	s_or_b64 exec, exec, s[14:15]
	s_and_b64 vcc, exec, s[38:39]
	s_mov_b64 s[14:15], -1
	s_cbranch_vccnz .LBB0_410
	s_andn2_b64 vcc, exec, s[10:11]
	s_cbranch_vccnz .LBB0_409
	s_mov_b32 s98, 1
	s_branch .LBB0_409

.LBB0_458:
	s_ashr_i32 s43, s42, 31
	s_lshl_b64 s[44:45], s[42:43], 19
	s_add_u32 s44, s64, s44
	s_addc_u32 s45, s65, s45
	s_and_b64 s[46:47], s[40:41], exec
	s_cselect_b32 s31, s45, s17
	s_cselect_b32 s43, s44, s16
	s_ashr_i32 s13, s12, 31
	s_lshl_b64 s[46:47], s[12:13], 19
	s_add_u32 s46, s22, s46
	s_addc_u32 s47, s23, s47
	s_and_b64 s[48:49], s[40:41], exec
	s_cselect_b32 s13, s47, s15
	s_cselect_b32 s50, s46, s14
	s_add_u32 s48, s16, 0x40080
	s_addc_u32 s49, s17, 0
	s_add_u32 s16, s14, 0x100
	s_addc_u32 s17, s15, 0
	s_mov_b32 s51, -2
	s_cmp_eq_u32 s98, 1
	s_cbranch_scc0 .Lnostb6
	s_mov_b32 s98, 0
	s_barrier
.Lnostb6:
	s_add_u32 s14, s48, 0xfffc0080
	s_addc_u32 s15, s49, -1
	s_add_i32 s70, 0, 0x10000
	s_cmp_eq_u32 s51, 12
	s_cselect_b32 s15, s31, s15
	s_cselect_b32 s14, s43, s14
	v_add_u32_e32 v138, s70, v142
	s_cselect_b32 s61, s13, s17
	s_cselect_b32 s60, s50, s16
	s_add_i32 s84, 0, 0x14000
	ds_read_b128 v[134:137], v138
	ds_read_b128 v[148:151], v138 offset:1024
	ds_read_b128 v[152:155], v138 offset:2048
	ds_read_b128 v[156:159], v138 offset:3072
	v_add_u32_e32 v138, s84, v142
	ds_read_b128 v[160:163], v138
	ds_read_b128 v[164:167], v138 offset:1024
	ds_read_b128 v[168:171], v138 offset:2048
	ds_read_b128 v[172:175], v138 offset:3072
	v_lshl_add_u64 v[138:139], s[48:49], 0, v[132:133]
	s_add_i32 m0, s19, 0xc000
	ds_read_b128 v[176:179], v146
	ds_read_b128 v[180:183], v146 offset:1024
	ds_read_b128 v[194:197], v146 offset:2048
	ds_read_b128 v[198:201], v146 offset:3072
	ds_read_b128 v[202:205], v146 offset:4096
	ds_read_b128 v[206:209], v146 offset:5120
	ds_read_b128 v[210:213], v146 offset:6144
	ds_read_b128 v[214:217], v146 offset:7168
	global_load_lds_dwordx4 v[138:139], off
	v_lshl_add_u64 v[138:139], v[138:139], 0, s[34:35]
	s_add_i32 m0, s19, 0xe000
	s_nop 0
	global_load_lds_dwordx4 v[138:139], off
	s_waitcnt vmcnt(8)
	s_waitcnt lgkmcnt(0)
	s_barrier
	s_setprio 1
	s_waitcnt lgkmcnt(0)
	v_mfma_f32_16x16x32_bf16 v[124:127], v[134:137], v[176:179], 0
	v_mfma_f32_16x16x32_bf16 v[116:119], v[152:155], v[176:179], 0
	v_mfma_f32_16x16x32_bf16 v[108:111], v[134:137], v[194:197], 0
	v_mfma_f32_16x16x32_bf16 v[100:103], v[152:155], v[194:197], 0
	v_mfma_f32_16x16x32_bf16 v[92:95], v[134:137], v[202:205], 0
	v_mfma_f32_16x16x32_bf16 v[84:87], v[152:155], v[202:205], 0
	v_mfma_f32_16x16x32_bf16 v[76:79], v[134:137], v[210:213], 0
	v_mfma_f32_16x16x32_bf16 v[68:71], v[152:155], v[210:213], 0
	v_mfma_f32_16x16x32_bf16 v[124:127], v[148:151], v[180:183], v[124:127]
	v_mfma_f32_16x16x32_bf16 v[116:119], v[156:159], v[180:183], v[116:119]
	v_mfma_f32_16x16x32_bf16 v[108:111], v[148:151], v[198:201], v[108:111]
	v_mfma_f32_16x16x32_bf16 v[100:103], v[156:159], v[198:201], v[100:103]
	v_mfma_f32_16x16x32_bf16 v[92:95], v[148:151], v[206:209], v[92:95]
	v_mfma_f32_16x16x32_bf16 v[84:87], v[156:159], v[206:209], v[84:87]
	v_mfma_f32_16x16x32_bf16 v[76:79], v[148:151], v[214:217], v[76:79]
	v_mfma_f32_16x16x32_bf16 v[68:71], v[156:159], v[214:217], v[68:71]
	s_setprio 0
	s_setprio 1
	v_mfma_f32_16x16x32_bf16 v[120:123], v[160:163], v[176:179], 0
	v_mfma_f32_16x16x32_bf16 v[112:115], v[168:171], v[176:179], 0
	v_mfma_f32_16x16x32_bf16 v[104:107], v[160:163], v[194:197], 0
	v_mfma_f32_16x16x32_bf16 v[96:99], v[168:171], v[194:197], 0
	v_mfma_f32_16x16x32_bf16 v[88:91], v[160:163], v[202:205], 0
	v_mfma_f32_16x16x32_bf16 v[80:83], v[168:171], v[202:205], 0
	v_mfma_f32_16x16x32_bf16 v[72:75], v[160:163], v[210:213], 0
	v_mfma_f32_16x16x32_bf16 v[64:67], v[168:171], v[210:213], 0
	v_mfma_f32_16x16x32_bf16 v[120:123], v[164:167], v[180:183], v[120:123]
	v_mfma_f32_16x16x32_bf16 v[112:115], v[172:175], v[180:183], v[112:115]
	v_mfma_f32_16x16x32_bf16 v[104:107], v[164:167], v[198:201], v[104:107]
	v_mfma_f32_16x16x32_bf16 v[96:99], v[172:175], v[198:201], v[96:99]
	v_mfma_f32_16x16x32_bf16 v[88:91], v[164:167], v[206:209], v[88:91]
	v_mfma_f32_16x16x32_bf16 v[80:83], v[172:175], v[206:209], v[80:83]
	v_mfma_f32_16x16x32_bf16 v[72:75], v[164:167], v[214:217], v[72:75]
	v_mfma_f32_16x16x32_bf16 v[64:67], v[172:175], v[214:217], v[64:67]
	s_setprio 0
	s_barrier
	v_lshl_add_u64 v[138:139], s[60:61], 0, v[184:185]
	s_add_i32 s60, s70, s6
	s_mov_b32 m0, s60
	ds_read_b128 v[176:179], v146 offset:16384
	ds_read_b128 v[180:183], v146 offset:17408
	ds_read_b128 v[194:197], v146 offset:18432
	ds_read_b128 v[198:201], v146 offset:19456
	ds_read_b128 v[202:205], v146 offset:20480
	ds_read_b128 v[206:209], v146 offset:21504
	ds_read_b128 v[210:213], v146 offset:22528
	ds_read_b128 v[214:217], v146 offset:23552
	global_load_lds_dwordx4 v[138:139], off
	v_lshl_add_u64 v[218:219], v[138:139], 0, s[34:35]
	s_add_i32 m0, s60, 0x2000
	s_add_i32 s60, s84, s6
	global_load_lds_dwordx4 v[218:219], off
	v_lshl_add_u64 v[218:219], v[138:139], 0, s[92:93]
	s_mov_b32 m0, s60
	s_nop 0
	global_load_lds_dwordx4 v[218:219], off
	v_lshl_add_u64 v[218:219], v[138:139], 0, s[52:53]
	s_add_i32 m0, s60, 0x2000
	s_nop 0
	global_load_lds_dwordx4 v[218:219], off
	v_lshl_add_u64 v[218:219], s[14:15], 0, v[128:129]
	s_mov_b32 m0, s19
	v_lshl_add_u64 v[220:221], v[218:219], 0, s[34:35]
	global_load_lds_dwordx4 v[218:219], off
	s_mov_b32 m0, s20
	s_nop 0
	global_load_lds_dwordx4 v[220:221], off
	s_waitcnt vmcnt(8)
	s_waitcnt lgkmcnt(0)
	s_barrier
	s_setprio 1
	s_waitcnt lgkmcnt(0)
	v_mfma_f32_16x16x32_bf16 v[60:63], v[134:137], v[176:179], 0
	v_mfma_f32_16x16x32_bf16 v[52:55], v[152:155], v[176:179], 0
	v_mfma_f32_16x16x32_bf16 v[44:47], v[134:137], v[194:197], 0
	v_mfma_f32_16x16x32_bf16 v[36:39], v[152:155], v[194:197], 0
	v_mfma_f32_16x16x32_bf16 v[28:31], v[134:137], v[202:205], 0
	v_mfma_f32_16x16x32_bf16 v[20:23], v[152:155], v[202:205], 0
	v_mfma_f32_16x16x32_bf16 v[12:15], v[134:137], v[210:213], 0
	v_mfma_f32_16x16x32_bf16 v[4:7], v[152:155], v[210:213], 0
	v_mfma_f32_16x16x32_bf16 v[60:63], v[148:151], v[180:183], v[60:63]
	v_mfma_f32_16x16x32_bf16 v[52:55], v[156:159], v[180:183], v[52:55]
	v_mfma_f32_16x16x32_bf16 v[44:47], v[148:151], v[198:201], v[44:47]
	v_mfma_f32_16x16x32_bf16 v[36:39], v[156:159], v[198:201], v[36:39]
	v_mfma_f32_16x16x32_bf16 v[28:31], v[148:151], v[206:209], v[28:31]
	v_mfma_f32_16x16x32_bf16 v[20:23], v[156:159], v[206:209], v[20:23]
	v_mfma_f32_16x16x32_bf16 v[12:15], v[148:151], v[214:217], v[12:15]
	v_mfma_f32_16x16x32_bf16 v[4:7], v[156:159], v[214:217], v[4:7]
	s_setprio 0
	s_setprio 1
	v_mfma_f32_16x16x32_bf16 v[56:59], v[160:163], v[176:179], 0
	v_mfma_f32_16x16x32_bf16 v[48:51], v[168:171], v[176:179], 0
	v_mfma_f32_16x16x32_bf16 v[40:43], v[160:163], v[194:197], 0
	v_mfma_f32_16x16x32_bf16 v[32:35], v[168:171], v[194:197], 0
	v_mfma_f32_16x16x32_bf16 v[24:27], v[160:163], v[202:205], 0
	v_mfma_f32_16x16x32_bf16 v[16:19], v[168:171], v[202:205], 0
	v_mfma_f32_16x16x32_bf16 v[8:11], v[160:163], v[210:213], 0
	v_mfma_f32_16x16x32_bf16 v[0:3], v[168:171], v[210:213], 0
	v_mfma_f32_16x16x32_bf16 v[56:59], v[164:167], v[180:183], v[56:59]
	v_mfma_f32_16x16x32_bf16 v[48:51], v[172:175], v[180:183], v[48:51]
	v_mfma_f32_16x16x32_bf16 v[40:43], v[164:167], v[198:201], v[40:43]
	v_mfma_f32_16x16x32_bf16 v[32:35], v[172:175], v[198:201], v[32:35]
	v_mfma_f32_16x16x32_bf16 v[24:27], v[164:167], v[206:209], v[24:27]
	v_mfma_f32_16x16x32_bf16 v[16:19], v[172:175], v[206:209], v[16:19]
	v_mfma_f32_16x16x32_bf16 v[8:11], v[164:167], v[214:217], v[8:11]
	v_mfma_f32_16x16x32_bf16 v[0:3], v[172:175], v[214:217], v[0:3]
	s_setprio 0
	s_barrier
	s_add_i32 s14, 0, 0x18000
	v_add_u32_e32 v147, s14, v142
	s_add_i32 s15, 0, 0x1c000
	ds_read_b128 v[134:137], v147
	ds_read_b128 v[148:151], v147 offset:1024
	ds_read_b128 v[152:155], v147 offset:2048
	ds_read_b128 v[156:159], v147 offset:3072
	v_add_u32_e32 v147, s15, v142
	ds_read_b128 v[160:163], v147
	ds_read_b128 v[164:167], v147 offset:1024
	ds_read_b128 v[168:171], v147 offset:2048
	ds_read_b128 v[172:175], v147 offset:3072
	s_mov_b32 m0, s24
	v_lshl_add_u64 v[220:221], v[218:219], 0, s[92:93]
	ds_read_b128 v[176:179], v146 offset:32768
	ds_read_b128 v[180:183], v146 offset:33792
	ds_read_b128 v[194:197], v146 offset:34816
	ds_read_b128 v[198:201], v146 offset:35840
	ds_read_b128 v[202:205], v146 offset:36864
	ds_read_b128 v[206:209], v146 offset:37888
	ds_read_b128 v[210:213], v146 offset:38912
	ds_read_b128 v[214:217], v146 offset:39936
	global_load_lds_dwordx4 v[220:221], off
	v_lshl_add_u64 v[220:221], v[218:219], 0, s[52:53]
	s_mov_b32 m0, s25
	s_nop 0
	global_load_lds_dwordx4 v[220:221], off
	s_waitcnt vmcnt(8)
	s_waitcnt lgkmcnt(0)
	s_barrier
	s_setprio 1
	s_waitcnt lgkmcnt(0)
	v_mfma_f32_16x16x32_bf16 v[124:127], v[134:137], v[176:179], v[124:127]
	v_mfma_f32_16x16x32_bf16 v[116:119], v[152:155], v[176:179], v[116:119]
	v_mfma_f32_16x16x32_bf16 v[108:111], v[134:137], v[194:197], v[108:111]
	v_mfma_f32_16x16x32_bf16 v[100:103], v[152:155], v[194:197], v[100:103]
	v_mfma_f32_16x16x32_bf16 v[92:95], v[134:137], v[202:205], v[92:95]
	v_mfma_f32_16x16x32_bf16 v[84:87], v[152:155], v[202:205], v[84:87]
	v_mfma_f32_16x16x32_bf16 v[76:79], v[134:137], v[210:213], v[76:79]
	v_mfma_f32_16x16x32_bf16 v[68:71], v[152:155], v[210:213], v[68:71]
	v_mfma_f32_16x16x32_bf16 v[124:127], v[148:151], v[180:183], v[124:127]
	v_mfma_f32_16x16x32_bf16 v[116:119], v[156:159], v[180:183], v[116:119]
	v_mfma_f32_16x16x32_bf16 v[108:111], v[148:151], v[198:201], v[108:111]
	v_mfma_f32_16x16x32_bf16 v[100:103], v[156:159], v[198:201], v[100:103]
	v_mfma_f32_16x16x32_bf16 v[92:95], v[148:151], v[206:209], v[92:95]
	v_mfma_f32_16x16x32_bf16 v[84:87], v[156:159], v[206:209], v[84:87]
	v_mfma_f32_16x16x32_bf16 v[76:79], v[148:151], v[214:217], v[76:79]
	v_mfma_f32_16x16x32_bf16 v[68:71], v[156:159], v[214:217], v[68:71]
	s_setprio 0
	s_setprio 1
	v_mfma_f32_16x16x32_bf16 v[120:123], v[160:163], v[176:179], v[120:123]
	v_mfma_f32_16x16x32_bf16 v[112:115], v[168:171], v[176:179], v[112:115]
	v_mfma_f32_16x16x32_bf16 v[104:107], v[160:163], v[194:197], v[104:107]
	v_mfma_f32_16x16x32_bf16 v[96:99], v[168:171], v[194:197], v[96:99]
	v_mfma_f32_16x16x32_bf16 v[88:91], v[160:163], v[202:205], v[88:91]
	v_mfma_f32_16x16x32_bf16 v[80:83], v[168:171], v[202:205], v[80:83]
	v_mfma_f32_16x16x32_bf16 v[72:75], v[160:163], v[210:213], v[72:75]
	v_mfma_f32_16x16x32_bf16 v[64:67], v[168:171], v[210:213], v[64:67]
	v_mfma_f32_16x16x32_bf16 v[120:123], v[164:167], v[180:183], v[120:123]
	v_mfma_f32_16x16x32_bf16 v[112:115], v[172:175], v[180:183], v[112:115]
	v_mfma_f32_16x16x32_bf16 v[104:107], v[164:167], v[198:201], v[104:107]
	v_mfma_f32_16x16x32_bf16 v[96:99], v[172:175], v[198:201], v[96:99]
	v_mfma_f32_16x16x32_bf16 v[88:91], v[164:167], v[206:209], v[88:91]
	v_mfma_f32_16x16x32_bf16 v[80:83], v[172:175], v[206:209], v[80:83]
	v_mfma_f32_16x16x32_bf16 v[72:75], v[164:167], v[214:217], v[72:75]
	v_mfma_f32_16x16x32_bf16 v[64:67], v[172:175], v[214:217], v[64:67]
	s_setprio 0
	s_barrier
	s_add_i32 s14, s14, s6
	v_lshl_add_u64 v[220:221], v[138:139], 0, s[56:57]
	s_mov_b32 m0, s14
	ds_read_b128 v[176:179], v146 offset:49152
	ds_read_b128 v[180:183], v146 offset:50176
	ds_read_b128 v[194:197], v146 offset:51200
	ds_read_b128 v[198:201], v146 offset:52224
	ds_read_b128 v[202:205], v146 offset:53248
	ds_read_b128 v[206:209], v146 offset:54272
	ds_read_b128 v[210:213], v146 offset:55296
	ds_read_b128 v[214:217], v146 offset:56320
	global_load_lds_dwordx4 v[220:221], off
	v_lshl_add_u64 v[220:221], v[138:139], 0, s[96:97]
	s_add_i32 m0, s14, 0x2000
	s_add_i32 s14, s15, s6
	global_load_lds_dwordx4 v[220:221], off
	v_lshl_add_u64 v[220:221], v[138:139], 0, s[88:89]
	s_mov_b32 m0, s14
	v_lshl_add_u64 v[138:139], v[138:139], 0, s[68:69]
	global_load_lds_dwordx4 v[220:221], off
	s_add_i32 m0, s14, 0x2000
	s_nop 0
	global_load_lds_dwordx4 v[138:139], off
	v_lshl_add_u64 v[138:139], v[218:219], 0, s[56:57]
	s_mov_b32 m0, s26
	s_nop 0
	global_load_lds_dwordx4 v[138:139], off
	v_lshl_add_u64 v[138:139], v[218:219], 0, s[96:97]
	s_mov_b32 m0, s27
	s_nop 0
	global_load_lds_dwordx4 v[138:139], off
	s_waitcnt vmcnt(8)
	s_waitcnt lgkmcnt(0)
	s_barrier
	s_setprio 1
	s_waitcnt lgkmcnt(0)
	v_mfma_f32_16x16x32_bf16 v[60:63], v[134:137], v[176:179], v[60:63]
	v_mfma_f32_16x16x32_bf16 v[52:55], v[152:155], v[176:179], v[52:55]
	v_mfma_f32_16x16x32_bf16 v[44:47], v[134:137], v[194:197], v[44:47]
	v_mfma_f32_16x16x32_bf16 v[36:39], v[152:155], v[194:197], v[36:39]
	v_mfma_f32_16x16x32_bf16 v[28:31], v[134:137], v[202:205], v[28:31]
	v_mfma_f32_16x16x32_bf16 v[20:23], v[152:155], v[202:205], v[20:23]
	v_mfma_f32_16x16x32_bf16 v[12:15], v[134:137], v[210:213], v[12:15]
	v_mfma_f32_16x16x32_bf16 v[4:7], v[152:155], v[210:213], v[4:7]
	v_mfma_f32_16x16x32_bf16 v[60:63], v[148:151], v[180:183], v[60:63]
	v_mfma_f32_16x16x32_bf16 v[52:55], v[156:159], v[180:183], v[52:55]
	v_mfma_f32_16x16x32_bf16 v[44:47], v[148:151], v[198:201], v[44:47]
	v_mfma_f32_16x16x32_bf16 v[36:39], v[156:159], v[198:201], v[36:39]
	v_mfma_f32_16x16x32_bf16 v[28:31], v[148:151], v[206:209], v[28:31]
	v_mfma_f32_16x16x32_bf16 v[20:23], v[156:159], v[206:209], v[20:23]
	v_mfma_f32_16x16x32_bf16 v[12:15], v[148:151], v[214:217], v[12:15]
	v_mfma_f32_16x16x32_bf16 v[4:7], v[156:159], v[214:217], v[4:7]
	s_setprio 0
	s_setprio 1
	v_mfma_f32_16x16x32_bf16 v[56:59], v[160:163], v[176:179], v[56:59]
	v_mfma_f32_16x16x32_bf16 v[48:51], v[168:171], v[176:179], v[48:51]
	v_mfma_f32_16x16x32_bf16 v[40:43], v[160:163], v[194:197], v[40:43]
	v_mfma_f32_16x16x32_bf16 v[32:35], v[168:171], v[194:197], v[32:35]
	v_mfma_f32_16x16x32_bf16 v[24:27], v[160:163], v[202:205], v[24:27]
	v_mfma_f32_16x16x32_bf16 v[16:19], v[168:171], v[202:205], v[16:19]
	v_mfma_f32_16x16x32_bf16 v[8:11], v[160:163], v[210:213], v[8:11]
	v_mfma_f32_16x16x32_bf16 v[0:3], v[168:171], v[210:213], v[0:3]
	v_mfma_f32_16x16x32_bf16 v[56:59], v[164:167], v[180:183], v[56:59]
	v_mfma_f32_16x16x32_bf16 v[48:51], v[172:175], v[180:183], v[48:51]
	v_mfma_f32_16x16x32_bf16 v[40:43], v[164:167], v[198:201], v[40:43]
	v_mfma_f32_16x16x32_bf16 v[32:35], v[172:175], v[198:201], v[32:35]
	v_mfma_f32_16x16x32_bf16 v[24:27], v[164:167], v[206:209], v[24:27]
	v_mfma_f32_16x16x32_bf16 v[16:19], v[172:175], v[206:209], v[16:19]
	v_mfma_f32_16x16x32_bf16 v[8:11], v[164:167], v[214:217], v[8:11]
	v_mfma_f32_16x16x32_bf16 v[0:3], v[172:175], v[214:217], v[0:3]
	s_setprio 0
	s_barrier
	s_add_i32 s51, s51, 2
	s_add_u32 s48, s48, 0x100
	s_addc_u32 s49, s49, 0
	s_add_u32 s16, s16, 0x100
	s_addc_u32 s17, s17, 0
	s_cmp_gt_u32 s51, 13

.LBB0_467:
	s_andn2_b64 vcc, exec, s[8:9]
	s_cbranch_vccnz .LBB0_454
	s_mov_b32 s98, 1
	s_branch .LBB0_454

.LBB0_480:
	s_ashr_i32 s41, s40, 31
	s_lshl_b64 s[42:43], s[40:41], 19
	s_add_u32 s42, s64, s42
	s_addc_u32 s43, s65, s43
	s_and_b64 s[44:45], s[38:39], exec
	s_cselect_b32 s31, s43, s17
	s_cselect_b32 s41, s42, s16
	s_ashr_i32 s13, s12, 31
	s_lshl_b64 s[44:45], s[12:13], 19
	s_add_u32 s44, s22, s44
	s_addc_u32 s45, s23, s45
	s_and_b64 s[46:47], s[38:39], exec
	s_cselect_b32 s13, s45, s15
	s_cselect_b32 s48, s44, s14
	s_add_u32 s46, s16, 0x40080
	s_addc_u32 s47, s17, 0
	s_add_u32 s16, s14, 0x100
	s_addc_u32 s17, s15, 0
	s_mov_b32 s49, -2
	s_cmp_eq_u32 s98, 1
	s_cbranch_scc0 .Lnostb7
	s_mov_b32 s98, 0
	s_barrier
.Lnostb7:
	s_add_u32 s14, s46, 0xfffc0080
	s_addc_u32 s15, s47, -1
	s_add_i32 s60, 0, 0x10000
	s_cmp_eq_u32 s49, 12
	s_cselect_b32 s15, s31, s15
	s_cselect_b32 s14, s41, s14
	v_add_u32_e32 v135, s60, v143
	s_cselect_b32 s51, s13, s17
	s_cselect_b32 s50, s48, s16
	s_add_i32 s61, 0, 0x14000
	ds_read_b128 v[136:139], v135
	ds_read_b128 v[148:151], v135 offset:1024
	ds_read_b128 v[152:155], v135 offset:2048
	ds_read_b128 v[156:159], v135 offset:3072
	v_add_u32_e32 v135, s61, v143
	ds_read_b128 v[160:163], v135
	ds_read_b128 v[164:167], v135 offset:1024
	ds_read_b128 v[168:171], v135 offset:2048
	ds_read_b128 v[172:175], v135 offset:3072
	v_lshl_add_u64 v[140:141], s[46:47], 0, v[184:185]
	s_add_i32 m0, s19, 0xc000
	ds_read_b128 v[176:179], v147
	ds_read_b128 v[180:183], v147 offset:1024
	ds_read_b128 v[194:197], v147 offset:2048
	ds_read_b128 v[198:201], v147 offset:3072
	ds_read_b128 v[202:205], v147 offset:4096
	ds_read_b128 v[206:209], v147 offset:5120
	ds_read_b128 v[210:213], v147 offset:6144
	ds_read_b128 v[214:217], v147 offset:7168
	global_load_lds_dwordx4 v[140:141], off
	v_lshl_add_u64 v[140:141], v[140:141], 0, s[34:35]
	s_add_i32 m0, s19, 0xe000
	s_nop 0
	global_load_lds_dwordx4 v[140:141], off
	s_waitcnt vmcnt(8)
	s_waitcnt lgkmcnt(0)
	s_barrier
	s_setprio 1
	s_waitcnt lgkmcnt(0)
	v_mfma_f32_16x16x32_bf16 v[124:127], v[136:139], v[176:179], 0
	v_mfma_f32_16x16x32_bf16 v[116:119], v[152:155], v[176:179], 0
	v_mfma_f32_16x16x32_bf16 v[108:111], v[136:139], v[194:197], 0
	v_mfma_f32_16x16x32_bf16 v[100:103], v[152:155], v[194:197], 0
	v_mfma_f32_16x16x32_bf16 v[92:95], v[136:139], v[202:205], 0
	v_mfma_f32_16x16x32_bf16 v[84:87], v[152:155], v[202:205], 0
	v_mfma_f32_16x16x32_bf16 v[76:79], v[136:139], v[210:213], 0
	v_mfma_f32_16x16x32_bf16 v[68:71], v[152:155], v[210:213], 0
	v_mfma_f32_16x16x32_bf16 v[124:127], v[148:151], v[180:183], v[124:127]
	v_mfma_f32_16x16x32_bf16 v[116:119], v[156:159], v[180:183], v[116:119]
	v_mfma_f32_16x16x32_bf16 v[108:111], v[148:151], v[198:201], v[108:111]
	v_mfma_f32_16x16x32_bf16 v[100:103], v[156:159], v[198:201], v[100:103]
	v_mfma_f32_16x16x32_bf16 v[92:95], v[148:151], v[206:209], v[92:95]
	v_mfma_f32_16x16x32_bf16 v[84:87], v[156:159], v[206:209], v[84:87]
	v_mfma_f32_16x16x32_bf16 v[76:79], v[148:151], v[214:217], v[76:79]
	v_mfma_f32_16x16x32_bf16 v[68:71], v[156:159], v[214:217], v[68:71]
	s_setprio 0
	s_setprio 1
	v_mfma_f32_16x16x32_bf16 v[120:123], v[160:163], v[176:179], 0
	v_mfma_f32_16x16x32_bf16 v[112:115], v[168:171], v[176:179], 0
	v_mfma_f32_16x16x32_bf16 v[104:107], v[160:163], v[194:197], 0
	v_mfma_f32_16x16x32_bf16 v[96:99], v[168:171], v[194:197], 0
	v_mfma_f32_16x16x32_bf16 v[88:91], v[160:163], v[202:205], 0
	v_mfma_f32_16x16x32_bf16 v[80:83], v[168:171], v[202:205], 0
	v_mfma_f32_16x16x32_bf16 v[72:75], v[160:163], v[210:213], 0
	v_mfma_f32_16x16x32_bf16 v[64:67], v[168:171], v[210:213], 0
	v_mfma_f32_16x16x32_bf16 v[120:123], v[164:167], v[180:183], v[120:123]
	v_mfma_f32_16x16x32_bf16 v[112:115], v[172:175], v[180:183], v[112:115]
	v_mfma_f32_16x16x32_bf16 v[104:107], v[164:167], v[198:201], v[104:107]
	v_mfma_f32_16x16x32_bf16 v[96:99], v[172:175], v[198:201], v[96:99]
	v_mfma_f32_16x16x32_bf16 v[88:91], v[164:167], v[206:209], v[88:91]
	v_mfma_f32_16x16x32_bf16 v[80:83], v[172:175], v[206:209], v[80:83]
	v_mfma_f32_16x16x32_bf16 v[72:75], v[164:167], v[214:217], v[72:75]
	v_mfma_f32_16x16x32_bf16 v[64:67], v[172:175], v[214:217], v[64:67]
	s_setprio 0
	s_barrier
	v_lshl_add_u64 v[140:141], s[50:51], 0, v[128:129]
	s_add_i32 s50, s60, s6
	s_mov_b32 m0, s50
	ds_read_b128 v[176:179], v147 offset:16384
	ds_read_b128 v[180:183], v147 offset:17408
	ds_read_b128 v[194:197], v147 offset:18432
	ds_read_b128 v[198:201], v147 offset:19456
	ds_read_b128 v[202:205], v147 offset:20480
	ds_read_b128 v[206:209], v147 offset:21504
	ds_read_b128 v[210:213], v147 offset:22528
	ds_read_b128 v[214:217], v147 offset:23552
	global_load_lds_dwordx4 v[140:141], off
	v_lshl_add_u64 v[218:219], v[140:141], 0, s[34:35]
	s_add_i32 m0, s50, 0x2000
	s_add_i32 s50, s61, s6
	global_load_lds_dwordx4 v[218:219], off
	v_lshl_add_u64 v[218:219], v[140:141], 0, s[92:93]
	s_mov_b32 m0, s50
	s_nop 0
	global_load_lds_dwordx4 v[218:219], off
	v_lshl_add_u64 v[218:219], v[140:141], 0, s[52:53]
	s_add_i32 m0, s50, 0x2000
	s_nop 0
	global_load_lds_dwordx4 v[218:219], off
	v_lshl_add_u64 v[218:219], s[14:15], 0, v[130:131]
	s_mov_b32 m0, s19
	v_lshl_add_u64 v[220:221], v[218:219], 0, s[34:35]
	global_load_lds_dwordx4 v[218:219], off
	s_mov_b32 m0, s20
	s_nop 0
	global_load_lds_dwordx4 v[220:221], off
	s_waitcnt vmcnt(8)
	s_waitcnt lgkmcnt(0)
	s_barrier
	s_setprio 1
	s_waitcnt lgkmcnt(0)
	v_mfma_f32_16x16x32_bf16 v[60:63], v[136:139], v[176:179], 0
	v_mfma_f32_16x16x32_bf16 v[52:55], v[152:155], v[176:179], 0
	v_mfma_f32_16x16x32_bf16 v[44:47], v[136:139], v[194:197], 0
	v_mfma_f32_16x16x32_bf16 v[36:39], v[152:155], v[194:197], 0
	v_mfma_f32_16x16x32_bf16 v[28:31], v[136:139], v[202:205], 0
	v_mfma_f32_16x16x32_bf16 v[20:23], v[152:155], v[202:205], 0
	v_mfma_f32_16x16x32_bf16 v[12:15], v[136:139], v[210:213], 0
	v_mfma_f32_16x16x32_bf16 v[4:7], v[152:155], v[210:213], 0
	v_mfma_f32_16x16x32_bf16 v[60:63], v[148:151], v[180:183], v[60:63]
	v_mfma_f32_16x16x32_bf16 v[52:55], v[156:159], v[180:183], v[52:55]
	v_mfma_f32_16x16x32_bf16 v[44:47], v[148:151], v[198:201], v[44:47]
	v_mfma_f32_16x16x32_bf16 v[36:39], v[156:159], v[198:201], v[36:39]
	v_mfma_f32_16x16x32_bf16 v[28:31], v[148:151], v[206:209], v[28:31]
	v_mfma_f32_16x16x32_bf16 v[20:23], v[156:159], v[206:209], v[20:23]
	v_mfma_f32_16x16x32_bf16 v[12:15], v[148:151], v[214:217], v[12:15]
	v_mfma_f32_16x16x32_bf16 v[4:7], v[156:159], v[214:217], v[4:7]
	s_setprio 0
	s_setprio 1
	v_mfma_f32_16x16x32_bf16 v[56:59], v[160:163], v[176:179], 0
	v_mfma_f32_16x16x32_bf16 v[48:51], v[168:171], v[176:179], 0
	v_mfma_f32_16x16x32_bf16 v[40:43], v[160:163], v[194:197], 0
	v_mfma_f32_16x16x32_bf16 v[32:35], v[168:171], v[194:197], 0
	v_mfma_f32_16x16x32_bf16 v[24:27], v[160:163], v[202:205], 0
	v_mfma_f32_16x16x32_bf16 v[16:19], v[168:171], v[202:205], 0
	v_mfma_f32_16x16x32_bf16 v[8:11], v[160:163], v[210:213], 0
	v_mfma_f32_16x16x32_bf16 v[0:3], v[168:171], v[210:213], 0
	v_mfma_f32_16x16x32_bf16 v[56:59], v[164:167], v[180:183], v[56:59]
	v_mfma_f32_16x16x32_bf16 v[48:51], v[172:175], v[180:183], v[48:51]
	v_mfma_f32_16x16x32_bf16 v[40:43], v[164:167], v[198:201], v[40:43]
	v_mfma_f32_16x16x32_bf16 v[32:35], v[172:175], v[198:201], v[32:35]
	v_mfma_f32_16x16x32_bf16 v[24:27], v[164:167], v[206:209], v[24:27]
	v_mfma_f32_16x16x32_bf16 v[16:19], v[172:175], v[206:209], v[16:19]
	v_mfma_f32_16x16x32_bf16 v[8:11], v[164:167], v[214:217], v[8:11]
	v_mfma_f32_16x16x32_bf16 v[0:3], v[172:175], v[214:217], v[0:3]
	s_setprio 0
	s_barrier
	s_add_i32 s14, 0, 0x18000
	v_add_u32_e32 v135, s14, v143
	s_add_i32 s15, 0, 0x1c000
	ds_read_b128 v[136:139], v135
	ds_read_b128 v[148:151], v135 offset:1024
	ds_read_b128 v[152:155], v135 offset:2048
	ds_read_b128 v[156:159], v135 offset:3072
	v_add_u32_e32 v135, s15, v143
	ds_read_b128 v[160:163], v135
	ds_read_b128 v[164:167], v135 offset:1024
	ds_read_b128 v[168:171], v135 offset:2048
	ds_read_b128 v[172:175], v135 offset:3072
	s_mov_b32 m0, s24
	v_lshl_add_u64 v[220:221], v[218:219], 0, s[92:93]
	ds_read_b128 v[176:179], v147 offset:32768
	ds_read_b128 v[180:183], v147 offset:33792
	ds_read_b128 v[194:197], v147 offset:34816
	ds_read_b128 v[198:201], v147 offset:35840
	ds_read_b128 v[202:205], v147 offset:36864
	ds_read_b128 v[206:209], v147 offset:37888
	ds_read_b128 v[210:213], v147 offset:38912
	ds_read_b128 v[214:217], v147 offset:39936
	global_load_lds_dwordx4 v[220:221], off
	v_lshl_add_u64 v[220:221], v[218:219], 0, s[52:53]
	s_mov_b32 m0, s25
	s_nop 0
	global_load_lds_dwordx4 v[220:221], off
	s_waitcnt vmcnt(8)
	s_waitcnt lgkmcnt(0)
	s_barrier
	s_setprio 1
	s_waitcnt lgkmcnt(0)
	v_mfma_f32_16x16x32_bf16 v[124:127], v[136:139], v[176:179], v[124:127]
	v_mfma_f32_16x16x32_bf16 v[116:119], v[152:155], v[176:179], v[116:119]
	v_mfma_f32_16x16x32_bf16 v[108:111], v[136:139], v[194:197], v[108:111]
	v_mfma_f32_16x16x32_bf16 v[100:103], v[152:155], v[194:197], v[100:103]
	v_mfma_f32_16x16x32_bf16 v[92:95], v[136:139], v[202:205], v[92:95]
	v_mfma_f32_16x16x32_bf16 v[84:87], v[152:155], v[202:205], v[84:87]
	v_mfma_f32_16x16x32_bf16 v[76:79], v[136:139], v[210:213], v[76:79]
	v_mfma_f32_16x16x32_bf16 v[68:71], v[152:155], v[210:213], v[68:71]
	v_mfma_f32_16x16x32_bf16 v[124:127], v[148:151], v[180:183], v[124:127]
	v_mfma_f32_16x16x32_bf16 v[116:119], v[156:159], v[180:183], v[116:119]
	v_mfma_f32_16x16x32_bf16 v[108:111], v[148:151], v[198:201], v[108:111]
	v_mfma_f32_16x16x32_bf16 v[100:103], v[156:159], v[198:201], v[100:103]
	v_mfma_f32_16x16x32_bf16 v[92:95], v[148:151], v[206:209], v[92:95]
	v_mfma_f32_16x16x32_bf16 v[84:87], v[156:159], v[206:209], v[84:87]
	v_mfma_f32_16x16x32_bf16 v[76:79], v[148:151], v[214:217], v[76:79]
	v_mfma_f32_16x16x32_bf16 v[68:71], v[156:159], v[214:217], v[68:71]
	s_setprio 0
	s_setprio 1
	v_mfma_f32_16x16x32_bf16 v[120:123], v[160:163], v[176:179], v[120:123]
	v_mfma_f32_16x16x32_bf16 v[112:115], v[168:171], v[176:179], v[112:115]
	v_mfma_f32_16x16x32_bf16 v[104:107], v[160:163], v[194:197], v[104:107]
	v_mfma_f32_16x16x32_bf16 v[96:99], v[168:171], v[194:197], v[96:99]
	v_mfma_f32_16x16x32_bf16 v[88:91], v[160:163], v[202:205], v[88:91]
	v_mfma_f32_16x16x32_bf16 v[80:83], v[168:171], v[202:205], v[80:83]
	v_mfma_f32_16x16x32_bf16 v[72:75], v[160:163], v[210:213], v[72:75]
	v_mfma_f32_16x16x32_bf16 v[64:67], v[168:171], v[210:213], v[64:67]
	v_mfma_f32_16x16x32_bf16 v[120:123], v[164:167], v[180:183], v[120:123]
	v_mfma_f32_16x16x32_bf16 v[112:115], v[172:175], v[180:183], v[112:115]
	v_mfma_f32_16x16x32_bf16 v[104:107], v[164:167], v[198:201], v[104:107]
	v_mfma_f32_16x16x32_bf16 v[96:99], v[172:175], v[198:201], v[96:99]
	v_mfma_f32_16x16x32_bf16 v[88:91], v[164:167], v[206:209], v[88:91]
	v_mfma_f32_16x16x32_bf16 v[80:83], v[172:175], v[206:209], v[80:83]
	v_mfma_f32_16x16x32_bf16 v[72:75], v[164:167], v[214:217], v[72:75]
	v_mfma_f32_16x16x32_bf16 v[64:67], v[172:175], v[214:217], v[64:67]
	s_setprio 0
	s_barrier
	s_add_i32 s14, s14, s6
	v_lshl_add_u64 v[220:221], v[140:141], 0, s[56:57]
	s_mov_b32 m0, s14
	ds_read_b128 v[176:179], v147 offset:49152
	ds_read_b128 v[180:183], v147 offset:50176
	ds_read_b128 v[194:197], v147 offset:51200
	ds_read_b128 v[198:201], v147 offset:52224
	ds_read_b128 v[202:205], v147 offset:53248
	ds_read_b128 v[206:209], v147 offset:54272
	ds_read_b128 v[210:213], v147 offset:55296
	ds_read_b128 v[214:217], v147 offset:56320
	global_load_lds_dwordx4 v[220:221], off
	v_lshl_add_u64 v[220:221], v[140:141], 0, s[96:97]
	s_add_i32 m0, s14, 0x2000
	s_add_i32 s14, s15, s6
	global_load_lds_dwordx4 v[220:221], off
	v_lshl_add_u64 v[220:221], v[140:141], 0, s[88:89]
	s_mov_b32 m0, s14
	v_lshl_add_u64 v[140:141], v[140:141], 0, s[68:69]
	global_load_lds_dwordx4 v[220:221], off
	s_add_i32 m0, s14, 0x2000
	s_nop 0
	global_load_lds_dwordx4 v[140:141], off
	v_lshl_add_u64 v[140:141], v[218:219], 0, s[56:57]
	s_mov_b32 m0, s26
	s_nop 0
	global_load_lds_dwordx4 v[140:141], off
	v_lshl_add_u64 v[140:141], v[218:219], 0, s[96:97]
	s_mov_b32 m0, s27
	s_nop 0
	global_load_lds_dwordx4 v[140:141], off
	s_waitcnt vmcnt(8)
	s_waitcnt lgkmcnt(0)
	s_barrier
	s_setprio 1
	s_waitcnt lgkmcnt(0)
	v_mfma_f32_16x16x32_bf16 v[60:63], v[136:139], v[176:179], v[60:63]
	v_mfma_f32_16x16x32_bf16 v[52:55], v[152:155], v[176:179], v[52:55]
	v_mfma_f32_16x16x32_bf16 v[44:47], v[136:139], v[194:197], v[44:47]
	v_mfma_f32_16x16x32_bf16 v[36:39], v[152:155], v[194:197], v[36:39]
	v_mfma_f32_16x16x32_bf16 v[28:31], v[136:139], v[202:205], v[28:31]
	v_mfma_f32_16x16x32_bf16 v[20:23], v[152:155], v[202:205], v[20:23]
	v_mfma_f32_16x16x32_bf16 v[12:15], v[136:139], v[210:213], v[12:15]
	v_mfma_f32_16x16x32_bf16 v[4:7], v[152:155], v[210:213], v[4:7]
	v_mfma_f32_16x16x32_bf16 v[60:63], v[148:151], v[180:183], v[60:63]
	v_mfma_f32_16x16x32_bf16 v[52:55], v[156:159], v[180:183], v[52:55]
	v_mfma_f32_16x16x32_bf16 v[44:47], v[148:151], v[198:201], v[44:47]
	v_mfma_f32_16x16x32_bf16 v[36:39], v[156:159], v[198:201], v[36:39]
	v_mfma_f32_16x16x32_bf16 v[28:31], v[148:151], v[206:209], v[28:31]
	v_mfma_f32_16x16x32_bf16 v[20:23], v[156:159], v[206:209], v[20:23]
	v_mfma_f32_16x16x32_bf16 v[12:15], v[148:151], v[214:217], v[12:15]
	v_mfma_f32_16x16x32_bf16 v[4:7], v[156:159], v[214:217], v[4:7]
	s_setprio 0
	s_setprio 1
	v_mfma_f32_16x16x32_bf16 v[56:59], v[160:163], v[176:179], v[56:59]
	v_mfma_f32_16x16x32_bf16 v[48:51], v[168:171], v[176:179], v[48:51]
	v_mfma_f32_16x16x32_bf16 v[40:43], v[160:163], v[194:197], v[40:43]
	v_mfma_f32_16x16x32_bf16 v[32:35], v[168:171], v[194:197], v[32:35]
	v_mfma_f32_16x16x32_bf16 v[24:27], v[160:163], v[202:205], v[24:27]
	v_mfma_f32_16x16x32_bf16 v[16:19], v[168:171], v[202:205], v[16:19]
	v_mfma_f32_16x16x32_bf16 v[8:11], v[160:163], v[210:213], v[8:11]
	v_mfma_f32_16x16x32_bf16 v[0:3], v[168:171], v[210:213], v[0:3]
	v_mfma_f32_16x16x32_bf16 v[56:59], v[164:167], v[180:183], v[56:59]
	v_mfma_f32_16x16x32_bf16 v[48:51], v[172:175], v[180:183], v[48:51]
	v_mfma_f32_16x16x32_bf16 v[40:43], v[164:167], v[198:201], v[40:43]
	v_mfma_f32_16x16x32_bf16 v[32:35], v[172:175], v[198:201], v[32:35]
	v_mfma_f32_16x16x32_bf16 v[24:27], v[164:167], v[206:209], v[24:27]
	v_mfma_f32_16x16x32_bf16 v[16:19], v[172:175], v[206:209], v[16:19]
	v_mfma_f32_16x16x32_bf16 v[8:11], v[164:167], v[214:217], v[8:11]
	v_mfma_f32_16x16x32_bf16 v[0:3], v[172:175], v[214:217], v[0:3]
	s_setprio 0
	s_barrier
	s_add_i32 s49, s49, 2
	s_add_u32 s46, s46, 0x100
	s_addc_u32 s47, s47, 0
	s_add_u32 s16, s16, 0x100
	s_addc_u32 s17, s17, 0
	s_cmp_gt_u32 s49, 13

.LBB0_486:
	s_or_b64 exec, exec, s[14:15]
	s_waitcnt lgkmcnt(0)
	s_barrier
	ds_read2_b32 v[150:151], v145 offset1:16
	ds_read2_b32 v[140:141], v145 offset0:32 offset1:48
	ds_read2_b32 v[138:139], v145 offset0:128 offset1:144
	ds_read2_b32 v[136:137], v145 offset0:160 offset1:176
	v_pk_mul_f32 v[120:121], v[124:125], v[120:121]
	s_waitcnt lgkmcnt(0)
	v_mul_f32_e32 v152, 0xbfb8aa3b, v150
	v_pk_mul_f32 v[154:155], v[124:125], v[152:153] op_sel_hi:[1,0]
	v_pk_mul_f32 v[124:125], v[126:127], v[152:153] op_sel_hi:[1,0]
	v_mul_f32_e32 v150, v150, v150
	v_exp_f32_e32 v124, v124
	v_exp_f32_e32 v125, v125
	v_pk_mul_f32 v[122:123], v[126:127], v[122:123]
	v_pk_mul_f32 v[112:113], v[116:117], v[112:113]
	v_pk_mul_f32 v[122:123], v[122:123], v[150:151] op_sel_hi:[1,0]
	v_pk_add_f32 v[124:125], v[124:125], 1.0 op_sel_hi:[1,0]
	v_exp_f32_e32 v154, v154
	v_rcp_f32_e32 v124, v124
	v_rcp_f32_e32 v125, v125
	v_exp_f32_e32 v155, v155
	v_pk_mul_f32 v[114:115], v[118:119], v[114:115]
	v_pk_mul_f32 v[120:121], v[120:121], v[150:151] op_sel_hi:[1,0]
	v_pk_mul_f32 v[122:123], v[122:123], v[124:125]
	v_pk_mul_f32 v[124:125], v[116:117], v[152:153] op_sel_hi:[1,0]
	v_pk_mul_f32 v[116:117], v[118:119], v[152:153] op_sel_hi:[1,0]
	v_exp_f32_e32 v124, v124
	v_exp_f32_e32 v125, v125
	v_exp_f32_e32 v116, v116
	v_exp_f32_e32 v117, v117
	v_pk_add_f32 v[154:155], v[154:155], 1.0 op_sel_hi:[1,0]
	v_pk_add_f32 v[124:125], v[124:125], 1.0 op_sel_hi:[1,0]
	v_rcp_f32_e32 v154, v154
	v_pk_add_f32 v[116:117], v[116:117], 1.0 op_sel_hi:[1,0]
	v_rcp_f32_e32 v155, v155
	v_rcp_f32_e32 v124, v124
	v_rcp_f32_e32 v125, v125
	v_rcp_f32_e32 v116, v116
	v_rcp_f32_e32 v117, v117
	v_pk_mul_f32 v[112:113], v[112:113], v[150:151] op_sel_hi:[1,0]
	v_pk_mul_f32 v[114:115], v[114:115], v[150:151] op_sel_hi:[1,0]
	v_pk_mul_f32 v[120:121], v[120:121], v[154:155]
	v_pk_mul_f32 v[112:113], v[112:113], v[124:125]
	v_pk_mul_f32 v[114:115], v[114:115], v[116:117]
	v_mov_b32_e32 v116, 0
	v_mov_b32_e32 v117, 0
	v_cvt_pk_fp8_f32 v116, v120, v121
	v_cvt_pk_fp8_f32 v117, v112, v113
	v_lshl_add_u32 v148, s30, 8, v142
	v_lshl_or_b32 v134, s29, 7, v146
	v_cvt_pk_fp8_f32 v116, v122, v123 op_sel:[0,0,1]
	v_cvt_pk_fp8_f32 v117, v114, v115 op_sel:[0,0,1]
	v_mov_b64_e32 v[112:113], s[72:73]
	v_ashrrev_i32_e32 v135, 31, v134
	v_mad_i64_i32 v[114:115], s[14:15], v148, s18, v[112:113]
	v_lshl_add_u64 v[114:115], v[114:115], 0, v[134:135]
	global_store_dwordx2 v[114:115], v[116:117], off
	v_mul_f32_e32 v114, 0xbfb8aa3b, v151
	v_pk_mul_f32 v[118:119], v[108:109], v[114:115] op_sel_hi:[1,0]
	v_pk_mul_f32 v[104:105], v[108:109], v[104:105]
	v_pk_mul_f32 v[108:109], v[110:111], v[114:115] op_sel_hi:[1,0]
	v_mul_f32_e32 v116, v151, v151
	v_exp_f32_e32 v108, v108
	v_exp_f32_e32 v109, v109
	v_pk_mul_f32 v[106:107], v[110:111], v[106:107]
	v_pk_mul_f32 v[96:97], v[100:101], v[96:97]
	v_pk_mul_f32 v[106:107], v[106:107], v[116:117] op_sel_hi:[1,0]
	v_pk_add_f32 v[108:109], v[108:109], 1.0 op_sel_hi:[1,0]
	v_exp_f32_e32 v118, v118
	v_rcp_f32_e32 v108, v108
	v_rcp_f32_e32 v109, v109
	v_exp_f32_e32 v119, v119
	v_pk_mul_f32 v[98:99], v[102:103], v[98:99]
	v_pk_mul_f32 v[104:105], v[104:105], v[116:117] op_sel_hi:[1,0]
	v_pk_mul_f32 v[106:107], v[106:107], v[108:109]
	v_pk_mul_f32 v[108:109], v[100:101], v[114:115] op_sel_hi:[1,0]
	v_pk_mul_f32 v[100:101], v[102:103], v[114:115] op_sel_hi:[1,0]
	v_exp_f32_e32 v108, v108
	v_exp_f32_e32 v109, v109
	v_exp_f32_e32 v100, v100
	v_exp_f32_e32 v101, v101
	v_pk_add_f32 v[118:119], v[118:119], 1.0 op_sel_hi:[1,0]
	v_pk_add_f32 v[108:109], v[108:109], 1.0 op_sel_hi:[1,0]
	v_rcp_f32_e32 v118, v118
	v_pk_add_f32 v[100:101], v[100:101], 1.0 op_sel_hi:[1,0]
	v_rcp_f32_e32 v119, v119
	v_rcp_f32_e32 v108, v108
	v_rcp_f32_e32 v109, v109
	v_rcp_f32_e32 v100, v100
	v_rcp_f32_e32 v101, v101
	v_pk_mul_f32 v[96:97], v[96:97], v[116:117] op_sel_hi:[1,0]
	v_pk_mul_f32 v[98:99], v[98:99], v[116:117] op_sel_hi:[1,0]
	v_pk_mul_f32 v[104:105], v[104:105], v[118:119]
	v_pk_mul_f32 v[96:97], v[96:97], v[108:109]
	v_pk_mul_f32 v[98:99], v[98:99], v[100:101]
	v_mov_b32_e32 v100, 0
	v_mov_b32_e32 v101, 0
	v_cvt_pk_fp8_f32 v100, v104, v105
	v_cvt_pk_fp8_f32 v101, v96, v97
	v_or_b32_e32 v96, 16, v148
	v_mad_i64_i32 v[96:97], s[14:15], v96, s18, v[112:113]
	v_cvt_pk_fp8_f32 v100, v106, v107 op_sel:[0,0,1]
	v_cvt_pk_fp8_f32 v101, v98, v99 op_sel:[0,0,1]
	v_lshl_add_u64 v[96:97], v[96:97], 0, v[134:135]
	v_pk_mul_f32 v[88:89], v[92:93], v[88:89]
	v_mul_f32_e32 v98, v140, v140
	global_store_dwordx2 v[96:97], v[100:101], off
	v_mul_f32_e32 v96, 0xbfb8aa3b, v140
	v_pk_mul_f32 v[100:101], v[92:93], v[96:97] op_sel_hi:[1,0]
	v_pk_mul_f32 v[92:93], v[94:95], v[96:97] op_sel_hi:[1,0]
	v_pk_mul_f32 v[90:91], v[94:95], v[90:91]
	v_exp_f32_e32 v92, v92
	v_exp_f32_e32 v93, v93
	v_pk_mul_f32 v[90:91], v[90:91], v[98:99] op_sel_hi:[1,0]
	v_pk_mul_f32 v[80:81], v[84:85], v[80:81]
	v_exp_f32_e32 v100, v100
	v_pk_add_f32 v[92:93], v[92:93], 1.0 op_sel_hi:[1,0]
	v_exp_f32_e32 v101, v101
	v_rcp_f32_e32 v92, v92
	v_rcp_f32_e32 v93, v93
	v_pk_mul_f32 v[82:83], v[86:87], v[82:83]
	v_pk_add_f32 v[100:101], v[100:101], 1.0 op_sel_hi:[1,0]
	v_pk_mul_f32 v[88:89], v[88:89], v[98:99] op_sel_hi:[1,0]
	v_pk_mul_f32 v[90:91], v[90:91], v[92:93]
	v_pk_mul_f32 v[92:93], v[84:85], v[96:97] op_sel_hi:[1,0]
	v_pk_mul_f32 v[84:85], v[86:87], v[96:97] op_sel_hi:[1,0]
	v_exp_f32_e32 v92, v92
	v_exp_f32_e32 v93, v93
	v_exp_f32_e32 v84, v84
	v_exp_f32_e32 v85, v85
	v_rcp_f32_e32 v100, v100
	v_pk_add_f32 v[92:93], v[92:93], 1.0 op_sel_hi:[1,0]
	v_rcp_f32_e32 v101, v101
	v_pk_add_f32 v[84:85], v[84:85], 1.0 op_sel_hi:[1,0]
	v_rcp_f32_e32 v92, v92
	v_rcp_f32_e32 v93, v93
	v_rcp_f32_e32 v84, v84
	v_rcp_f32_e32 v85, v85
	v_pk_mul_f32 v[80:81], v[80:81], v[98:99] op_sel_hi:[1,0]
	v_pk_mul_f32 v[82:83], v[82:83], v[98:99] op_sel_hi:[1,0]
	v_pk_mul_f32 v[88:89], v[88:89], v[100:101]
	v_pk_mul_f32 v[80:81], v[80:81], v[92:93]
	v_pk_mul_f32 v[82:83], v[82:83], v[84:85]
	v_mov_b32_e32 v84, 0
	v_mov_b32_e32 v85, 0
	v_cvt_pk_fp8_f32 v84, v88, v89
	v_cvt_pk_fp8_f32 v85, v80, v81
	v_or_b32_e32 v80, 32, v148
	v_mad_i64_i32 v[80:81], s[14:15], v80, s18, v[112:113]
	v_cvt_pk_fp8_f32 v84, v90, v91 op_sel:[0,0,1]
	v_cvt_pk_fp8_f32 v85, v82, v83 op_sel:[0,0,1]
	v_lshl_add_u64 v[80:81], v[80:81], 0, v[134:135]
	v_pk_mul_f32 v[72:73], v[76:77], v[72:73]
	v_mul_f32_e32 v82, v141, v141
	global_store_dwordx2 v[80:81], v[84:85], off
	v_mul_f32_e32 v80, 0xbfb8aa3b, v141
	v_pk_mul_f32 v[84:85], v[76:77], v[80:81] op_sel_hi:[1,0]
	v_pk_mul_f32 v[76:77], v[78:79], v[80:81] op_sel_hi:[1,0]
	v_pk_mul_f32 v[74:75], v[78:79], v[74:75]
	v_exp_f32_e32 v76, v76
	v_exp_f32_e32 v77, v77
	v_pk_mul_f32 v[74:75], v[74:75], v[82:83] op_sel_hi:[1,0]
	v_pk_mul_f32 v[64:65], v[68:69], v[64:65]
	v_exp_f32_e32 v84, v84
	v_pk_add_f32 v[76:77], v[76:77], 1.0 op_sel_hi:[1,0]
	v_exp_f32_e32 v85, v85
	v_rcp_f32_e32 v76, v76
	v_rcp_f32_e32 v77, v77
	v_pk_mul_f32 v[66:67], v[70:71], v[66:67]
	v_pk_add_f32 v[84:85], v[84:85], 1.0 op_sel_hi:[1,0]
	v_pk_mul_f32 v[72:73], v[72:73], v[82:83] op_sel_hi:[1,0]
	v_pk_mul_f32 v[74:75], v[74:75], v[76:77]
	v_pk_mul_f32 v[76:77], v[68:69], v[80:81] op_sel_hi:[1,0]
	v_pk_mul_f32 v[68:69], v[70:71], v[80:81] op_sel_hi:[1,0]
	v_exp_f32_e32 v76, v76
	v_exp_f32_e32 v77, v77
	v_exp_f32_e32 v68, v68
	v_exp_f32_e32 v69, v69
	v_rcp_f32_e32 v84, v84
	v_pk_add_f32 v[76:77], v[76:77], 1.0 op_sel_hi:[1,0]
	v_rcp_f32_e32 v85, v85
	v_pk_add_f32 v[68:69], v[68:69], 1.0 op_sel_hi:[1,0]
	v_rcp_f32_e32 v76, v76
	v_rcp_f32_e32 v77, v77
	v_rcp_f32_e32 v68, v68
	v_rcp_f32_e32 v69, v69
	v_pk_mul_f32 v[64:65], v[64:65], v[82:83] op_sel_hi:[1,0]
	v_pk_mul_f32 v[66:67], v[66:67], v[82:83] op_sel_hi:[1,0]
	v_pk_mul_f32 v[72:73], v[72:73], v[84:85]
	v_pk_mul_f32 v[64:65], v[64:65], v[76:77]
	v_pk_mul_f32 v[66:67], v[66:67], v[68:69]
	v_mov_b32_e32 v68, 0
	v_mov_b32_e32 v69, 0
	v_cvt_pk_fp8_f32 v68, v72, v73
	v_cvt_pk_fp8_f32 v69, v64, v65
	v_or_b32_e32 v64, 48, v148
	v_mad_i64_i32 v[64:65], s[14:15], v64, s18, v[112:113]
	v_cvt_pk_fp8_f32 v68, v74, v75 op_sel:[0,0,1]
	v_cvt_pk_fp8_f32 v69, v66, v67 op_sel:[0,0,1]
	v_lshl_add_u64 v[64:65], v[64:65], 0, v[134:135]
	v_pk_mul_f32 v[56:57], v[60:61], v[56:57]
	v_mul_f32_e32 v66, v138, v138
	global_store_dwordx2 v[64:65], v[68:69], off
	v_add_u32_e32 v65, 0x80, v148
	v_mul_f32_e32 v64, 0xbfb8aa3b, v138
	v_pk_mul_f32 v[68:69], v[60:61], v[64:65] op_sel_hi:[1,0]
	v_pk_mul_f32 v[60:61], v[62:63], v[64:65] op_sel_hi:[1,0]
	v_pk_mul_f32 v[58:59], v[62:63], v[58:59]
	v_exp_f32_e32 v60, v60
	v_exp_f32_e32 v61, v61
	v_pk_mul_f32 v[58:59], v[58:59], v[66:67] op_sel_hi:[1,0]
	v_pk_mul_f32 v[48:49], v[52:53], v[48:49]
	v_exp_f32_e32 v68, v68
	v_pk_add_f32 v[60:61], v[60:61], 1.0 op_sel_hi:[1,0]
	v_exp_f32_e32 v69, v69
	v_rcp_f32_e32 v60, v60
	v_rcp_f32_e32 v61, v61
	v_pk_mul_f32 v[50:51], v[54:55], v[50:51]
	v_pk_add_f32 v[68:69], v[68:69], 1.0 op_sel_hi:[1,0]
	v_pk_mul_f32 v[56:57], v[56:57], v[66:67] op_sel_hi:[1,0]
	v_pk_mul_f32 v[58:59], v[58:59], v[60:61]
	v_pk_mul_f32 v[60:61], v[52:53], v[64:65] op_sel_hi:[1,0]
	v_pk_mul_f32 v[52:53], v[54:55], v[64:65] op_sel_hi:[1,0]
	v_exp_f32_e32 v60, v60
	v_exp_f32_e32 v61, v61
	v_exp_f32_e32 v52, v52
	v_exp_f32_e32 v53, v53
	v_rcp_f32_e32 v68, v68
	v_pk_add_f32 v[60:61], v[60:61], 1.0 op_sel_hi:[1,0]
	v_rcp_f32_e32 v69, v69
	v_pk_add_f32 v[52:53], v[52:53], 1.0 op_sel_hi:[1,0]
	v_rcp_f32_e32 v60, v60
	v_rcp_f32_e32 v61, v61
	v_rcp_f32_e32 v52, v52
	v_rcp_f32_e32 v53, v53
	v_pk_mul_f32 v[48:49], v[48:49], v[66:67] op_sel_hi:[1,0]
	v_pk_mul_f32 v[50:51], v[50:51], v[66:67] op_sel_hi:[1,0]
	v_pk_mul_f32 v[56:57], v[56:57], v[68:69]
	v_pk_mul_f32 v[48:49], v[48:49], v[60:61]
	v_pk_mul_f32 v[50:51], v[50:51], v[52:53]
	v_mov_b32_e32 v52, 0
	v_mov_b32_e32 v53, 0
	v_cvt_pk_fp8_f32 v52, v56, v57
	v_cvt_pk_fp8_f32 v53, v48, v49
	v_mad_i64_i32 v[48:49], s[14:15], v65, s18, v[112:113]
	v_cvt_pk_fp8_f32 v52, v58, v59 op_sel:[0,0,1]
	v_cvt_pk_fp8_f32 v53, v50, v51 op_sel:[0,0,1]
	v_lshl_add_u64 v[48:49], v[48:49], 0, v[134:135]
	v_pk_mul_f32 v[40:41], v[44:45], v[40:41]
	v_mul_f32_e32 v50, v139, v139
	global_store_dwordx2 v[48:49], v[52:53], off
	v_mul_f32_e32 v48, 0xbfb8aa3b, v139
	v_pk_mul_f32 v[52:53], v[44:45], v[48:49] op_sel_hi:[1,0]
	v_pk_mul_f32 v[44:45], v[46:47], v[48:49] op_sel_hi:[1,0]
	v_pk_mul_f32 v[42:43], v[46:47], v[42:43]
	v_exp_f32_e32 v44, v44
	v_exp_f32_e32 v45, v45
	v_pk_mul_f32 v[42:43], v[42:43], v[50:51] op_sel_hi:[1,0]
	v_pk_mul_f32 v[32:33], v[36:37], v[32:33]
	v_exp_f32_e32 v52, v52
	v_pk_add_f32 v[44:45], v[44:45], 1.0 op_sel_hi:[1,0]
	v_exp_f32_e32 v53, v53
	v_rcp_f32_e32 v44, v44
	v_rcp_f32_e32 v45, v45
	v_pk_mul_f32 v[34:35], v[38:39], v[34:35]
	v_pk_add_f32 v[52:53], v[52:53], 1.0 op_sel_hi:[1,0]
	v_pk_mul_f32 v[40:41], v[40:41], v[50:51] op_sel_hi:[1,0]
	v_pk_mul_f32 v[42:43], v[42:43], v[44:45]
	v_pk_mul_f32 v[44:45], v[36:37], v[48:49] op_sel_hi:[1,0]
	v_pk_mul_f32 v[36:37], v[38:39], v[48:49] op_sel_hi:[1,0]
	v_exp_f32_e32 v44, v44
	v_exp_f32_e32 v45, v45
	v_exp_f32_e32 v36, v36
	v_exp_f32_e32 v37, v37
	v_rcp_f32_e32 v52, v52
	v_pk_add_f32 v[44:45], v[44:45], 1.0 op_sel_hi:[1,0]
	v_rcp_f32_e32 v53, v53
	v_pk_add_f32 v[36:37], v[36:37], 1.0 op_sel_hi:[1,0]
	v_rcp_f32_e32 v44, v44
	v_rcp_f32_e32 v45, v45
	v_rcp_f32_e32 v36, v36
	v_rcp_f32_e32 v37, v37
	v_pk_mul_f32 v[32:33], v[32:33], v[50:51] op_sel_hi:[1,0]
	v_pk_mul_f32 v[34:35], v[34:35], v[50:51] op_sel_hi:[1,0]
	v_pk_mul_f32 v[40:41], v[40:41], v[52:53]
	v_pk_mul_f32 v[32:33], v[32:33], v[44:45]
	v_pk_mul_f32 v[34:35], v[34:35], v[36:37]
	v_mov_b32_e32 v36, 0
	v_mov_b32_e32 v37, 0
	v_cvt_pk_fp8_f32 v36, v40, v41
	v_cvt_pk_fp8_f32 v37, v32, v33
	v_add_u32_e32 v32, 0x90, v148
	v_mad_i64_i32 v[32:33], s[14:15], v32, s18, v[112:113]
	v_cvt_pk_fp8_f32 v36, v42, v43 op_sel:[0,0,1]
	v_cvt_pk_fp8_f32 v37, v34, v35 op_sel:[0,0,1]
	v_lshl_add_u64 v[32:33], v[32:33], 0, v[134:135]
	v_pk_mul_f32 v[24:25], v[28:29], v[24:25]
	v_mul_f32_e32 v34, v136, v136
	global_store_dwordx2 v[32:33], v[36:37], off
	v_mul_f32_e32 v32, 0xbfb8aa3b, v136
	v_pk_mul_f32 v[36:37], v[28:29], v[32:33] op_sel_hi:[1,0]
	v_pk_mul_f32 v[28:29], v[30:31], v[32:33] op_sel_hi:[1,0]
	v_pk_mul_f32 v[26:27], v[30:31], v[26:27]
	v_exp_f32_e32 v28, v28
	v_exp_f32_e32 v29, v29
	v_pk_mul_f32 v[26:27], v[26:27], v[34:35] op_sel_hi:[1,0]
	v_pk_mul_f32 v[16:17], v[20:21], v[16:17]
	v_exp_f32_e32 v36, v36
	v_pk_add_f32 v[28:29], v[28:29], 1.0 op_sel_hi:[1,0]
	v_exp_f32_e32 v37, v37
	v_rcp_f32_e32 v28, v28
	v_rcp_f32_e32 v29, v29
	v_pk_mul_f32 v[18:19], v[22:23], v[18:19]
	v_pk_add_f32 v[36:37], v[36:37], 1.0 op_sel_hi:[1,0]
	v_pk_mul_f32 v[24:25], v[24:25], v[34:35] op_sel_hi:[1,0]
	v_pk_mul_f32 v[26:27], v[26:27], v[28:29]
	v_pk_mul_f32 v[28:29], v[20:21], v[32:33] op_sel_hi:[1,0]
	v_pk_mul_f32 v[20:21], v[22:23], v[32:33] op_sel_hi:[1,0]
	v_exp_f32_e32 v28, v28
	v_exp_f32_e32 v29, v29
	v_exp_f32_e32 v20, v20
	v_exp_f32_e32 v21, v21
	v_rcp_f32_e32 v36, v36
	v_pk_add_f32 v[28:29], v[28:29], 1.0 op_sel_hi:[1,0]
	v_rcp_f32_e32 v37, v37
	v_pk_add_f32 v[20:21], v[20:21], 1.0 op_sel_hi:[1,0]
	v_rcp_f32_e32 v28, v28
	v_rcp_f32_e32 v29, v29
	v_rcp_f32_e32 v20, v20
	v_rcp_f32_e32 v21, v21
	v_pk_mul_f32 v[16:17], v[16:17], v[34:35] op_sel_hi:[1,0]
	v_pk_mul_f32 v[18:19], v[18:19], v[34:35] op_sel_hi:[1,0]
	v_pk_mul_f32 v[24:25], v[24:25], v[36:37]
	v_pk_mul_f32 v[16:17], v[16:17], v[28:29]
	v_pk_mul_f32 v[18:19], v[18:19], v[20:21]
	v_mov_b32_e32 v20, 0
	v_mov_b32_e32 v21, 0
	v_cvt_pk_fp8_f32 v20, v24, v25
	v_cvt_pk_fp8_f32 v21, v16, v17
	v_add_u32_e32 v16, 0xa0, v148
	v_mad_i64_i32 v[16:17], s[14:15], v16, s18, v[112:113]
	v_cvt_pk_fp8_f32 v20, v26, v27 op_sel:[0,0,1]
	v_cvt_pk_fp8_f32 v21, v18, v19 op_sel:[0,0,1]
	v_lshl_add_u64 v[16:17], v[16:17], 0, v[134:135]
	v_pk_mul_f32 v[8:9], v[12:13], v[8:9]
	v_mul_f32_e32 v18, v137, v137
	global_store_dwordx2 v[16:17], v[20:21], off
	v_mul_f32_e32 v16, 0xbfb8aa3b, v137
	v_pk_mul_f32 v[20:21], v[12:13], v[16:17] op_sel_hi:[1,0]
	v_pk_mul_f32 v[12:13], v[14:15], v[16:17] op_sel_hi:[1,0]
	v_pk_mul_f32 v[10:11], v[14:15], v[10:11]
	v_exp_f32_e32 v12, v12
	v_exp_f32_e32 v13, v13
	v_pk_mul_f32 v[10:11], v[10:11], v[18:19] op_sel_hi:[1,0]
	v_pk_mul_f32 v[0:1], v[4:5], v[0:1]
	v_exp_f32_e32 v20, v20
	v_pk_add_f32 v[12:13], v[12:13], 1.0 op_sel_hi:[1,0]
	v_exp_f32_e32 v21, v21
	v_rcp_f32_e32 v12, v12
	v_rcp_f32_e32 v13, v13
	v_pk_mul_f32 v[2:3], v[6:7], v[2:3]
	v_pk_add_f32 v[20:21], v[20:21], 1.0 op_sel_hi:[1,0]
	v_pk_mul_f32 v[8:9], v[8:9], v[18:19] op_sel_hi:[1,0]
	v_pk_mul_f32 v[10:11], v[10:11], v[12:13]
	v_pk_mul_f32 v[12:13], v[4:5], v[16:17] op_sel_hi:[1,0]
	v_pk_mul_f32 v[4:5], v[6:7], v[16:17] op_sel_hi:[1,0]
	v_exp_f32_e32 v12, v12
	v_exp_f32_e32 v13, v13
	v_exp_f32_e32 v4, v4
	v_exp_f32_e32 v5, v5
	v_rcp_f32_e32 v20, v20
	v_pk_add_f32 v[12:13], v[12:13], 1.0 op_sel_hi:[1,0]
	v_rcp_f32_e32 v21, v21
	v_pk_add_f32 v[4:5], v[4:5], 1.0 op_sel_hi:[1,0]
	v_rcp_f32_e32 v12, v12
	v_rcp_f32_e32 v13, v13
	v_rcp_f32_e32 v4, v4
	v_rcp_f32_e32 v5, v5
	v_pk_mul_f32 v[0:1], v[0:1], v[18:19] op_sel_hi:[1,0]
	v_pk_mul_f32 v[2:3], v[2:3], v[18:19] op_sel_hi:[1,0]
	v_pk_mul_f32 v[8:9], v[8:9], v[20:21]
	v_pk_mul_f32 v[0:1], v[0:1], v[12:13]
	v_pk_mul_f32 v[2:3], v[2:3], v[4:5]
	v_mov_b32_e32 v4, 0
	v_mov_b32_e32 v5, 0
	v_cvt_pk_fp8_f32 v4, v8, v9
	v_cvt_pk_fp8_f32 v5, v0, v1
	v_add_u32_e32 v0, 0xb0, v148
	v_mad_i64_i32 v[0:1], s[14:15], v0, s18, v[112:113]
	v_cvt_pk_fp8_f32 v4, v10, v11 op_sel:[0,0,1]
	v_cvt_pk_fp8_f32 v5, v2, v3 op_sel:[0,0,1]
	v_lshl_add_u64 v[0:1], v[0:1], 0, v[134:135]
	s_mov_b64 s[14:15], -1
	s_andn2_b64 vcc, exec, s[38:39]
	global_store_dwordx2 v[0:1], v[4:5], off
	s_cbranch_vccnz .LBB0_477
	s_lshl_b32 s14, s40, 8
	s_ashr_i32 s15, s14, 31
	v_lshl_add_u64 v[0:1], s[14:15], 2, v[132:133]
	global_load_dword v134, v[0:1], off
	s_andn2_b64 vcc, exec, s[8:9]
	s_cbranch_vccnz .LBB0_476
	s_mov_b32 s98, 1
	s_branch .LBB0_476

.LBB0_502:
	s_ashr_i32 s13, s12, 31
	s_lshl_b64 s[42:43], s[12:13], 18
	s_add_u32 s42, s54, s42
	s_addc_u32 s43, s55, s43
	s_and_b64 s[44:45], s[40:41], exec
	s_cselect_b32 s13, s43, s17
	s_cselect_b32 s31, s42, s16
	s_ashr_i32 s11, s10, 31
	s_lshl_b64 s[44:45], s[10:11], 18
	s_add_u32 s44, s22, s44
	s_addc_u32 s45, s23, s45
	s_and_b64 s[46:47], s[40:41], exec
	s_cselect_b32 s11, s45, s15
	s_cselect_b32 s48, s44, s14
	s_add_u32 s46, s16, 0x20080
	s_addc_u32 s47, s17, 0
	s_add_u32 s49, s14, 0x100
	s_addc_u32 s50, s15, 0
	s_mov_b32 s51, -2
	s_cmp_eq_u32 s98, 1
	s_cbranch_scc0 .Lnostb8
	s_mov_b32 s98, 0
	s_barrier
.Lnostb8:
	s_add_u32 s14, s46, 0xfffe0080
	s_addc_u32 s15, s47, -1
	s_add_i32 s60, 0, 0x10000
	s_cmp_eq_u32 s51, 4
	s_cselect_b32 s15, s13, s15
	s_cselect_b32 s14, s31, s14
	s_cselect_b32 s17, s11, s50
	s_cselect_b32 s16, s48, s49
	s_add_i32 s61, 0, 0x14000
	v_add_u32_e32 v0, s60, v172
	v_add_u32_e32 v4, s61, v172
	ds_read_b128 v[24:27], v0
	ds_read_b128 v[28:31], v0 offset:1024
	ds_read_b128 v[16:19], v0 offset:2048
	ds_read_b128 v[20:23], v0 offset:3072
	ds_read_b128 v[8:11], v4
	ds_read_b128 v[12:15], v4 offset:1024
	ds_read_b128 v[0:3], v4 offset:2048
	ds_read_b128 v[4:7], v4 offset:3072
	v_lshl_add_u64 v[166:167], s[46:47], 0, v[164:165]
	s_add_i32 m0, s19, 0xc000
	ds_read_b128 v[194:197], v176
	ds_read_b128 v[198:201], v176 offset:1024
	ds_read_b128 v[202:205], v176 offset:2048
	ds_read_b128 v[206:209], v176 offset:3072
	ds_read_b128 v[210:213], v176 offset:4096
	ds_read_b128 v[214:217], v176 offset:5120
	ds_read_b128 v[218:221], v176 offset:6144
	ds_read_b128 v[222:225], v176 offset:7168
	global_load_lds_dwordx4 v[166:167], off
	v_lshl_add_u64 v[166:167], v[166:167], 0, s[94:95]
	s_add_i32 m0, s19, 0xe000
	s_nop 0
	global_load_lds_dwordx4 v[166:167], off
	s_waitcnt vmcnt(8)
	s_waitcnt lgkmcnt(0)
	s_barrier
	s_setprio 1
	s_waitcnt lgkmcnt(0)
	v_mfma_scale_f32_16x16x128_f8f6f4 v[156:159], v[24:31], v[194:201], 0, v240, v240 op_sel_hi:[0,0,0]
	v_mfma_scale_f32_16x16x128_f8f6f4 v[148:151], v[16:23], v[194:201], 0, v240, v240 op_sel_hi:[0,0,0]
	v_mfma_scale_f32_16x16x128_f8f6f4 v[140:143], v[24:31], v[202:209], 0, v240, v240 op_sel_hi:[0,0,0]
	v_mfma_scale_f32_16x16x128_f8f6f4 v[132:135], v[16:23], v[202:209], 0, v240, v240 op_sel_hi:[0,0,0]
	v_mfma_scale_f32_16x16x128_f8f6f4 v[124:127], v[24:31], v[210:217], 0, v240, v240 op_sel_hi:[0,0,0]
	v_mfma_scale_f32_16x16x128_f8f6f4 v[116:119], v[16:23], v[210:217], 0, v240, v240 op_sel_hi:[0,0,0]
	v_mfma_scale_f32_16x16x128_f8f6f4 v[108:111], v[24:31], v[218:225], 0, v240, v240 op_sel_hi:[0,0,0]
	v_mfma_scale_f32_16x16x128_f8f6f4 v[100:103], v[16:23], v[218:225], 0, v240, v240 op_sel_hi:[0,0,0]
	s_setprio 0
	s_setprio 1
	v_mfma_scale_f32_16x16x128_f8f6f4 v[152:155], v[8:15], v[194:201], 0, v240, v240 op_sel_hi:[0,0,0]
	v_mfma_scale_f32_16x16x128_f8f6f4 v[144:147], v[0:7], v[194:201], 0, v240, v240 op_sel_hi:[0,0,0]
	v_mfma_scale_f32_16x16x128_f8f6f4 v[136:139], v[8:15], v[202:209], 0, v240, v240 op_sel_hi:[0,0,0]
	v_mfma_scale_f32_16x16x128_f8f6f4 v[128:131], v[0:7], v[202:209], 0, v240, v240 op_sel_hi:[0,0,0]
	v_mfma_scale_f32_16x16x128_f8f6f4 v[120:123], v[8:15], v[210:217], 0, v240, v240 op_sel_hi:[0,0,0]
	v_mfma_scale_f32_16x16x128_f8f6f4 v[112:115], v[0:7], v[210:217], 0, v240, v240 op_sel_hi:[0,0,0]
	v_mfma_scale_f32_16x16x128_f8f6f4 v[104:107], v[8:15], v[218:225], 0, v240, v240 op_sel_hi:[0,0,0]
	v_mfma_scale_f32_16x16x128_f8f6f4 v[96:99], v[0:7], v[218:225], 0, v240, v240 op_sel_hi:[0,0,0]
	s_setprio 0
	s_barrier
	v_lshl_add_u64 v[166:167], s[16:17], 0, v[184:185]
	s_add_i32 s16, s60, s6
	s_mov_b32 m0, s16
	ds_read_b128 v[194:197], v176 offset:16384
	ds_read_b128 v[198:201], v176 offset:17408
	ds_read_b128 v[202:205], v176 offset:18432
	ds_read_b128 v[206:209], v176 offset:19456
	ds_read_b128 v[210:213], v176 offset:20480
	ds_read_b128 v[214:217], v176 offset:21504
	ds_read_b128 v[218:221], v176 offset:22528
	ds_read_b128 v[222:225], v176 offset:23552
	global_load_lds_dwordx4 v[166:167], off
	v_lshl_add_u64 v[168:169], v[166:167], 0, s[94:95]
	s_add_i32 m0, s16, 0x2000
	s_add_i32 s16, s61, s6
	global_load_lds_dwordx4 v[168:169], off
	v_lshl_add_u64 v[168:169], v[166:167], 0, s[34:35]
	s_mov_b32 m0, s16
	s_nop 0
	global_load_lds_dwordx4 v[168:169], off
	v_lshl_add_u64 v[168:169], v[166:167], 0, s[90:91]
	s_add_i32 m0, s16, 0x2000
	s_nop 0
	global_load_lds_dwordx4 v[168:169], off
	v_lshl_add_u64 v[168:169], s[14:15], 0, v[160:161]
	s_mov_b32 m0, s19
	v_lshl_add_u64 v[178:179], v[168:169], 0, s[94:95]
	global_load_lds_dwordx4 v[168:169], off
	s_mov_b32 m0, s20
	s_nop 0
	global_load_lds_dwordx4 v[178:179], off
	s_waitcnt vmcnt(8)
	s_waitcnt lgkmcnt(0)
	s_barrier
	s_setprio 1
	s_waitcnt lgkmcnt(0)
	v_mfma_scale_f32_16x16x128_f8f6f4 v[92:95], v[24:31], v[194:201], 0, v240, v240 op_sel_hi:[0,0,0]
	v_mfma_scale_f32_16x16x128_f8f6f4 v[84:87], v[16:23], v[194:201], 0, v240, v240 op_sel_hi:[0,0,0]
	v_mfma_scale_f32_16x16x128_f8f6f4 v[76:79], v[24:31], v[202:209], 0, v240, v240 op_sel_hi:[0,0,0]
	v_mfma_scale_f32_16x16x128_f8f6f4 v[68:71], v[16:23], v[202:209], 0, v240, v240 op_sel_hi:[0,0,0]
	v_mfma_scale_f32_16x16x128_f8f6f4 v[60:63], v[24:31], v[210:217], 0, v240, v240 op_sel_hi:[0,0,0]
	v_mfma_scale_f32_16x16x128_f8f6f4 v[52:55], v[16:23], v[210:217], 0, v240, v240 op_sel_hi:[0,0,0]
	v_mfma_scale_f32_16x16x128_f8f6f4 v[44:47], v[24:31], v[218:225], 0, v240, v240 op_sel_hi:[0,0,0]
	v_mfma_scale_f32_16x16x128_f8f6f4 v[36:39], v[16:23], v[218:225], 0, v240, v240 op_sel_hi:[0,0,0]
	s_setprio 0
	s_setprio 1
	v_mfma_scale_f32_16x16x128_f8f6f4 v[88:91], v[8:15], v[194:201], 0, v240, v240 op_sel_hi:[0,0,0]
	v_mfma_scale_f32_16x16x128_f8f6f4 v[80:83], v[0:7], v[194:201], 0, v240, v240 op_sel_hi:[0,0,0]
	v_mfma_scale_f32_16x16x128_f8f6f4 v[72:75], v[8:15], v[202:209], 0, v240, v240 op_sel_hi:[0,0,0]
	v_mfma_scale_f32_16x16x128_f8f6f4 v[64:67], v[0:7], v[202:209], 0, v240, v240 op_sel_hi:[0,0,0]
	v_mfma_scale_f32_16x16x128_f8f6f4 v[56:59], v[8:15], v[210:217], 0, v240, v240 op_sel_hi:[0,0,0]
	v_mfma_scale_f32_16x16x128_f8f6f4 v[48:51], v[0:7], v[210:217], 0, v240, v240 op_sel_hi:[0,0,0]
	v_mfma_scale_f32_16x16x128_f8f6f4 v[40:43], v[8:15], v[218:225], 0, v240, v240 op_sel_hi:[0,0,0]
	v_mfma_scale_f32_16x16x128_f8f6f4 v[32:35], v[0:7], v[218:225], 0, v240, v240 op_sel_hi:[0,0,0]
	s_setprio 0
	s_barrier
	s_add_i32 s14, 0, 0x18000
	s_add_i32 s15, 0, 0x1c000
	v_add_u32_e32 v12, s14, v172
	v_add_u32_e32 v28, s15, v172
	ds_read_b128 v[0:3], v12
	ds_read_b128 v[4:7], v12 offset:1024
	ds_read_b128 v[8:11], v12 offset:2048
	ds_read_b128 v[12:15], v12 offset:3072
	ds_read_b128 v[16:19], v28
	ds_read_b128 v[20:23], v28 offset:1024
	ds_read_b128 v[24:27], v28 offset:2048
	ds_read_b128 v[28:31], v28 offset:3072
	s_mov_b32 m0, s24
	v_lshl_add_u64 v[178:179], v[168:169], 0, s[34:35]
	ds_read_b128 v[194:197], v176 offset:32768
	ds_read_b128 v[198:201], v176 offset:33792
	ds_read_b128 v[202:205], v176 offset:34816
	ds_read_b128 v[206:209], v176 offset:35840
	ds_read_b128 v[210:213], v176 offset:36864
	ds_read_b128 v[214:217], v176 offset:37888
	ds_read_b128 v[218:221], v176 offset:38912
	ds_read_b128 v[222:225], v176 offset:39936
	global_load_lds_dwordx4 v[178:179], off
	v_lshl_add_u64 v[178:179], v[168:169], 0, s[90:91]
	s_mov_b32 m0, s25
	s_nop 0
	global_load_lds_dwordx4 v[178:179], off
	s_waitcnt vmcnt(8)
	s_waitcnt lgkmcnt(0)
	s_barrier
	s_setprio 1
	s_waitcnt lgkmcnt(0)
	v_mfma_scale_f32_16x16x128_f8f6f4 v[156:159], v[0:7], v[194:201], v[156:159], v240, v240 op_sel_hi:[0,0,0]
	v_mfma_scale_f32_16x16x128_f8f6f4 v[148:151], v[8:15], v[194:201], v[148:151], v240, v240 op_sel_hi:[0,0,0]
	v_mfma_scale_f32_16x16x128_f8f6f4 v[140:143], v[0:7], v[202:209], v[140:143], v240, v240 op_sel_hi:[0,0,0]
	v_mfma_scale_f32_16x16x128_f8f6f4 v[132:135], v[8:15], v[202:209], v[132:135], v240, v240 op_sel_hi:[0,0,0]
	v_mfma_scale_f32_16x16x128_f8f6f4 v[124:127], v[0:7], v[210:217], v[124:127], v240, v240 op_sel_hi:[0,0,0]
	v_mfma_scale_f32_16x16x128_f8f6f4 v[116:119], v[8:15], v[210:217], v[116:119], v240, v240 op_sel_hi:[0,0,0]
	v_mfma_scale_f32_16x16x128_f8f6f4 v[108:111], v[0:7], v[218:225], v[108:111], v240, v240 op_sel_hi:[0,0,0]
	v_mfma_scale_f32_16x16x128_f8f6f4 v[100:103], v[8:15], v[218:225], v[100:103], v240, v240 op_sel_hi:[0,0,0]
	s_setprio 0
	s_setprio 1
	v_mfma_scale_f32_16x16x128_f8f6f4 v[152:155], v[16:23], v[194:201], v[152:155], v240, v240 op_sel_hi:[0,0,0]
	v_mfma_scale_f32_16x16x128_f8f6f4 v[144:147], v[24:31], v[194:201], v[144:147], v240, v240 op_sel_hi:[0,0,0]
	v_mfma_scale_f32_16x16x128_f8f6f4 v[136:139], v[16:23], v[202:209], v[136:139], v240, v240 op_sel_hi:[0,0,0]
	v_mfma_scale_f32_16x16x128_f8f6f4 v[128:131], v[24:31], v[202:209], v[128:131], v240, v240 op_sel_hi:[0,0,0]
	v_mfma_scale_f32_16x16x128_f8f6f4 v[120:123], v[16:23], v[210:217], v[120:123], v240, v240 op_sel_hi:[0,0,0]
	v_mfma_scale_f32_16x16x128_f8f6f4 v[112:115], v[24:31], v[210:217], v[112:115], v240, v240 op_sel_hi:[0,0,0]
	v_mfma_scale_f32_16x16x128_f8f6f4 v[104:107], v[16:23], v[218:225], v[104:107], v240, v240 op_sel_hi:[0,0,0]
	v_mfma_scale_f32_16x16x128_f8f6f4 v[96:99], v[24:31], v[218:225], v[96:99], v240, v240 op_sel_hi:[0,0,0]
	s_setprio 0
	s_barrier
	s_add_i32 s14, s14, s6
	v_lshl_add_u64 v[178:179], v[166:167], 0, s[56:57]
	s_mov_b32 m0, s14
	ds_read_b128 v[194:197], v176 offset:49152
	ds_read_b128 v[198:201], v176 offset:50176
	ds_read_b128 v[202:205], v176 offset:51200
	ds_read_b128 v[206:209], v176 offset:52224
	ds_read_b128 v[210:213], v176 offset:53248
	ds_read_b128 v[214:217], v176 offset:54272
	ds_read_b128 v[218:221], v176 offset:55296
	ds_read_b128 v[222:225], v176 offset:56320
	global_load_lds_dwordx4 v[178:179], off
	v_lshl_add_u64 v[178:179], v[166:167], 0, s[58:59]
	s_add_i32 m0, s14, 0x2000
	s_add_i32 s14, s15, s6
	global_load_lds_dwordx4 v[178:179], off
	v_lshl_add_u64 v[178:179], v[166:167], 0, s[96:97]
	s_mov_b32 m0, s14
	v_lshl_add_u64 v[166:167], v[166:167], 0, s[4:5]
	global_load_lds_dwordx4 v[178:179], off
	s_add_i32 m0, s14, 0x2000
	s_nop 0
	global_load_lds_dwordx4 v[166:167], off
	v_lshl_add_u64 v[166:167], v[168:169], 0, s[56:57]
	s_mov_b32 m0, s26
	s_nop 0
	global_load_lds_dwordx4 v[166:167], off
	v_lshl_add_u64 v[166:167], v[168:169], 0, s[58:59]
	s_mov_b32 m0, s27
	s_nop 0
	global_load_lds_dwordx4 v[166:167], off
	s_waitcnt vmcnt(8)
	s_waitcnt lgkmcnt(0)
	s_barrier
	s_setprio 1
	s_waitcnt lgkmcnt(0)
	v_mfma_scale_f32_16x16x128_f8f6f4 v[92:95], v[0:7], v[194:201], v[92:95], v240, v240 op_sel_hi:[0,0,0]
	v_mfma_scale_f32_16x16x128_f8f6f4 v[84:87], v[8:15], v[194:201], v[84:87], v240, v240 op_sel_hi:[0,0,0]
	v_mfma_scale_f32_16x16x128_f8f6f4 v[76:79], v[0:7], v[202:209], v[76:79], v240, v240 op_sel_hi:[0,0,0]
	v_mfma_scale_f32_16x16x128_f8f6f4 v[68:71], v[8:15], v[202:209], v[68:71], v240, v240 op_sel_hi:[0,0,0]
	v_mfma_scale_f32_16x16x128_f8f6f4 v[60:63], v[0:7], v[210:217], v[60:63], v240, v240 op_sel_hi:[0,0,0]
	v_mfma_scale_f32_16x16x128_f8f6f4 v[52:55], v[8:15], v[210:217], v[52:55], v240, v240 op_sel_hi:[0,0,0]
	v_mfma_scale_f32_16x16x128_f8f6f4 v[44:47], v[0:7], v[218:225], v[44:47], v240, v240 op_sel_hi:[0,0,0]
	v_mfma_scale_f32_16x16x128_f8f6f4 v[36:39], v[8:15], v[218:225], v[36:39], v240, v240 op_sel_hi:[0,0,0]
	s_setprio 0
	s_setprio 1
	v_mfma_scale_f32_16x16x128_f8f6f4 v[88:91], v[16:23], v[194:201], v[88:91], v240, v240 op_sel_hi:[0,0,0]
	v_mfma_scale_f32_16x16x128_f8f6f4 v[80:83], v[24:31], v[194:201], v[80:83], v240, v240 op_sel_hi:[0,0,0]
	v_mfma_scale_f32_16x16x128_f8f6f4 v[72:75], v[16:23], v[202:209], v[72:75], v240, v240 op_sel_hi:[0,0,0]
	v_mfma_scale_f32_16x16x128_f8f6f4 v[64:67], v[24:31], v[202:209], v[64:67], v240, v240 op_sel_hi:[0,0,0]
	v_mfma_scale_f32_16x16x128_f8f6f4 v[56:59], v[16:23], v[210:217], v[56:59], v240, v240 op_sel_hi:[0,0,0]
	v_mfma_scale_f32_16x16x128_f8f6f4 v[48:51], v[24:31], v[210:217], v[48:51], v240, v240 op_sel_hi:[0,0,0]
	v_mfma_scale_f32_16x16x128_f8f6f4 v[40:43], v[16:23], v[218:225], v[40:43], v240, v240 op_sel_hi:[0,0,0]
	v_mfma_scale_f32_16x16x128_f8f6f4 v[32:35], v[24:31], v[218:225], v[32:35], v240, v240 op_sel_hi:[0,0,0]
	s_setprio 0
	s_barrier
	s_add_i32 s51, s51, 2
	s_add_u32 s46, s46, 0x100
	s_addc_u32 s47, s47, 0
	s_add_u32 s49, s49, 0x100
	s_addc_u32 s50, s50, 0
	s_cmp_gt_u32 s51, 5

.LBB0_511:
	s_andn2_b64 vcc, exec, s[0:1]
	s_cbranch_vccnz .LBB0_498
	s_mov_b32 s98, 1
	s_branch .LBB0_498

.LBB0_515:
	s_mov_b32 s99, 0
	s_mov_b32 s98, 0
	s_waitcnt vmcnt(0)
	s_waitcnt vmcnt(0) lgkmcnt(0)
	s_barrier
	s_and_saveexec_b64 s[0:1], s[62:63]
	s_cbranch_execz .LBB0_202
	v_readlane_b32 s6, v254, 49
	s_cmp_eq_u32 s100, 1
	s_cbranch_scc0 .Lgbar
	s_add_i32 s9, s6, 1
	s_lshl_b32 s9, s9, 5
	v_readlane_b32 s8, v252, 0
	v_readlane_b32 s10, v252, 45
	v_readlane_b32 s11, v252, 46
	s_and_b32 s8, s8, 7
	s_add_u32 s10, s10, 0xe3600
	s_addc_u32 s11, s11, 0
	s_lshl_b32 s13, 1, s8
	s_lshl_b32 s14, s8, 6
	v_mov_b32_e32 v1, 1
	v_mov_b32_e32 v2, s14
	s_cmp_eq_u32 s6, 2
	s_cbranch_scc1 .Llb_h
	s_cmp_eq_u32 s6, 9
	s_cbranch_scc1 .Llb_h
	s_mov_b32 s16, 0x0e060301
	s_mov_b32 s17, 0xb058281c
	s_cmp_eq_u32 s6, 1
	s_cbranch_scc1 .Llb_tab
	s_mov_b32 s16, 0x0a060301
	s_mov_b32 s17, 0x88482414
	s_cmp_eq_u32 s6, 6
	s_cbranch_scc1 .Llb_tab
	s_mov_b32 s16, 0x0c060301
	s_mov_b32 s17, 0xa070381c
	s_cmp_eq_u32 s6, 8
	s_cbranch_scc1 .Llb_tab
	s_mov_b32 s16, 0xf83c1e07
	s_mov_b32 s17, 0x8040a0d0
	s_cmp_eq_u32 s6, 4
	s_cbranch_scc1 .Llb_tab
	s_mov_b32 s16, 0x783c0e07
	s_mov_b32 s17, 0x8040e0f0
	s_cmp_eq_u32 s6, 11
	s_cbranch_scc1 .Llb_tab
	s_branch .Llb_have
